# v54 + GEMM phases: one static s_setprio 1 for waves 4-7 per phase, per-segment priority flips removed
# speedup vs baseline: 1.0046x; 1.0046x over previous
; #define PG8_STAGE(bufoff, gbase, voff) do { _Pragma("unroll") for (int _i = 0; _i < 2; ++_i) \
;         __builtin_amdgcn_global_load_lds((const unsigned*)((const char*)(gbase) + (voff)[_i]), (PG8_LAS unsigned*)(lds + (bufoff) + ldsw + _i * 8192), 16, 0, 0); } while (0)
; #define PG8_BAR __builtin_amdgcn_s_barrier()
; template <class Epi, class Sched, bool ALIGN_EPI = false, bool SP2 = false, bool F16 = false>
; __device__ __forceinline__ void gemm_phase(PG8_LAS unsigned char* lds, const Gemm g, const Sched& S, const Epi& E) {
;     int tid_l = threadIdx.x; asm volatile("" : "+v"(tid_l));
;     const int tid = tid_l, wid = __builtin_amdgcn_readfirstlane(tid >> 6), lane = tid & 63, wr = wid >> 2, wc = wid & 3, fr = lane & 15, fq = lane >> 4;
;     const int K = g.K, nt = K / BK;
;     unsigned voffA[2], voffB[2];
; #pragma unroll
;     for (int i = 0; i < 2; ++i) { int R, C; stage_rc(tid * 16 + i * 8192, R, C); const int Rb = Epi::PERM ? ((R & ~31) + perm32(R & 31)) : R;
;         voffA[i] = (unsigned)(R * K + C) * 2u; voffB[i] = (unsigned)(Rb * K + C) * 2u; }
;     const size_t kstep = (size_t)(BK * 2);
;     const size_t hstep = (size_t)HALF * K * 2;
;     const size_t tstep = 2 * hstep;
;     const unsigned ldsw = (unsigned)wid * 1024u;
;     const int aoff = lds_byte(wr * 64 + fr, fq * 8), boff = lds_byte(wc * 32 + fr, fq * 8);
;     ...
;     Unit cur, nxt; int ui = 0;
;     if (!S.next(0, cur)) return;
;     f32x4 acc[2][2][4][2];
; #pragma unroll
;     for (int a = 0; a < 2; ++a)
; #pragma unroll
;         for (int b = 0; b < 2; ++b)
; #pragma unroll
;             for (int m = 0; m < 4; ++m)
; #pragma unroll
;                 for (int n = 0; n < 2; ++n) acc[a][b][m][n] = (f32x4){0.f, 0.f, 0.f, 0.f};
;     bf16x8 At[4][2], B0[2][2], B1[2][2];
;     const char* cA = (const char*)g.A + (size_t)cur.pm * tstep; const char* cB = (const char*)g.Bt + (size_t)cur.pn * tstep + (cur.pm >= g.mhalf ? g.bstride : (size_t)0);
;     S.a_ready(cur);
;     if constexpr (SP2) {
;         PG8_STAGE(PG8_SB(0, 0), cB, voffB); PG8_STAGE(PG8_SB(0, 1), cB + hstep, voffB); PG8_STAGE(PG8_SA(0, 0), cA, voffA); PG8_STAGE(PG8_SA(0, 1), cA + hstep, voffA);
;         if (wr == 1) PG8_BAR;
.LBB0_242:
	s_mov_b32 s61, s35
	v_writelane_b32 v255, s60, 14
	s_andn2_b64 vcc, exec, s[0:1]
	s_mov_b32 s95, s13
	v_writelane_b32 v255, s61, 15
	s_cbranch_vccnz .LBB0_438
	v_readlane_b32 s0, v252, 59
	v_mov_b32_e32 v7, v226
	v_readlane_b32 s1, v252, 60
	s_andn2_b64 vcc, exec, s[0:1]
	v_readfirstlane_b32 s0, v7
	s_cbranch_vccnz .LBB0_372
	s_lshr_b32 s98, s0, 6
	s_cmp_ge_u32 s98, 4
	s_cbranch_scc0 .Linproj_prio_done
	s_setprio 1
.Linproj_prio_done:
	v_lshlrev_b32_e32 v0, 4, v7
	s_waitcnt lgkmcnt(0)
	v_add_u32_e32 v1, 0x2000, v0
	v_ashrrev_i32_e32 v2, 31, v1
	v_lshrrev_b32_e32 v2, 22, v2
	v_add_u32_e32 v2, v1, v2
	v_ashrrev_i32_e32 v4, 10, v2
	v_mul_i32_i24_e32 v2, 0x400, v4
	v_sub_u32_e32 v1, v1, v2
	v_lshrrev_b32_e32 v2, 4, v1
	v_bitop3_b32 v1, v2, v1, 32 bitop3:0x6c
	v_ashrrev_i32_e32 v2, 31, v1
	v_lshrrev_b32_e32 v2, 26, v2
	v_add_u32_e32 v2, v1, v2
	v_lshlrev_b32_e32 v3, 3, v4
	s_lshl_b64 s[4:5], s[60:61], 23
	v_readlane_b32 s1, v252, 51
	v_ashrrev_i32_e32 v5, 6, v2
	v_and_b32_e32 v3, -16, v3
	s_add_u32 s30, s1, s4
	v_readlane_b32 s1, v252, 52
	v_add_u32_e32 v3, v5, v3
	s_addc_u32 s31, s1, s5
	v_and_b32_e32 v6, 3, v5
	s_mov_b32 s5, 0x1fffe0
	v_lshrrev_b32_e32 v8, 2, v3
	v_lshlrev_b32_e32 v9, 1, v3
	v_and_b32_e32 v2, 0xc0, v2
	v_and_or_b32 v6, v3, s5, v6
	v_and_b32_e32 v8, 4, v8
	v_and_b32_e32 v9, 24, v9
	v_sub_u32_e32 v1, v1, v2
	v_or3_b32 v8, v6, v8, v9
	v_lshlrev_b32_e32 v6, 5, v4
	v_ashrrev_i16_sdwa v1, v228, sext(v1) dst_sel:DWORD dst_unused:UNUSED_PAD src0_sel:DWORD src1_sel:BYTE_0
	v_and_b32_e32 v9, 32, v6
	v_bfe_i32 v6, v1, 0, 16
	v_add_lshl_u32 v1, v9, v6, 1
	v_lshl_add_u32 v142, v8, 11, v1
	v_lshl_add_u32 v144, v3, 11, v1
	v_bfe_i32 v1, v7, 27, 1
	v_lshrrev_b32_e32 v1, 22, v1
	v_add_u32_e32 v1, v0, v1
	v_and_b32_e32 v1, 0xfffffc00, v1
	v_sub_u32_e32 v0, v0, v1
	v_lshrrev_b32_e32 v1, 4, v0
	v_ashrrev_i32_e32 v2, 31, v7
	v_bitop3_b32 v0, v1, v0, 32 bitop3:0x6c
	v_lshrrev_b32_e32 v2, 26, v2
	v_ashrrev_i32_e32 v1, 31, v0
	v_add_u32_e32 v2, v7, v2
	v_lshrrev_b32_e32 v1, 26, v1
	v_ashrrev_i32_e32 v9, 6, v2
	v_add_u32_e32 v1, v0, v1
	v_lshlrev_b32_e32 v2, 3, v9
	v_ashrrev_i32_e32 v8, 6, v1
	v_and_b32_e32 v2, -16, v2
	s_ashr_i32 s1, s0, 6
	v_add_u32_e32 v2, v8, v2
	s_ashr_i32 s4, s0, 8
	s_lshl_b32 s20, s1, 10
	v_and_b32_e32 v3, 3, v8
	v_lshrrev_b32_e32 v10, 2, v2
	s_waitcnt lgkmcnt(1)
	v_lshlrev_b32_e32 v11, 1, v2
	v_and_b32_e32 v1, 0xc0, v1
	v_readlane_b32 s6, v254, 38
	v_and_or_b32 v3, v2, s5, v3
	v_and_b32_e32 v10, 4, v10
	v_and_b32_e32 v11, 24, v11
	v_sub_u32_e32 v0, v0, v1
	v_readlane_b32 s7, v254, 39
	s_add_u32 s5, s30, s6
	v_or3_b32 v3, v3, v10, v11
	v_lshlrev_b32_e32 v10, 5, v9
	v_ashrrev_i16_sdwa v0, v228, sext(v0) dst_sel:DWORD dst_unused:UNUSED_PAD src0_sel:DWORD src1_sel:BYTE_0
	s_addc_u32 s6, s31, s7
	v_readlane_b32 s7, v254, 42
	v_and_b32_e32 v11, 32, v10
	v_bfe_i32 v10, v0, 0, 16
	s_add_u32 s42, s5, s7
	v_add_lshl_u32 v0, v11, v10, 1
	s_addc_u32 s43, s6, 0
	s_add_i32 s21, s20, 0
	v_lshl_add_u32 v146, v3, 11, v0
	s_add_i32 m0, s21, 0x10000
	v_writelane_b32 v255, s14, 16
	global_load_lds_dwordx4 v146, s[42:43]
	s_add_i32 m0, s21, 0x12000
	s_add_u32 s6, s42, 0x40000
	global_load_lds_dwordx4 v142, s[42:43]
	s_addc_u32 s7, s43, 0
	s_add_i32 m0, s21, 0x14000
	v_writelane_b32 v255, s15, 17
	global_load_lds_dwordx4 v146, s[6:7]
	s_add_i32 m0, s21, 0x16000
	v_lshl_add_u32 v148, v2, 11, v0
	global_load_lds_dwordx4 v142, s[6:7]
	v_readlane_b32 s6, v254, 43
	s_mov_b32 m0, s21
	v_readlane_b32 s7, v254, 44
	s_add_i32 s14, s21, 0x2000
	s_add_i32 s15, s21, 0x4000
	s_add_i32 s37, s21, 0x6000
	s_cmp_eq_u32 s4, 1
	v_mov_b32_e32 v147, v129
	global_load_lds_dwordx4 v148, s[6:7]
	s_mov_b32 m0, s14
	v_mov_b32_e32 v143, v129
	global_load_lds_dwordx4 v144, s[6:7]
	v_readlane_b32 s6, v254, 45
	s_mov_b32 m0, s15
	v_readlane_b32 s7, v254, 46
	v_lshl_add_u64 v[0:1], s[42:43], 0, v[146:147]
	v_lshl_add_u64 v[2:3], s[42:43], 0, v[142:143]
	s_nop 2
	global_load_lds_dwordx4 v148, s[6:7]
	s_mov_b32 m0, s37
	s_nop 0
	global_load_lds_dwordx4 v144, s[6:7]
	s_cselect_b64 s[6:7], -1, 0
	v_writelane_b32 v255, s6, 18
	s_cmp_lg_u32 s4, 1
	s_nop 0
	v_writelane_b32 v255, s7, 19
	s_cbranch_scc1 .LBB0_246
	s_barrier

; #define PG8_STAGE(bufoff, gbase, voff) do { _Pragma("unroll") for (int _i = 0; _i < 2; ++_i) \
;         __builtin_amdgcn_global_load_lds((const unsigned*)((const char*)(gbase) + (voff)[_i]), (PG8_LAS unsigned*)(lds + (bufoff) + ldsw + _i * 8192), 16, 0, 0); } while (0)
; #define PG8_LDA(dst, b, h) do { _Pragma("unroll") for (int m = 0; m < 4; ++m) _Pragma("unroll") for (int k = 0; k < 2; ++k) dst[m][k] = *(const PG8_LAS bf16x8*)(lds + PG8_SA(b, h) + aoff + m * 2048 + k * 1024); } while (0)
; #define PG8_LDB(dst, b, h) do { _Pragma("unroll") for (int n = 0; n < 2; ++n) _Pragma("unroll") for (int k = 0; k < 2; ++k) dst[n][k] = *(const PG8_LAS bf16x8*)(lds + PG8_SB(b, h) + boff + n * 2048 + k * 1024); } while (0)
; #define PG8_MMA(ai, bj, At, Bt) do { __builtin_amdgcn_s_setprio(1); _Pragma("unroll") for (int m = 0; m < 4; ++m) _Pragma("unroll") for (int n = 0; n < 2; ++n) _Pragma("unroll") for (int k = 0; k < 2; ++k) \
;         acc[ai][bj][m][n] = mma16<F16>(Bt[n][k], At[m][k], acc[ai][bj][m][n]); __builtin_amdgcn_s_setprio(0); } while (0)
; #define PG8_WAIT_V(n) asm volatile("s_waitcnt vmcnt(" #n ")" ::: "memory")
; #define PG8_WAIT_L(n) asm volatile("s_waitcnt lgkmcnt(" #n ")" ::: "memory")
; #define PG8_BAR __builtin_amdgcn_s_barrier()
; #define PG8_SCHED __builtin_amdgcn_sched_barrier(0)
; template <class Epi, class Sched, bool ALIGN_EPI = false, bool SP2 = false, bool F16 = false>
; __device__ __forceinline__ void gemm_phase(PG8_LAS unsigned char* lds, const Gemm g, const Sched& S, const Epi& E) {
;     ...
;             PG8_LDB(B0, 0, 0); PG8_LDB(B1, 0, 1); PG8_SCHED; PG8_LDA(At, 0, 0); PG8_STAGE(PG8_SA(1, 1), a1 + hstep, voffA);
;             PG8_WAIT_V(8); PG8_WAIT_L(0); PG8_BAR; PG8_MMA(0, 0, At, B0); PG8_MMA(0, 1, At, B1); PG8_BAR; PG8_SCHED;
;             PG8_LDA(At, 0, 1); PG8_STAGE(PG8_SB(0, 0), b2, voffB); PG8_STAGE(PG8_SB(0, 1), b2 + hstep, voffB); PG8_STAGE(PG8_SA(0, 0), a2, voffA);
;             PG8_WAIT_V(8); PG8_WAIT_L(0); PG8_BAR; PG8_MMA(1, 0, At, B0); PG8_MMA(1, 1, At, B1); PG8_BAR; PG8_SCHED;
.LBB0_255:
	s_ashr_i32 s29, s28, 31
	s_lshl_b64 s[4:5], s[28:29], 19
	s_add_u32 s46, s96, s4
	s_addc_u32 s47, s97, s5
	s_and_b64 s[4:5], s[40:41], exec
	s_cselect_b32 s4, s47, s1
	s_cselect_b32 s5, s46, s0
	s_ashr_i32 s73, s72, 31
	s_lshl_b64 s[54:55], s[72:73], 19
	s_add_u32 s7, s30, s54
	s_addc_u32 s34, s31, s55
	s_cmp_gt_i32 s28, 63
	s_cselect_b32 s54, 0x400000, 0
	s_add_u32 s64, s7, s54
	s_addc_u32 s65, s34, 0
	s_and_b64 s[54:55], s[40:41], exec
	s_cselect_b32 s7, s65, s43
	s_cselect_b32 s34, s64, s42
	s_add_u32 s0, s0, 0x40080
	s_addc_u32 s1, s1, 0
	s_add_u32 s59, s42, 0x100
	s_addc_u32 s61, s43, 0
	s_mov_b32 s67, -2
	v_add_u32_e32 v242, 0x10000, v239
	s_add_u32 s42, s0, 0xfffc0080
	s_addc_u32 s43, s1, -1
	s_add_i32 s68, 0, 0x10000
	s_cmp_eq_u32 s67, 12
	s_cselect_b32 s55, s4, s43
	s_cselect_b32 s54, s5, s42
	s_cselect_b32 s43, s7, s61
	s_cselect_b32 s42, s34, s59
	s_add_i32 s70, 0, 0x14000
	ds_read_b128 v[130:133], v242
	ds_read_b128 v[134:137], v242 offset:1024
	ds_read_b128 v[138:141], v242 offset:2048
	ds_read_b128 v[162:165], v242 offset:3072
	ds_read_b128 v[166:169], v242 offset:16384
	ds_read_b128 v[170:173], v242 offset:17408
	ds_read_b128 v[186:189], v242 offset:18432
	ds_read_b128 v[190:193], v242 offset:19456
	s_add_i32 m0, s21, 0xc000
	ds_read_b128 v[194:197], v240
	ds_read_b128 v[198:201], v240 offset:1024
	ds_read_b128 v[202:205], v240 offset:2048
	ds_read_b128 v[206:209], v240 offset:3072
	ds_read_b128 v[210:213], v240 offset:4096
	ds_read_b128 v[214:217], v240 offset:5120
	ds_read_b128 v[218:221], v240 offset:6144
	ds_read_b128 v[222:225], v240 offset:7168
	global_load_lds_dwordx4 v154, s[0:1]
	s_add_i32 m0, s21, 0xe000
	s_nop 0
	global_load_lds_dwordx4 v156, s[0:1]
	s_waitcnt vmcnt(24)
	s_waitcnt lgkmcnt(0)
	s_barrier
	s_waitcnt lgkmcnt(0)
	v_mfma_f32_16x16x32_f16 v[124:127], v[130:133], v[194:197], 0
	v_mfma_f32_16x16x32_f16 v[120:123], v[138:141], v[194:197], 0
	v_mfma_f32_16x16x32_f16 v[116:119], v[130:133], v[202:205], 0
	v_mfma_f32_16x16x32_f16 v[112:115], v[138:141], v[202:205], 0
	v_mfma_f32_16x16x32_f16 v[108:111], v[130:133], v[210:213], 0
	v_mfma_f32_16x16x32_f16 v[104:107], v[138:141], v[210:213], 0
	v_mfma_f32_16x16x32_f16 v[100:103], v[130:133], v[218:221], 0
	v_mfma_f32_16x16x32_f16 v[96:99], v[138:141], v[218:221], 0
	v_mfma_f32_16x16x32_f16 v[124:127], v[134:137], v[198:201], v[124:127]
	v_mfma_f32_16x16x32_f16 v[120:123], v[162:165], v[198:201], v[120:123]
	v_mfma_f32_16x16x32_f16 v[116:119], v[134:137], v[206:209], v[116:119]
	v_mfma_f32_16x16x32_f16 v[112:115], v[162:165], v[206:209], v[112:115]
	v_mfma_f32_16x16x32_f16 v[108:111], v[134:137], v[214:217], v[108:111]
	v_mfma_f32_16x16x32_f16 v[104:107], v[162:165], v[214:217], v[104:107]
	v_mfma_f32_16x16x32_f16 v[100:103], v[134:137], v[222:225], v[100:103]
	v_mfma_f32_16x16x32_f16 v[96:99], v[162:165], v[222:225], v[96:99]
	v_mfma_f32_16x16x32_f16 v[60:63], v[166:169], v[194:197], 0
	v_mfma_f32_16x16x32_f16 v[56:59], v[186:189], v[194:197], 0
	v_mfma_f32_16x16x32_f16 v[52:55], v[166:169], v[202:205], 0
	v_mfma_f32_16x16x32_f16 v[48:51], v[186:189], v[202:205], 0
	v_mfma_f32_16x16x32_f16 v[44:47], v[166:169], v[210:213], 0
	v_mfma_f32_16x16x32_f16 v[40:43], v[186:189], v[210:213], 0
	v_mfma_f32_16x16x32_f16 v[36:39], v[166:169], v[218:221], 0
	v_mfma_f32_16x16x32_f16 v[32:35], v[186:189], v[218:221], 0
	v_mfma_f32_16x16x32_f16 v[60:63], v[170:173], v[198:201], v[60:63]
	v_mfma_f32_16x16x32_f16 v[56:59], v[190:193], v[198:201], v[56:59]
	v_mfma_f32_16x16x32_f16 v[52:55], v[170:173], v[206:209], v[52:55]
	v_mfma_f32_16x16x32_f16 v[48:51], v[190:193], v[206:209], v[48:51]
	v_mfma_f32_16x16x32_f16 v[44:47], v[170:173], v[214:217], v[44:47]
	v_mfma_f32_16x16x32_f16 v[40:43], v[190:193], v[214:217], v[40:43]
	v_mfma_f32_16x16x32_f16 v[36:39], v[170:173], v[222:225], v[36:39]
	v_mfma_f32_16x16x32_f16 v[32:35], v[190:193], v[222:225], v[32:35]
	s_barrier
	s_add_u32 s98, s42, s16
	s_addc_u32 s99, s43, s17
	s_add_u32 s100, s54, s16
	s_addc_u32 s101, s55, s17
	s_add_i32 s68, s68, s20
	s_mov_b32 m0, s68
	ds_read_b128 v[194:197], v240 offset:16384
	ds_read_b128 v[198:201], v240 offset:17408
	ds_read_b128 v[202:205], v240 offset:18432
	ds_read_b128 v[206:209], v240 offset:19456
	ds_read_b128 v[210:213], v240 offset:20480
	ds_read_b128 v[214:217], v240 offset:21504
	ds_read_b128 v[218:221], v240 offset:22528
	ds_read_b128 v[222:225], v240 offset:23552
	global_load_lds_dwordx4 v146, s[42:43]
	s_add_i32 m0, s68, 0x2000
	s_add_u32 s68, s42, 0x40000
	s_addc_u32 s69, s43, 0
	s_add_i32 s70, s70, s20
	global_load_lds_dwordx4 v142, s[42:43]
	s_mov_b32 m0, s70
	s_nop 0
	global_load_lds_dwordx4 v146, s[68:69]
	s_add_i32 m0, s70, 0x2000
	s_nop 0
	global_load_lds_dwordx4 v142, s[68:69]
	s_mov_b32 m0, s21
	s_nop 0
	global_load_lds_dwordx4 v148, s[54:55]
	s_mov_b32 m0, s14
	s_nop 0
	global_load_lds_dwordx4 v144, s[54:55]
	s_waitcnt vmcnt(24)
	s_waitcnt lgkmcnt(0)
	s_barrier
; #define PG8_STAGE(bufoff, gbase, voff) do { _Pragma("unroll") for (int _i = 0; _i < 2; ++_i) \
;         __builtin_amdgcn_global_load_lds((const unsigned*)((const char*)(gbase) + (voff)[_i]), (PG8_LAS unsigned*)(lds + (bufoff) + ldsw + _i * 8192), 16, 0, 0); } while (0)
; #define PG8_LDA(dst, b, h) do { _Pragma("unroll") for (int m = 0; m < 4; ++m) _Pragma("unroll") for (int k = 0; k < 2; ++k) dst[m][k] = *(const PG8_LAS bf16x8*)(lds + PG8_SA(b, h) + aoff + m * 2048 + k * 1024); } while (0)
; #define PG8_LDB(dst, b, h) do { _Pragma("unroll") for (int n = 0; n < 2; ++n) _Pragma("unroll") for (int k = 0; k < 2; ++k) dst[n][k] = *(const PG8_LAS bf16x8*)(lds + PG8_SB(b, h) + boff + n * 2048 + k * 1024); } while (0)
; #define PG8_MMA(ai, bj, At, Bt) do { __builtin_amdgcn_s_setprio(1); _Pragma("unroll") for (int m = 0; m < 4; ++m) _Pragma("unroll") for (int n = 0; n < 2; ++n) _Pragma("unroll") for (int k = 0; k < 2; ++k) \
;         acc[ai][bj][m][n] = mma16<F16>(Bt[n][k], At[m][k], acc[ai][bj][m][n]); __builtin_amdgcn_s_setprio(0); } while (0)
; #define PG8_WAIT_V(n) asm volatile("s_waitcnt vmcnt(" #n ")" ::: "memory")
; #define PG8_WAIT_L(n) asm volatile("s_waitcnt lgkmcnt(" #n ")" ::: "memory")
; #define PG8_BAR __builtin_amdgcn_s_barrier()
; #define PG8_SCHED __builtin_amdgcn_sched_barrier(0)
; template <class Epi, class Sched, bool ALIGN_EPI = false, bool SP2 = false, bool F16 = false>
; __device__ __forceinline__ void gemm_phase(PG8_LAS unsigned char* lds, const Gemm g, const Sched& S, const Epi& E) {
;     ...
;             PG8_WAIT_V(8); PG8_WAIT_L(0); PG8_BAR; PG8_MMA(1, 0, At, B0); PG8_MMA(1, 1, At, B1); PG8_BAR; PG8_SCHED;
;             PG8_LDB(B0, 1, 0); PG8_LDB(B1, 1, 1); PG8_SCHED; PG8_LDA(At, 1, 0); PG8_STAGE(PG8_SA(0, 1), a2 + hstep, voffA);
;             PG8_WAIT_V(8); PG8_WAIT_L(0); PG8_BAR; PG8_MMA(0, 0, At, B0); PG8_MMA(0, 1, At, B1); PG8_BAR; PG8_SCHED;
	s_waitcnt lgkmcnt(0)
	v_mfma_f32_16x16x32_f16 v[92:95], v[130:133], v[194:197], 0
	v_mfma_f32_16x16x32_f16 v[88:91], v[138:141], v[194:197], 0
	v_mfma_f32_16x16x32_f16 v[84:87], v[130:133], v[202:205], 0
	v_mfma_f32_16x16x32_f16 v[80:83], v[138:141], v[202:205], 0
	v_mfma_f32_16x16x32_f16 v[76:79], v[130:133], v[210:213], 0
	v_mfma_f32_16x16x32_f16 v[72:75], v[138:141], v[210:213], 0
	v_mfma_f32_16x16x32_f16 v[68:71], v[130:133], v[218:221], 0
	v_mfma_f32_16x16x32_f16 v[64:67], v[138:141], v[218:221], 0
	v_mfma_f32_16x16x32_f16 v[92:95], v[134:137], v[198:201], v[92:95]
	v_mfma_f32_16x16x32_f16 v[88:91], v[162:165], v[198:201], v[88:91]
	v_mfma_f32_16x16x32_f16 v[84:87], v[134:137], v[206:209], v[84:87]
	v_mfma_f32_16x16x32_f16 v[80:83], v[162:165], v[206:209], v[80:83]
	v_mfma_f32_16x16x32_f16 v[76:79], v[134:137], v[214:217], v[76:79]
	v_mfma_f32_16x16x32_f16 v[72:75], v[162:165], v[214:217], v[72:75]
	v_mfma_f32_16x16x32_f16 v[68:71], v[134:137], v[222:225], v[68:71]
	v_mfma_f32_16x16x32_f16 v[64:67], v[162:165], v[222:225], v[64:67]
	v_mfma_f32_16x16x32_f16 v[28:31], v[166:169], v[194:197], 0
	v_mfma_f32_16x16x32_f16 v[24:27], v[186:189], v[194:197], 0
	v_mfma_f32_16x16x32_f16 v[20:23], v[166:169], v[202:205], 0
	v_mfma_f32_16x16x32_f16 v[16:19], v[186:189], v[202:205], 0
	v_mfma_f32_16x16x32_f16 v[12:15], v[166:169], v[210:213], 0
	v_mfma_f32_16x16x32_f16 v[8:11], v[186:189], v[210:213], 0
	v_mfma_f32_16x16x32_f16 v[4:7], v[166:169], v[218:221], 0
	v_mfma_f32_16x16x32_f16 v[0:3], v[186:189], v[218:221], 0
	v_mfma_f32_16x16x32_f16 v[28:31], v[170:173], v[198:201], v[28:31]
	v_mfma_f32_16x16x32_f16 v[24:27], v[190:193], v[198:201], v[24:27]
	v_mfma_f32_16x16x32_f16 v[20:23], v[170:173], v[206:209], v[20:23]
	v_mfma_f32_16x16x32_f16 v[16:19], v[190:193], v[206:209], v[16:19]
	v_mfma_f32_16x16x32_f16 v[12:15], v[170:173], v[214:217], v[12:15]
	v_mfma_f32_16x16x32_f16 v[8:11], v[190:193], v[214:217], v[8:11]
	v_mfma_f32_16x16x32_f16 v[4:7], v[170:173], v[222:225], v[4:7]
	v_mfma_f32_16x16x32_f16 v[0:3], v[190:193], v[222:225], v[0:3]
	s_barrier
	s_add_i32 s68, 0, 0x18000
	s_add_i32 s69, 0, 0x1c000
	ds_read_b128 v[130:133], v242 offset:32768
	ds_read_b128 v[134:137], v242 offset:33792
	ds_read_b128 v[138:141], v242 offset:34816
	ds_read_b128 v[162:165], v242 offset:35840
	ds_read_b128 v[166:169], v242 offset:49152
	ds_read_b128 v[170:173], v242 offset:50176
	ds_read_b128 v[186:189], v242 offset:51200
	ds_read_b128 v[190:193], v242 offset:52224
	s_add_u32 s54, s54, 0x40000
	s_addc_u32 s55, s55, 0
	s_mov_b32 m0, s15
	ds_read_b128 v[194:197], v240 offset:32768
	ds_read_b128 v[198:201], v240 offset:33792
	ds_read_b128 v[202:205], v240 offset:34816
	ds_read_b128 v[206:209], v240 offset:35840
	ds_read_b128 v[210:213], v240 offset:36864
	ds_read_b128 v[214:217], v240 offset:37888
	ds_read_b128 v[218:221], v240 offset:38912
	ds_read_b128 v[222:225], v240 offset:39936
	global_load_lds_dwordx4 v148, s[54:55]
	s_mov_b32 m0, s37
	s_nop 0
	global_load_lds_dwordx4 v144, s[54:55]
	s_waitcnt vmcnt(8)
	s_waitcnt lgkmcnt(0)
	s_barrier
	s_waitcnt lgkmcnt(0)
	v_mfma_f32_16x16x32_f16 v[124:127], v[130:133], v[194:197], v[124:127]
	v_mfma_f32_16x16x32_f16 v[120:123], v[138:141], v[194:197], v[120:123]
	v_mfma_f32_16x16x32_f16 v[116:119], v[130:133], v[202:205], v[116:119]
	v_mfma_f32_16x16x32_f16 v[112:115], v[138:141], v[202:205], v[112:115]
	v_mfma_f32_16x16x32_f16 v[108:111], v[130:133], v[210:213], v[108:111]
	v_mfma_f32_16x16x32_f16 v[104:107], v[138:141], v[210:213], v[104:107]
	v_mfma_f32_16x16x32_f16 v[100:103], v[130:133], v[218:221], v[100:103]
	v_mfma_f32_16x16x32_f16 v[96:99], v[138:141], v[218:221], v[96:99]
	v_mfma_f32_16x16x32_f16 v[124:127], v[134:137], v[198:201], v[124:127]
	v_mfma_f32_16x16x32_f16 v[120:123], v[162:165], v[198:201], v[120:123]
	v_mfma_f32_16x16x32_f16 v[116:119], v[134:137], v[206:209], v[116:119]
	v_mfma_f32_16x16x32_f16 v[112:115], v[162:165], v[206:209], v[112:115]
	v_mfma_f32_16x16x32_f16 v[108:111], v[134:137], v[214:217], v[108:111]
	v_mfma_f32_16x16x32_f16 v[104:107], v[162:165], v[214:217], v[104:107]
	v_mfma_f32_16x16x32_f16 v[100:103], v[134:137], v[222:225], v[100:103]
	v_mfma_f32_16x16x32_f16 v[96:99], v[162:165], v[222:225], v[96:99]
	v_mfma_f32_16x16x32_f16 v[60:63], v[166:169], v[194:197], v[60:63]
	v_mfma_f32_16x16x32_f16 v[56:59], v[186:189], v[194:197], v[56:59]
	v_mfma_f32_16x16x32_f16 v[52:55], v[166:169], v[202:205], v[52:55]
	v_mfma_f32_16x16x32_f16 v[48:51], v[186:189], v[202:205], v[48:51]
	v_mfma_f32_16x16x32_f16 v[44:47], v[166:169], v[210:213], v[44:47]
	v_mfma_f32_16x16x32_f16 v[40:43], v[186:189], v[210:213], v[40:43]
	v_mfma_f32_16x16x32_f16 v[36:39], v[166:169], v[218:221], v[36:39]
	v_mfma_f32_16x16x32_f16 v[32:35], v[186:189], v[218:221], v[32:35]
	v_mfma_f32_16x16x32_f16 v[60:63], v[170:173], v[198:201], v[60:63]
	v_mfma_f32_16x16x32_f16 v[56:59], v[190:193], v[198:201], v[56:59]
	v_mfma_f32_16x16x32_f16 v[52:55], v[170:173], v[206:209], v[52:55]
	v_mfma_f32_16x16x32_f16 v[48:51], v[190:193], v[206:209], v[48:51]
	v_mfma_f32_16x16x32_f16 v[44:47], v[170:173], v[214:217], v[44:47]
	v_mfma_f32_16x16x32_f16 v[40:43], v[190:193], v[214:217], v[40:43]
	v_mfma_f32_16x16x32_f16 v[36:39], v[170:173], v[222:225], v[36:39]
	v_mfma_f32_16x16x32_f16 v[32:35], v[190:193], v[222:225], v[32:35]
	s_barrier
; #define PG8_STAGE(bufoff, gbase, voff) do { _Pragma("unroll") for (int _i = 0; _i < 2; ++_i) \
;         __builtin_amdgcn_global_load_lds((const unsigned*)((const char*)(gbase) + (voff)[_i]), (PG8_LAS unsigned*)(lds + (bufoff) + ldsw + _i * 8192), 16, 0, 0); } while (0)
; #define PG8_LDA(dst, b, h) do { _Pragma("unroll") for (int m = 0; m < 4; ++m) _Pragma("unroll") for (int k = 0; k < 2; ++k) dst[m][k] = *(const PG8_LAS bf16x8*)(lds + PG8_SA(b, h) + aoff + m * 2048 + k * 1024); } while (0)
; #define PG8_LDB(dst, b, h) do { _Pragma("unroll") for (int n = 0; n < 2; ++n) _Pragma("unroll") for (int k = 0; k < 2; ++k) dst[n][k] = *(const PG8_LAS bf16x8*)(lds + PG8_SB(b, h) + boff + n * 2048 + k * 1024); } while (0)
; #define PG8_MMA(ai, bj, At, Bt) do { __builtin_amdgcn_s_setprio(1); _Pragma("unroll") for (int m = 0; m < 4; ++m) _Pragma("unroll") for (int n = 0; n < 2; ++n) _Pragma("unroll") for (int k = 0; k < 2; ++k) \
;         acc[ai][bj][m][n] = mma16<F16>(Bt[n][k], At[m][k], acc[ai][bj][m][n]); __builtin_amdgcn_s_setprio(0); } while (0)
; #define PG8_WAIT_V(n) asm volatile("s_waitcnt vmcnt(" #n ")" ::: "memory")
; template <class Epi, class Sched, bool ALIGN_EPI = false, bool SP2 = false, bool F16 = false>
; __device__ __forceinline__ void gemm_phase(PG8_LAS unsigned char* lds, const Gemm g, const Sched& S, const Epi& E) {
;     ...
;             PG8_LDB(B0, 0, 0); PG8_LDB(B1, 0, 1); PG8_SCHED; PG8_LDA(At, 0, 0); PG8_STAGE(PG8_SA(1, 1), a1 + hstep, voffA);
;             PG8_WAIT_V(8); PG8_WAIT_L(0); PG8_BAR; PG8_MMA(0, 0, At, B0); PG8_MMA(0, 1, At, B1); PG8_BAR; PG8_SCHED;
;             PG8_LDA(At, 0, 1); PG8_STAGE(PG8_SB(0, 0), b2, voffB); PG8_STAGE(PG8_SB(0, 1), b2 + hstep, voffB); PG8_STAGE(PG8_SA(0, 0), a2, voffA);
;             PG8_WAIT_V(8); PG8_WAIT_L(0); PG8_BAR; PG8_MMA(1, 0, At, B0); PG8_MMA(1, 1, At, B1); PG8_BAR; PG8_SCHED;
;             PG8_LDB(B0, 1, 0); PG8_LDB(B1, 1, 1); PG8_SCHED; PG8_LDA(At, 1, 0); PG8_STAGE(PG8_SA(0, 1), a2 + hstep, voffA);
;             PG8_WAIT_V(8); PG8_WAIT_L(0); PG8_BAR; PG8_MMA(0, 0, At, B0); PG8_MMA(0, 1, At, B1); PG8_BAR; PG8_SCHED;
;             PG8_LDA(At, 1, 1); PG8_STAGE(PG8_SB(1, 0), b3, voffB); PG8_STAGE(PG8_SB(1, 1), b3 + hstep, voffB); PG8_STAGE(PG8_SA(1, 0), a3, voffA);
;             PG8_WAIT_V(8); PG8_WAIT_L(0); PG8_BAR; PG8_MMA(1, 0, At, B0); PG8_MMA(1, 1, At, B1); PG8_BAR; PG8_SCHED;
	s_add_i32 s54, s68, s20
	s_mov_b32 m0, s54
	ds_read_b128 v[194:197], v240 offset:49152
	ds_read_b128 v[198:201], v240 offset:50176
	ds_read_b128 v[202:205], v240 offset:51200
	ds_read_b128 v[206:209], v240 offset:52224
	ds_read_b128 v[210:213], v240 offset:53248
	ds_read_b128 v[214:217], v240 offset:54272
	ds_read_b128 v[218:221], v240 offset:55296
	ds_read_b128 v[222:225], v240 offset:56320
	global_load_lds_dwordx4 v146, s[98:99]
	s_add_i32 m0, s54, 0x2000
	s_add_u32 s42, s42, 0x40080
	s_addc_u32 s43, s43, 0
	s_add_i32 s54, s69, s20
	global_load_lds_dwordx4 v142, s[98:99]
	s_mov_b32 m0, s54
	s_nop 0
	global_load_lds_dwordx4 v146, s[42:43]
	s_add_i32 m0, s54, 0x2000
	s_nop 0
	global_load_lds_dwordx4 v142, s[42:43]
	s_mov_b32 m0, s44
	s_nop 0
	global_load_lds_dwordx4 v148, s[100:101]
	s_mov_b32 m0, s45
	s_nop 0
	global_load_lds_dwordx4 v144, s[100:101]
	s_waitcnt vmcnt(8)
	s_waitcnt lgkmcnt(0)
	s_barrier
	s_waitcnt lgkmcnt(0)
	v_mfma_f32_16x16x32_f16 v[92:95], v[130:133], v[194:197], v[92:95]
	v_mfma_f32_16x16x32_f16 v[88:91], v[138:141], v[194:197], v[88:91]
	v_mfma_f32_16x16x32_f16 v[84:87], v[130:133], v[202:205], v[84:87]
	v_mfma_f32_16x16x32_f16 v[80:83], v[138:141], v[202:205], v[80:83]
	v_mfma_f32_16x16x32_f16 v[76:79], v[130:133], v[210:213], v[76:79]
	v_mfma_f32_16x16x32_f16 v[72:75], v[138:141], v[210:213], v[72:75]
	v_mfma_f32_16x16x32_f16 v[68:71], v[130:133], v[218:221], v[68:71]
	v_mfma_f32_16x16x32_f16 v[64:67], v[138:141], v[218:221], v[64:67]
	v_mfma_f32_16x16x32_f16 v[92:95], v[134:137], v[198:201], v[92:95]
	v_mfma_f32_16x16x32_f16 v[88:91], v[162:165], v[198:201], v[88:91]
	v_mfma_f32_16x16x32_f16 v[84:87], v[134:137], v[206:209], v[84:87]
	v_mfma_f32_16x16x32_f16 v[80:83], v[162:165], v[206:209], v[80:83]
	v_mfma_f32_16x16x32_f16 v[76:79], v[134:137], v[214:217], v[76:79]
	v_mfma_f32_16x16x32_f16 v[72:75], v[162:165], v[214:217], v[72:75]
	v_mfma_f32_16x16x32_f16 v[68:71], v[134:137], v[222:225], v[68:71]
	v_mfma_f32_16x16x32_f16 v[64:67], v[162:165], v[222:225], v[64:67]
	v_mfma_f32_16x16x32_f16 v[28:31], v[166:169], v[194:197], v[28:31]
	v_mfma_f32_16x16x32_f16 v[24:27], v[186:189], v[194:197], v[24:27]
	v_mfma_f32_16x16x32_f16 v[20:23], v[166:169], v[202:205], v[20:23]
	v_mfma_f32_16x16x32_f16 v[16:19], v[186:189], v[202:205], v[16:19]
	v_mfma_f32_16x16x32_f16 v[12:15], v[166:169], v[210:213], v[12:15]
	v_mfma_f32_16x16x32_f16 v[8:11], v[186:189], v[210:213], v[8:11]
	v_mfma_f32_16x16x32_f16 v[4:7], v[166:169], v[218:221], v[4:7]
	v_mfma_f32_16x16x32_f16 v[0:3], v[186:189], v[218:221], v[0:3]
	v_mfma_f32_16x16x32_f16 v[28:31], v[170:173], v[198:201], v[28:31]
	v_mfma_f32_16x16x32_f16 v[24:27], v[190:193], v[198:201], v[24:27]
	v_mfma_f32_16x16x32_f16 v[20:23], v[170:173], v[206:209], v[20:23]
	v_mfma_f32_16x16x32_f16 v[16:19], v[190:193], v[206:209], v[16:19]
	v_mfma_f32_16x16x32_f16 v[12:15], v[170:173], v[214:217], v[12:15]
	v_mfma_f32_16x16x32_f16 v[8:11], v[190:193], v[214:217], v[8:11]
	v_mfma_f32_16x16x32_f16 v[4:7], v[170:173], v[222:225], v[4:7]
	v_mfma_f32_16x16x32_f16 v[0:3], v[190:193], v[222:225], v[0:3]
	s_barrier
	s_add_i32 s67, s67, 2
	s_add_u32 s0, s0, 0x100
	s_addc_u32 s1, s1, 0
	s_add_u32 s59, s59, 0x100
	s_addc_u32 s61, s61, 0
	s_cmp_gt_u32 s67, 13
.LBB0_256:
	s_add_u32 s42, s0, 0xfffc0080
	s_addc_u32 s43, s1, -1
	s_add_i32 s68, 0, 0x10000
	s_cmp_eq_u32 s67, 12
	s_cselect_b32 s55, s4, s43
	s_cselect_b32 s54, s5, s42
	s_cselect_b32 s43, s7, s61
	s_cselect_b32 s42, s34, s59
	s_add_i32 s70, 0, 0x14000
	ds_read_b128 v[130:133], v242
	ds_read_b128 v[134:137], v242 offset:1024
	ds_read_b128 v[138:141], v242 offset:2048
	ds_read_b128 v[162:165], v242 offset:3072
	ds_read_b128 v[166:169], v242 offset:16384
	ds_read_b128 v[170:173], v242 offset:17408
	ds_read_b128 v[186:189], v242 offset:18432
	ds_read_b128 v[190:193], v242 offset:19456
	s_add_i32 m0, s21, 0xc000
	ds_read_b128 v[194:197], v240
	ds_read_b128 v[198:201], v240 offset:1024
	ds_read_b128 v[202:205], v240 offset:2048
	ds_read_b128 v[206:209], v240 offset:3072
	ds_read_b128 v[210:213], v240 offset:4096
	ds_read_b128 v[214:217], v240 offset:5120
	ds_read_b128 v[218:221], v240 offset:6144
	ds_read_b128 v[222:225], v240 offset:7168
	global_load_lds_dwordx4 v154, s[0:1]
	s_add_i32 m0, s21, 0xe000
	s_nop 0
	global_load_lds_dwordx4 v156, s[0:1]
	s_waitcnt vmcnt(8)
	s_waitcnt lgkmcnt(0)
	s_barrier
	s_waitcnt lgkmcnt(0)
	v_mfma_f32_16x16x32_f16 v[124:127], v[130:133], v[194:197], v[124:127]
	v_mfma_f32_16x16x32_f16 v[120:123], v[138:141], v[194:197], v[120:123]
	v_mfma_f32_16x16x32_f16 v[116:119], v[130:133], v[202:205], v[116:119]
	v_mfma_f32_16x16x32_f16 v[112:115], v[138:141], v[202:205], v[112:115]
	v_mfma_f32_16x16x32_f16 v[108:111], v[130:133], v[210:213], v[108:111]
	v_mfma_f32_16x16x32_f16 v[104:107], v[138:141], v[210:213], v[104:107]
	v_mfma_f32_16x16x32_f16 v[100:103], v[130:133], v[218:221], v[100:103]
	v_mfma_f32_16x16x32_f16 v[96:99], v[138:141], v[218:221], v[96:99]
	v_mfma_f32_16x16x32_f16 v[124:127], v[134:137], v[198:201], v[124:127]
	v_mfma_f32_16x16x32_f16 v[120:123], v[162:165], v[198:201], v[120:123]
	v_mfma_f32_16x16x32_f16 v[116:119], v[134:137], v[206:209], v[116:119]
	v_mfma_f32_16x16x32_f16 v[112:115], v[162:165], v[206:209], v[112:115]
	v_mfma_f32_16x16x32_f16 v[108:111], v[134:137], v[214:217], v[108:111]
	v_mfma_f32_16x16x32_f16 v[104:107], v[162:165], v[214:217], v[104:107]
	v_mfma_f32_16x16x32_f16 v[100:103], v[134:137], v[222:225], v[100:103]
	v_mfma_f32_16x16x32_f16 v[96:99], v[162:165], v[222:225], v[96:99]
	v_mfma_f32_16x16x32_f16 v[60:63], v[166:169], v[194:197], v[60:63]
	v_mfma_f32_16x16x32_f16 v[56:59], v[186:189], v[194:197], v[56:59]
	v_mfma_f32_16x16x32_f16 v[52:55], v[166:169], v[202:205], v[52:55]
	v_mfma_f32_16x16x32_f16 v[48:51], v[186:189], v[202:205], v[48:51]
	v_mfma_f32_16x16x32_f16 v[44:47], v[166:169], v[210:213], v[44:47]
	v_mfma_f32_16x16x32_f16 v[40:43], v[186:189], v[210:213], v[40:43]
	v_mfma_f32_16x16x32_f16 v[36:39], v[166:169], v[218:221], v[36:39]
	v_mfma_f32_16x16x32_f16 v[32:35], v[186:189], v[218:221], v[32:35]
	v_mfma_f32_16x16x32_f16 v[60:63], v[170:173], v[198:201], v[60:63]
	v_mfma_f32_16x16x32_f16 v[56:59], v[190:193], v[198:201], v[56:59]
	v_mfma_f32_16x16x32_f16 v[52:55], v[170:173], v[206:209], v[52:55]
	v_mfma_f32_16x16x32_f16 v[48:51], v[190:193], v[206:209], v[48:51]
	v_mfma_f32_16x16x32_f16 v[44:47], v[170:173], v[214:217], v[44:47]
	v_mfma_f32_16x16x32_f16 v[40:43], v[190:193], v[214:217], v[40:43]
	v_mfma_f32_16x16x32_f16 v[36:39], v[170:173], v[222:225], v[36:39]
	v_mfma_f32_16x16x32_f16 v[32:35], v[190:193], v[222:225], v[32:35]
	s_barrier
; #define PG8_STAGE(bufoff, gbase, voff) do { _Pragma("unroll") for (int _i = 0; _i < 2; ++_i) \
;         __builtin_amdgcn_global_load_lds((const unsigned*)((const char*)(gbase) + (voff)[_i]), (PG8_LAS unsigned*)(lds + (bufoff) + ldsw + _i * 8192), 16, 0, 0); } while (0)
; #define PG8_LDA(dst, b, h) do { _Pragma("unroll") for (int m = 0; m < 4; ++m) _Pragma("unroll") for (int k = 0; k < 2; ++k) dst[m][k] = *(const PG8_LAS bf16x8*)(lds + PG8_SA(b, h) + aoff + m * 2048 + k * 1024); } while (0)
; #define PG8_LDB(dst, b, h) do { _Pragma("unroll") for (int n = 0; n < 2; ++n) _Pragma("unroll") for (int k = 0; k < 2; ++k) dst[n][k] = *(const PG8_LAS bf16x8*)(lds + PG8_SB(b, h) + boff + n * 2048 + k * 1024); } while (0)
; #define PG8_MMA(ai, bj, At, Bt) do { __builtin_amdgcn_s_setprio(1); _Pragma("unroll") for (int m = 0; m < 4; ++m) _Pragma("unroll") for (int n = 0; n < 2; ++n) _Pragma("unroll") for (int k = 0; k < 2; ++k) \
;         acc[ai][bj][m][n] = mma16<F16>(Bt[n][k], At[m][k], acc[ai][bj][m][n]); __builtin_amdgcn_s_setprio(0); } while (0)
; #define PG8_WAIT_V(n) asm volatile("s_waitcnt vmcnt(" #n ")" ::: "memory")
; template <class Epi, class Sched, bool ALIGN_EPI = false, bool SP2 = false, bool F16 = false>
; __device__ __forceinline__ void gemm_phase(PG8_LAS unsigned char* lds, const Gemm g, const Sched& S, const Epi& E) {
;     ...
;             PG8_LDB(B0, 0, 0); PG8_LDB(B1, 0, 1); PG8_SCHED; PG8_LDA(At, 0, 0); PG8_STAGE(PG8_SA(1, 1), a1 + hstep, voffA);
;             PG8_WAIT_V(8); PG8_WAIT_L(0); PG8_BAR; PG8_MMA(0, 0, At, B0); PG8_MMA(0, 1, At, B1); PG8_BAR; PG8_SCHED;
;             PG8_LDA(At, 0, 1); PG8_STAGE(PG8_SB(0, 0), b2, voffB); PG8_STAGE(PG8_SB(0, 1), b2 + hstep, voffB); PG8_STAGE(PG8_SA(0, 0), a2, voffA);
;             PG8_WAIT_V(8); PG8_WAIT_L(0); PG8_BAR; PG8_MMA(1, 0, At, B0); PG8_MMA(1, 1, At, B1); PG8_BAR; PG8_SCHED;
;             PG8_LDB(B0, 1, 0); PG8_LDB(B1, 1, 1); PG8_SCHED; PG8_LDA(At, 1, 0); PG8_STAGE(PG8_SA(0, 1), a2 + hstep, voffA);
;             PG8_WAIT_V(8); PG8_WAIT_L(0); PG8_BAR; PG8_MMA(0, 0, At, B0); PG8_MMA(0, 1, At, B1); PG8_BAR; PG8_SCHED;
;             PG8_LDA(At, 1, 1); PG8_STAGE(PG8_SB(1, 0), b3, voffB); PG8_STAGE(PG8_SB(1, 1), b3 + hstep, voffB); PG8_STAGE(PG8_SA(1, 0), a3, voffA);
;             PG8_WAIT_V(8); PG8_WAIT_L(0); PG8_BAR; PG8_MMA(1, 0, At, B0); PG8_MMA(1, 1, At, B1); PG8_BAR; PG8_SCHED;
	s_add_u32 s98, s42, s16
	s_addc_u32 s99, s43, s17
	s_add_u32 s100, s54, s16
	s_addc_u32 s101, s55, s17
	s_add_i32 s68, s68, s20
	s_mov_b32 m0, s68
	ds_read_b128 v[194:197], v240 offset:16384
	ds_read_b128 v[198:201], v240 offset:17408
	ds_read_b128 v[202:205], v240 offset:18432
	ds_read_b128 v[206:209], v240 offset:19456
	ds_read_b128 v[210:213], v240 offset:20480
	ds_read_b128 v[214:217], v240 offset:21504
	ds_read_b128 v[218:221], v240 offset:22528
	ds_read_b128 v[222:225], v240 offset:23552
	global_load_lds_dwordx4 v146, s[42:43]
	s_add_i32 m0, s68, 0x2000
	s_add_u32 s68, s42, 0x40000
	s_addc_u32 s69, s43, 0
	s_add_i32 s70, s70, s20
	global_load_lds_dwordx4 v142, s[42:43]
	s_mov_b32 m0, s70
	s_nop 0
	global_load_lds_dwordx4 v146, s[68:69]
	s_add_i32 m0, s70, 0x2000
	s_nop 0
	global_load_lds_dwordx4 v142, s[68:69]
	s_mov_b32 m0, s21
	s_nop 0
	global_load_lds_dwordx4 v148, s[54:55]
	s_mov_b32 m0, s14
	s_nop 0
	global_load_lds_dwordx4 v144, s[54:55]
	s_waitcnt vmcnt(8)
	s_waitcnt lgkmcnt(0)
	s_barrier
	s_waitcnt lgkmcnt(0)
	v_mfma_f32_16x16x32_f16 v[92:95], v[130:133], v[194:197], v[92:95]
	v_mfma_f32_16x16x32_f16 v[88:91], v[138:141], v[194:197], v[88:91]
	v_mfma_f32_16x16x32_f16 v[84:87], v[130:133], v[202:205], v[84:87]
	v_mfma_f32_16x16x32_f16 v[80:83], v[138:141], v[202:205], v[80:83]
	v_mfma_f32_16x16x32_f16 v[76:79], v[130:133], v[210:213], v[76:79]
	v_mfma_f32_16x16x32_f16 v[72:75], v[138:141], v[210:213], v[72:75]
	v_mfma_f32_16x16x32_f16 v[68:71], v[130:133], v[218:221], v[68:71]
	v_mfma_f32_16x16x32_f16 v[64:67], v[138:141], v[218:221], v[64:67]
	v_mfma_f32_16x16x32_f16 v[92:95], v[134:137], v[198:201], v[92:95]
	v_mfma_f32_16x16x32_f16 v[88:91], v[162:165], v[198:201], v[88:91]
	v_mfma_f32_16x16x32_f16 v[84:87], v[134:137], v[206:209], v[84:87]
	v_mfma_f32_16x16x32_f16 v[80:83], v[162:165], v[206:209], v[80:83]
	v_mfma_f32_16x16x32_f16 v[76:79], v[134:137], v[214:217], v[76:79]
	v_mfma_f32_16x16x32_f16 v[72:75], v[162:165], v[214:217], v[72:75]
	v_mfma_f32_16x16x32_f16 v[68:71], v[134:137], v[222:225], v[68:71]
	v_mfma_f32_16x16x32_f16 v[64:67], v[162:165], v[222:225], v[64:67]
	v_mfma_f32_16x16x32_f16 v[28:31], v[166:169], v[194:197], v[28:31]
	v_mfma_f32_16x16x32_f16 v[24:27], v[186:189], v[194:197], v[24:27]
	v_mfma_f32_16x16x32_f16 v[20:23], v[166:169], v[202:205], v[20:23]
	v_mfma_f32_16x16x32_f16 v[16:19], v[186:189], v[202:205], v[16:19]
	v_mfma_f32_16x16x32_f16 v[12:15], v[166:169], v[210:213], v[12:15]
	v_mfma_f32_16x16x32_f16 v[8:11], v[186:189], v[210:213], v[8:11]
	v_mfma_f32_16x16x32_f16 v[4:7], v[166:169], v[218:221], v[4:7]
	v_mfma_f32_16x16x32_f16 v[0:3], v[186:189], v[218:221], v[0:3]
	v_mfma_f32_16x16x32_f16 v[28:31], v[170:173], v[198:201], v[28:31]
	v_mfma_f32_16x16x32_f16 v[24:27], v[190:193], v[198:201], v[24:27]
	v_mfma_f32_16x16x32_f16 v[20:23], v[170:173], v[206:209], v[20:23]
	v_mfma_f32_16x16x32_f16 v[16:19], v[190:193], v[206:209], v[16:19]
	v_mfma_f32_16x16x32_f16 v[12:15], v[170:173], v[214:217], v[12:15]
	v_mfma_f32_16x16x32_f16 v[8:11], v[190:193], v[214:217], v[8:11]
	v_mfma_f32_16x16x32_f16 v[4:7], v[170:173], v[222:225], v[4:7]
	v_mfma_f32_16x16x32_f16 v[0:3], v[190:193], v[222:225], v[0:3]
	s_barrier
	s_add_i32 s68, 0, 0x18000
	s_add_i32 s69, 0, 0x1c000
	ds_read_b128 v[130:133], v242 offset:32768
	ds_read_b128 v[134:137], v242 offset:33792
	ds_read_b128 v[138:141], v242 offset:34816
	ds_read_b128 v[162:165], v242 offset:35840
	ds_read_b128 v[166:169], v242 offset:49152
	ds_read_b128 v[170:173], v242 offset:50176
	ds_read_b128 v[186:189], v242 offset:51200
	ds_read_b128 v[190:193], v242 offset:52224
	s_add_u32 s54, s54, 0x40000
	s_addc_u32 s55, s55, 0
	s_mov_b32 m0, s15
	ds_read_b128 v[194:197], v240 offset:32768
	ds_read_b128 v[198:201], v240 offset:33792
	ds_read_b128 v[202:205], v240 offset:34816
	ds_read_b128 v[206:209], v240 offset:35840
	ds_read_b128 v[210:213], v240 offset:36864
	ds_read_b128 v[214:217], v240 offset:37888
	ds_read_b128 v[218:221], v240 offset:38912
	ds_read_b128 v[222:225], v240 offset:39936
	global_load_lds_dwordx4 v148, s[54:55]
	s_mov_b32 m0, s37
	s_nop 0
	global_load_lds_dwordx4 v144, s[54:55]
	s_waitcnt vmcnt(8)
	s_waitcnt lgkmcnt(0)
	s_barrier
; #define PG8_STAGE(bufoff, gbase, voff) do { _Pragma("unroll") for (int _i = 0; _i < 2; ++_i) \
;         __builtin_amdgcn_global_load_lds((const unsigned*)((const char*)(gbase) + (voff)[_i]), (PG8_LAS unsigned*)(lds + (bufoff) + ldsw + _i * 8192), 16, 0, 0); } while (0)
; #define PG8_LDA(dst, b, h) do { _Pragma("unroll") for (int m = 0; m < 4; ++m) _Pragma("unroll") for (int k = 0; k < 2; ++k) dst[m][k] = *(const PG8_LAS bf16x8*)(lds + PG8_SA(b, h) + aoff + m * 2048 + k * 1024); } while (0)
; #define PG8_LDB(dst, b, h) do { _Pragma("unroll") for (int n = 0; n < 2; ++n) _Pragma("unroll") for (int k = 0; k < 2; ++k) dst[n][k] = *(const PG8_LAS bf16x8*)(lds + PG8_SB(b, h) + boff + n * 2048 + k * 1024); } while (0)
; #define PG8_MMA(ai, bj, At, Bt) do { __builtin_amdgcn_s_setprio(1); _Pragma("unroll") for (int m = 0; m < 4; ++m) _Pragma("unroll") for (int n = 0; n < 2; ++n) _Pragma("unroll") for (int k = 0; k < 2; ++k) \
;         acc[ai][bj][m][n] = mma16<F16>(Bt[n][k], At[m][k], acc[ai][bj][m][n]); __builtin_amdgcn_s_setprio(0); } while (0)
; template <class Epi, class Sched, bool ALIGN_EPI = false, bool SP2 = false, bool F16 = false>
; __device__ __forceinline__ void gemm_phase(PG8_LAS unsigned char* lds, const Gemm g, const Sched& S, const Epi& E) {
;     ...
;             PG8_LDB(B0, 0, 0); PG8_LDB(B1, 0, 1); PG8_SCHED; PG8_LDA(At, 0, 0); PG8_STAGE(PG8_SA(1, 1), a1 + hstep, voffA);
;             PG8_WAIT_V(8); PG8_WAIT_L(0); PG8_BAR; PG8_MMA(0, 0, At, B0); PG8_MMA(0, 1, At, B1); PG8_BAR; PG8_SCHED;
;             PG8_LDA(At, 0, 1); PG8_STAGE(PG8_SB(0, 0), b2, voffB); PG8_STAGE(PG8_SB(0, 1), b2 + hstep, voffB); PG8_STAGE(PG8_SA(0, 0), a2, voffA);
;             PG8_WAIT_V(8); PG8_WAIT_L(0); PG8_BAR; PG8_MMA(1, 0, At, B0); PG8_MMA(1, 1, At, B1); PG8_BAR; PG8_SCHED;
;             PG8_LDB(B0, 1, 0); PG8_LDB(B1, 1, 1); PG8_SCHED; PG8_LDA(At, 1, 0); PG8_STAGE(PG8_SA(0, 1), a2 + hstep, voffA);
;             PG8_WAIT_V(8); PG8_WAIT_L(0); PG8_BAR; PG8_MMA(0, 0, At, B0); PG8_MMA(0, 1, At, B1); PG8_BAR; PG8_SCHED;
;             PG8_LDA(At, 1, 1); PG8_STAGE(PG8_SB(1, 0), b3, voffB); PG8_STAGE(PG8_SB(1, 1), b3 + hstep, voffB); PG8_STAGE(PG8_SA(1, 0), a3, voffA);
;             PG8_WAIT_V(8); PG8_WAIT_L(0); PG8_BAR; PG8_MMA(1, 0, At, B0); PG8_MMA(1, 1, At, B1); PG8_BAR; PG8_SCHED;
;     ...
;         if constexpr (ALIGN_EPI) { if (wr == 0) PG8_BAR; }
	s_waitcnt lgkmcnt(0)
	v_mfma_f32_16x16x32_f16 v[124:127], v[130:133], v[194:197], v[124:127]
	v_mfma_f32_16x16x32_f16 v[120:123], v[138:141], v[194:197], v[120:123]
	v_mfma_f32_16x16x32_f16 v[116:119], v[130:133], v[202:205], v[116:119]
	v_mfma_f32_16x16x32_f16 v[112:115], v[138:141], v[202:205], v[112:115]
	v_mfma_f32_16x16x32_f16 v[108:111], v[130:133], v[210:213], v[108:111]
	v_mfma_f32_16x16x32_f16 v[104:107], v[138:141], v[210:213], v[104:107]
	v_mfma_f32_16x16x32_f16 v[100:103], v[130:133], v[218:221], v[100:103]
	v_mfma_f32_16x16x32_f16 v[96:99], v[138:141], v[218:221], v[96:99]
	v_mfma_f32_16x16x32_f16 v[124:127], v[134:137], v[198:201], v[124:127]
	v_mfma_f32_16x16x32_f16 v[120:123], v[162:165], v[198:201], v[120:123]
	v_mfma_f32_16x16x32_f16 v[116:119], v[134:137], v[206:209], v[116:119]
	v_mfma_f32_16x16x32_f16 v[112:115], v[162:165], v[206:209], v[112:115]
	v_mfma_f32_16x16x32_f16 v[108:111], v[134:137], v[214:217], v[108:111]
	v_mfma_f32_16x16x32_f16 v[104:107], v[162:165], v[214:217], v[104:107]
	v_mfma_f32_16x16x32_f16 v[100:103], v[134:137], v[222:225], v[100:103]
	v_mfma_f32_16x16x32_f16 v[96:99], v[162:165], v[222:225], v[96:99]
	v_mfma_f32_16x16x32_f16 v[60:63], v[166:169], v[194:197], v[60:63]
	v_mfma_f32_16x16x32_f16 v[56:59], v[186:189], v[194:197], v[56:59]
	v_mfma_f32_16x16x32_f16 v[52:55], v[166:169], v[202:205], v[52:55]
	v_mfma_f32_16x16x32_f16 v[48:51], v[186:189], v[202:205], v[48:51]
	v_mfma_f32_16x16x32_f16 v[44:47], v[166:169], v[210:213], v[44:47]
	v_mfma_f32_16x16x32_f16 v[40:43], v[186:189], v[210:213], v[40:43]
	v_mfma_f32_16x16x32_f16 v[36:39], v[166:169], v[218:221], v[36:39]
	v_mfma_f32_16x16x32_f16 v[32:35], v[186:189], v[218:221], v[32:35]
	v_mfma_f32_16x16x32_f16 v[60:63], v[170:173], v[198:201], v[60:63]
	v_mfma_f32_16x16x32_f16 v[56:59], v[190:193], v[198:201], v[56:59]
	v_mfma_f32_16x16x32_f16 v[52:55], v[170:173], v[206:209], v[52:55]
	v_mfma_f32_16x16x32_f16 v[48:51], v[190:193], v[206:209], v[48:51]
	v_mfma_f32_16x16x32_f16 v[44:47], v[170:173], v[214:217], v[44:47]
	v_mfma_f32_16x16x32_f16 v[40:43], v[190:193], v[214:217], v[40:43]
	v_mfma_f32_16x16x32_f16 v[36:39], v[170:173], v[222:225], v[36:39]
	v_mfma_f32_16x16x32_f16 v[32:35], v[190:193], v[222:225], v[32:35]
	s_barrier
	s_add_i32 s54, s68, s20
	s_mov_b32 m0, s54
	ds_read_b128 v[194:197], v240 offset:49152
	ds_read_b128 v[198:201], v240 offset:50176
	ds_read_b128 v[202:205], v240 offset:51200
	ds_read_b128 v[206:209], v240 offset:52224
	ds_read_b128 v[210:213], v240 offset:53248
	ds_read_b128 v[214:217], v240 offset:54272
	ds_read_b128 v[218:221], v240 offset:55296
	ds_read_b128 v[222:225], v240 offset:56320
	global_load_lds_dwordx4 v146, s[98:99]
	s_add_i32 m0, s54, 0x2000
	s_add_u32 s42, s42, 0x40080
	s_addc_u32 s43, s43, 0
	s_add_i32 s54, s69, s20
	global_load_lds_dwordx4 v142, s[98:99]
	s_mov_b32 m0, s54
	s_nop 0
	global_load_lds_dwordx4 v146, s[42:43]
	s_add_i32 m0, s54, 0x2000
	s_nop 0
	global_load_lds_dwordx4 v142, s[42:43]
	s_mov_b32 m0, s44
	s_nop 0
	global_load_lds_dwordx4 v148, s[100:101]
	s_mov_b32 m0, s45
	s_nop 0
	global_load_lds_dwordx4 v144, s[100:101]
	s_waitcnt vmcnt(8)
	s_waitcnt lgkmcnt(0)
	s_barrier
	s_waitcnt lgkmcnt(0)
	v_mfma_f32_16x16x32_f16 v[92:95], v[130:133], v[194:197], v[92:95]
	v_mfma_f32_16x16x32_f16 v[88:91], v[138:141], v[194:197], v[88:91]
	v_mfma_f32_16x16x32_f16 v[84:87], v[130:133], v[202:205], v[84:87]
	v_mfma_f32_16x16x32_f16 v[80:83], v[138:141], v[202:205], v[80:83]
	v_mfma_f32_16x16x32_f16 v[76:79], v[130:133], v[210:213], v[76:79]
	v_mfma_f32_16x16x32_f16 v[72:75], v[138:141], v[210:213], v[72:75]
	v_mfma_f32_16x16x32_f16 v[68:71], v[130:133], v[218:221], v[68:71]
	v_mfma_f32_16x16x32_f16 v[64:67], v[138:141], v[218:221], v[64:67]
	v_mfma_f32_16x16x32_f16 v[92:95], v[134:137], v[198:201], v[92:95]
	v_mfma_f32_16x16x32_f16 v[88:91], v[162:165], v[198:201], v[88:91]
	v_mfma_f32_16x16x32_f16 v[84:87], v[134:137], v[206:209], v[84:87]
	v_mfma_f32_16x16x32_f16 v[80:83], v[162:165], v[206:209], v[80:83]
	v_mfma_f32_16x16x32_f16 v[76:79], v[134:137], v[214:217], v[76:79]
	v_mfma_f32_16x16x32_f16 v[72:75], v[162:165], v[214:217], v[72:75]
	v_mfma_f32_16x16x32_f16 v[68:71], v[134:137], v[222:225], v[68:71]
	v_mfma_f32_16x16x32_f16 v[64:67], v[162:165], v[222:225], v[64:67]
	v_mfma_f32_16x16x32_f16 v[28:31], v[166:169], v[194:197], v[28:31]
	v_mfma_f32_16x16x32_f16 v[24:27], v[186:189], v[194:197], v[24:27]
	v_mfma_f32_16x16x32_f16 v[20:23], v[166:169], v[202:205], v[20:23]
	v_mfma_f32_16x16x32_f16 v[16:19], v[186:189], v[202:205], v[16:19]
	v_mfma_f32_16x16x32_f16 v[12:15], v[166:169], v[210:213], v[12:15]
	v_mfma_f32_16x16x32_f16 v[8:11], v[186:189], v[210:213], v[8:11]
	v_mfma_f32_16x16x32_f16 v[4:7], v[166:169], v[218:221], v[4:7]
	v_mfma_f32_16x16x32_f16 v[0:3], v[186:189], v[218:221], v[0:3]
	v_mfma_f32_16x16x32_f16 v[28:31], v[170:173], v[198:201], v[28:31]
	v_mfma_f32_16x16x32_f16 v[24:27], v[190:193], v[198:201], v[24:27]
	v_mfma_f32_16x16x32_f16 v[20:23], v[170:173], v[206:209], v[20:23]
	v_mfma_f32_16x16x32_f16 v[16:19], v[190:193], v[206:209], v[16:19]
	v_mfma_f32_16x16x32_f16 v[12:15], v[170:173], v[214:217], v[12:15]
	v_mfma_f32_16x16x32_f16 v[8:11], v[190:193], v[214:217], v[8:11]
	v_mfma_f32_16x16x32_f16 v[4:7], v[170:173], v[222:225], v[4:7]
	v_mfma_f32_16x16x32_f16 v[0:3], v[190:193], v[222:225], v[0:3]
	s_barrier
	s_add_i32 s67, s67, 2
	s_add_u32 s0, s0, 0x100
	s_addc_u32 s1, s1, 0
	s_add_u32 s59, s59, 0x100
	s_addc_u32 s61, s61, 0
	s_cmp_gt_u32 s67, 13
	s_cbranch_scc0 .LBB0_256
	s_and_b64 vcc, exec, s[8:9]
	s_cbranch_vccz .LBB0_259
	s_barrier

; #define PG8_WAIT_V(n) asm volatile("s_waitcnt vmcnt(" #n ")" ::: "memory")
; #define PG8_BAR __builtin_amdgcn_s_barrier()
; template <class Epi, class Sched, bool ALIGN_EPI = false, bool SP2 = false, bool F16 = false>
; __device__ __forceinline__ void gemm_phase(PG8_LAS unsigned char* lds, const Gemm g, const Sched& S, const Epi& E) {
;     ...
;     PG8_WAIT_V(0);
;     if constexpr (!ALIGN_EPI) { if (wr == 0) PG8_BAR; }
;     PG8_BAR;
.LBB0_371:
	s_setprio 0
	s_waitcnt vmcnt(0)
	v_readlane_b32 s72, v252, 38
	v_readlane_b32 s44, v252, 18
	v_readlane_b32 s80, v252, 40
	v_readlane_b32 s60, v255, 14
	v_readlane_b32 s14, v255, 16
	v_readlane_b32 s73, v252, 39
	v_readlane_b32 s58, v252, 32
	v_readlane_b32 s59, v252, 33
	v_readlane_b32 s81, v252, 41
	v_readlane_b32 s82, v252, 42
	v_readlane_b32 s83, v252, 43
	v_readlane_b32 s84, v252, 44
	v_readlane_b32 s85, v252, 45
	v_readlane_b32 s86, v252, 46
	v_readlane_b32 s87, v252, 47
	v_readlane_b32 s28, v255, 13
	v_readlane_b32 s76, v255, 11
	v_readlane_b32 s77, v255, 12
	s_mov_b32 s13, s95
	v_readlane_b32 s61, v255, 15
	v_readlane_b32 s15, v255, 17
	s_barrier
	v_readlane_b32 s45, v252, 19
	v_readlane_b32 s46, v252, 20
	v_readlane_b32 s47, v252, 21
	v_readlane_b32 s48, v252, 22
	v_readlane_b32 s49, v252, 23
	v_readlane_b32 s50, v252, 24
	v_readlane_b32 s51, v252, 25
	v_readlane_b32 s52, v252, 26
	v_readlane_b32 s53, v252, 27
	v_readlane_b32 s54, v252, 28
	v_readlane_b32 s55, v252, 29
	v_readlane_b32 s56, v252, 30
	v_readlane_b32 s57, v252, 31

; #define PG8_STAGE(bufoff, gbase, voff) do { _Pragma("unroll") for (int _i = 0; _i < 2; ++_i) \
;         __builtin_amdgcn_global_load_lds((const unsigned*)((const char*)(gbase) + (voff)[_i]), (PG8_LAS unsigned*)(lds + (bufoff) + ldsw + _i * 8192), 16, 0, 0); } while (0)
; #define PG8_BAR __builtin_amdgcn_s_barrier()
; template <class Epi, class Sched, bool ALIGN_EPI = false, bool SP2 = false, bool F16 = false>
; __device__ __forceinline__ void gemm_phase(PG8_LAS unsigned char* lds, const Gemm g, const Sched& S, const Epi& E) {
;     int tid_l = threadIdx.x; asm volatile("" : "+v"(tid_l));
;     const int tid = tid_l, wid = __builtin_amdgcn_readfirstlane(tid >> 6), lane = tid & 63, wr = wid >> 2, wc = wid & 3, fr = lane & 15, fq = lane >> 4;
;     const int K = g.K, nt = K / BK;
;     unsigned voffA[2], voffB[2];
; #pragma unroll
;     for (int i = 0; i < 2; ++i) { int R, C; stage_rc(tid * 16 + i * 8192, R, C); const int Rb = Epi::PERM ? ((R & ~31) + perm32(R & 31)) : R;
;         voffA[i] = (unsigned)(R * K + C) * 2u; voffB[i] = (unsigned)(Rb * K + C) * 2u; }
;     const size_t kstep = (size_t)(BK * 2);
;     const size_t hstep = (size_t)HALF * K * 2;
;     const size_t tstep = 2 * hstep;
;     const unsigned ldsw = (unsigned)wid * 1024u;
;     const int aoff = lds_byte(wr * 64 + fr, fq * 8), boff = lds_byte(wc * 32 + fr, fq * 8);
;     ...
;     Unit cur, nxt; int ui = 0;
;     if (!S.next(0, cur)) return;
;     f32x4 acc[2][2][4][2];
; #pragma unroll
;     for (int a = 0; a < 2; ++a)
; #pragma unroll
;         for (int b = 0; b < 2; ++b)
; #pragma unroll
;             for (int m = 0; m < 4; ++m)
; #pragma unroll
;                 for (int n = 0; n < 2; ++n) acc[a][b][m][n] = (f32x4){0.f, 0.f, 0.f, 0.f};
;     bf16x8 At[4][2], B0[2][2], B1[2][2];
;     const char* cA = (const char*)g.A + (size_t)cur.pm * tstep; const char* cB = (const char*)g.Bt + (size_t)cur.pn * tstep + (cur.pm >= g.mhalf ? g.bstride : (size_t)0);
;     S.a_ready(cur);
;     if constexpr (SP2) {
;         PG8_STAGE(PG8_SB(0, 0), cB, voffB); PG8_STAGE(PG8_SB(0, 1), cB + hstep, voffB); PG8_STAGE(PG8_SA(0, 0), cA, voffA); PG8_STAGE(PG8_SA(0, 1), cA + hstep, voffA);
;         if (wr == 1) PG8_BAR;
.LBB0_781:
	s_andn2_b64 vcc, exec, s[0:1]
	v_readlane_b32 s0, v254, 9
	v_readlane_b32 s1, v254, 10
	s_nop 1
	v_cndmask_b32_e64 v0, 0, 1, s[0:1]
	v_cmp_ne_u32_e64 s[38:39], 1, v0
	s_cbranch_vccnz .LBB0_892
	v_mov_b32_e32 v10, v226
	s_and_b64 vcc, exec, s[38:39]
	v_readfirstlane_b32 s4, v10
	s_cbranch_vccnz .LBB0_826
	s_lshr_b32 s98, s4, 6
	s_cmp_ge_u32 s98, 4
	s_cbranch_scc0 .Loutproj_prio_done
	s_setprio 1
.Loutproj_prio_done:
	v_lshlrev_b32_e32 v0, 4, v10
	s_waitcnt lgkmcnt(0)
	v_add_u32_e32 v1, 0x2000, v0
	v_ashrrev_i32_e32 v2, 31, v1
	v_lshrrev_b32_e32 v2, 22, v2
	v_add_u32_e32 v2, v1, v2
	v_ashrrev_i32_e32 v4, 10, v2
	v_mul_i32_i24_e32 v2, 0x400, v4
	v_sub_u32_e32 v1, v1, v2
	v_lshrrev_b32_e32 v2, 4, v1
	v_bitop3_b32 v1, v2, v1, 32 bitop3:0x6c
	v_ashrrev_i32_e32 v2, 31, v1
	v_readlane_b32 s0, v255, 14
	v_lshrrev_b32_e32 v2, 26, v2
	v_readlane_b32 s1, v255, 15
	v_add_u32_e32 v2, v1, v2
	v_lshlrev_b32_e32 v3, 3, v4
	s_lshl_b64 s[0:1], s[0:1], 21
	v_readlane_b32 s5, v254, 15
	v_ashrrev_i32_e32 v5, 6, v2
	v_and_b32_e32 v3, -16, v3
	s_add_u32 s8, s5, s0
	v_readlane_b32 s0, v254, 16
	v_add_u32_e32 v3, v5, v3
	s_addc_u32 s9, s0, s1
	v_and_b32_e32 v6, 3, v5
	s_mov_b32 s0, 0x1fffe0
	v_lshrrev_b32_e32 v7, 2, v3
	v_lshlrev_b32_e32 v8, 1, v3
	v_and_b32_e32 v2, 0xc0, v2
	v_and_or_b32 v6, v3, s0, v6
	v_and_b32_e32 v7, 4, v7
	v_and_b32_e32 v8, 24, v8
	v_sub_u32_e32 v1, v1, v2
	v_or3_b32 v7, v6, v7, v8
	v_lshlrev_b32_e32 v6, 5, v4
	v_ashrrev_i16_sdwa v1, v228, sext(v1) dst_sel:DWORD dst_unused:UNUSED_PAD src0_sel:DWORD src1_sel:BYTE_0
	v_and_b32_e32 v8, 32, v6
	v_bfe_i32 v6, v1, 0, 16
	v_add_lshl_u32 v1, v8, v6, 1
	v_lshl_add_u32 v162, v7, 11, v1
	v_lshl_add_u32 v164, v3, 11, v1
	v_bfe_i32 v1, v10, 27, 1
	v_lshrrev_b32_e32 v1, 22, v1
	v_add_u32_e32 v1, v0, v1
	v_and_b32_e32 v1, 0xfffffc00, v1
	v_sub_u32_e32 v0, v0, v1
	v_lshrrev_b32_e32 v1, 4, v0
	v_ashrrev_i32_e32 v2, 31, v10
	v_bitop3_b32 v0, v1, v0, 32 bitop3:0x6c
	v_lshrrev_b32_e32 v2, 26, v2
	v_ashrrev_i32_e32 v1, 31, v0
	v_add_u32_e32 v2, v10, v2
	v_lshrrev_b32_e32 v1, 26, v1
	v_ashrrev_i32_e32 v8, 6, v2
	v_add_u32_e32 v1, v0, v1
	v_lshlrev_b32_e32 v2, 3, v8
	v_ashrrev_i32_e32 v7, 6, v1
	v_and_b32_e32 v2, -16, v2
	v_add_u32_e32 v2, v7, v2
	v_and_b32_e32 v3, 3, v7
	v_lshrrev_b32_e32 v9, 2, v2
	v_lshlrev_b32_e32 v11, 1, v2
	v_and_b32_e32 v1, 0xc0, v1
	s_ashr_i32 s5, s4, 6
	v_and_or_b32 v3, v2, s0, v3
	v_and_b32_e32 v9, 4, v9
	v_and_b32_e32 v11, 24, v11
	v_sub_u32_e32 v0, v0, v1
	s_ashr_i32 s6, s4, 8
	s_lshl_b32 s10, s5, 10
	v_or3_b32 v3, v3, v9, v11
	v_lshlrev_b32_e32 v9, 5, v8
	v_ashrrev_i16_sdwa v0, v228, sext(v0) dst_sel:DWORD dst_unused:UNUSED_PAD src0_sel:DWORD src1_sel:BYTE_0
	v_readlane_b32 s0, v254, 47
	v_and_b32_e32 v11, 32, v9
	v_bfe_i32 v9, v0, 0, 16
	v_readlane_b32 s1, v254, 48
	s_add_u32 s0, s8, s0
	v_add_lshl_u32 v0, v11, v9, 1
	s_addc_u32 s1, s9, s1
	s_add_i32 s11, s10, 0
	v_lshl_add_u32 v166, v3, 11, v0
	s_add_i32 m0, s11, 0x10000
	v_lshl_add_u32 v168, v2, 11, v0
	global_load_lds_dwordx4 v166, s[0:1]
	s_add_i32 m0, s11, 0x12000
	s_add_u32 s14, s0, 0x40000
	global_load_lds_dwordx4 v162, s[0:1]
	s_addc_u32 s15, s1, 0
	s_add_i32 m0, s11, 0x14000
	s_add_i32 s13, s11, 0x2000
	global_load_lds_dwordx4 v166, s[14:15]
	s_add_i32 m0, s11, 0x16000
	v_readlane_b32 s20, v254, 52
	global_load_lds_dwordx4 v162, s[14:15]
	v_readlane_b32 s14, v254, 50
	s_mov_b32 m0, s11
	v_readlane_b32 s15, v254, 51
	v_readlane_b32 s21, v254, 53
	v_mov_b32_e32 v167, v129
	v_mov_b32_e32 v163, v129
	v_lshl_add_u64 v[0:1], s[0:1], 0, v[166:167]
	v_lshl_add_u64 v[2:3], s[0:1], 0, v[162:163]
	global_load_lds_dwordx4 v168, s[14:15]
	s_mov_b32 m0, s13
	s_nop 0
	global_load_lds_dwordx4 v164, s[14:15]
	s_add_i32 s14, s11, 0x4000
	s_mov_b32 m0, s14
	s_add_i32 s15, s11, 0x6000
	global_load_lds_dwordx4 v168, s[20:21]
	s_mov_b32 m0, s15
	s_cmp_eq_u32 s6, 1
	global_load_lds_dwordx4 v164, s[20:21]
	s_cselect_b64 s[44:45], -1, 0
	s_cmp_lg_u32 s6, 1
	s_cbranch_scc1 .LBB0_785
	s_barrier

; #define PG8_STAGE(bufoff, gbase, voff) do { _Pragma("unroll") for (int _i = 0; _i < 2; ++_i) \
;         __builtin_amdgcn_global_load_lds((const unsigned*)((const char*)(gbase) + (voff)[_i]), (PG8_LAS unsigned*)(lds + (bufoff) + ldsw + _i * 8192), 16, 0, 0); } while (0)
; #define PG8_LDA(dst, b, h) do { _Pragma("unroll") for (int m = 0; m < 4; ++m) _Pragma("unroll") for (int k = 0; k < 2; ++k) dst[m][k] = *(const PG8_LAS bf16x8*)(lds + PG8_SA(b, h) + aoff + m * 2048 + k * 1024); } while (0)
; #define PG8_LDB(dst, b, h) do { _Pragma("unroll") for (int n = 0; n < 2; ++n) _Pragma("unroll") for (int k = 0; k < 2; ++k) dst[n][k] = *(const PG8_LAS bf16x8*)(lds + PG8_SB(b, h) + boff + n * 2048 + k * 1024); } while (0)
; #define PG8_MMA(ai, bj, At, Bt) do { __builtin_amdgcn_s_setprio(1); _Pragma("unroll") for (int m = 0; m < 4; ++m) _Pragma("unroll") for (int n = 0; n < 2; ++n) _Pragma("unroll") for (int k = 0; k < 2; ++k) \
;         acc[ai][bj][m][n] = mma16<F16>(Bt[n][k], At[m][k], acc[ai][bj][m][n]); __builtin_amdgcn_s_setprio(0); } while (0)
; #define PG8_WAIT_V(n) asm volatile("s_waitcnt vmcnt(" #n ")" ::: "memory")
; template <class Epi, class Sched, bool ALIGN_EPI = false, bool SP2 = false, bool F16 = false>
; __device__ __forceinline__ void gemm_phase(PG8_LAS unsigned char* lds, const Gemm g, const Sched& S, const Epi& E) {
;     ...
;             PG8_LDB(B0, 0, 0); PG8_LDB(B1, 0, 1); PG8_SCHED; PG8_LDA(At, 0, 0); PG8_STAGE(PG8_SA(1, 1), a1 + hstep, voffA);
;             PG8_WAIT_V(8); PG8_WAIT_L(0); PG8_BAR; PG8_MMA(0, 0, At, B0); PG8_MMA(0, 1, At, B1); PG8_BAR; PG8_SCHED;
;             PG8_LDA(At, 0, 1); PG8_STAGE(PG8_SB(0, 0), b2, voffB); PG8_STAGE(PG8_SB(0, 1), b2 + hstep, voffB); PG8_STAGE(PG8_SA(0, 0), a2, voffA);
;             PG8_WAIT_V(8); PG8_WAIT_L(0); PG8_BAR; PG8_MMA(1, 0, At, B0); PG8_MMA(1, 1, At, B1); PG8_BAR; PG8_SCHED;
;             PG8_LDB(B0, 1, 0); PG8_LDB(B1, 1, 1); PG8_SCHED; PG8_LDA(At, 1, 0); PG8_STAGE(PG8_SA(0, 1), a2 + hstep, voffA);
;             PG8_WAIT_V(8); PG8_WAIT_L(0); PG8_BAR; PG8_MMA(0, 0, At, B0); PG8_MMA(0, 1, At, B1); PG8_BAR; PG8_SCHED;
;             PG8_LDA(At, 1, 1); PG8_STAGE(PG8_SB(1, 0), b3, voffB); PG8_STAGE(PG8_SB(1, 1), b3 + hstep, voffB); PG8_STAGE(PG8_SA(1, 0), a3, voffA);
;             PG8_WAIT_V(8); PG8_WAIT_L(0); PG8_BAR; PG8_MMA(1, 0, At, B0); PG8_MMA(1, 1, At, B1); PG8_BAR; PG8_SCHED;
.LBB0_801:
	s_add_u32 s0, s60, s62
	s_addc_u32 s1, s61, s63
	s_add_u32 s0, s0, 0x100
	s_addc_u32 s1, s1, 0
	s_add_u32 s4, s74, s62
	s_addc_u32 s5, s75, s63
	s_add_i32 s6, 0, 0x10000
	s_cmpk_eq_i32 s62, 0x700
	s_cselect_b32 s65, s55, s1
	s_cselect_b32 s64, s70, s0
	v_add_u32_e32 v128, s6, v239
	s_cselect_b32 s1, s53, s5
	s_cselect_b32 s0, s71, s4
	s_add_i32 s7, 0, 0x14000
	ds_read_b128 v[136:139], v128
	ds_read_b128 v[140:143], v128 offset:1024
	ds_read_b128 v[144:147], v128 offset:2048
	ds_read_b128 v[148:151], v128 offset:3072
	v_add_u32_e32 v128, s7, v239
	ds_read_b128 v[152:155], v128
	ds_read_b128 v[156:159], v128 offset:1024
	ds_read_b128 v[190:193], v128 offset:2048
	ds_read_b128 v[194:197], v128 offset:3072
	v_lshl_add_u64 v[130:131], v[132:133], 0, s[62:63]
	s_add_i32 m0, s11, 0xc000
	ds_read_b128 v[198:201], v240
	ds_read_b128 v[202:205], v240 offset:1024
	ds_read_b128 v[206:209], v240 offset:2048
	ds_read_b128 v[210:213], v240 offset:3072
	ds_read_b128 v[214:217], v240 offset:4096
	ds_read_b128 v[218:221], v240 offset:5120
	ds_read_b128 v[222:225], v240 offset:6144
	ds_read_b128 v[242:245], v240 offset:7168
	global_load_lds_dwordx4 v[130:131], off
	v_lshl_add_u64 v[130:131], v[134:135], 0, s[62:63]
	s_add_i32 m0, s11, 0xe000
	s_nop 0
	global_load_lds_dwordx4 v[130:131], off
	s_waitcnt vmcnt(8)
	s_waitcnt lgkmcnt(0)
	s_barrier
	s_waitcnt lgkmcnt(0)
	v_mfma_f32_16x16x32_bf16 v[124:127], v[136:139], v[198:201], v[124:127]
	v_mfma_f32_16x16x32_bf16 v[120:123], v[144:147], v[198:201], v[120:123]
	v_mfma_f32_16x16x32_bf16 v[116:119], v[136:139], v[206:209], v[116:119]
	v_mfma_f32_16x16x32_bf16 v[112:115], v[144:147], v[206:209], v[112:115]
	v_mfma_f32_16x16x32_bf16 v[108:111], v[136:139], v[214:217], v[108:111]
	v_mfma_f32_16x16x32_bf16 v[104:107], v[144:147], v[214:217], v[104:107]
	v_mfma_f32_16x16x32_bf16 v[100:103], v[136:139], v[222:225], v[100:103]
	v_mfma_f32_16x16x32_bf16 v[96:99], v[144:147], v[222:225], v[96:99]
	v_mfma_f32_16x16x32_bf16 v[124:127], v[140:143], v[202:205], v[124:127]
	v_mfma_f32_16x16x32_bf16 v[120:123], v[148:151], v[202:205], v[120:123]
	v_mfma_f32_16x16x32_bf16 v[116:119], v[140:143], v[210:213], v[116:119]
	v_mfma_f32_16x16x32_bf16 v[112:115], v[148:151], v[210:213], v[112:115]
	v_mfma_f32_16x16x32_bf16 v[108:111], v[140:143], v[218:221], v[108:111]
	v_mfma_f32_16x16x32_bf16 v[104:107], v[148:151], v[218:221], v[104:107]
	v_mfma_f32_16x16x32_bf16 v[100:103], v[140:143], v[242:245], v[100:103]
	v_mfma_f32_16x16x32_bf16 v[96:99], v[148:151], v[242:245], v[96:99]
	v_mfma_f32_16x16x32_bf16 v[60:63], v[152:155], v[198:201], v[60:63]
	v_mfma_f32_16x16x32_bf16 v[56:59], v[190:193], v[198:201], v[56:59]
	v_mfma_f32_16x16x32_bf16 v[52:55], v[152:155], v[206:209], v[52:55]
	v_mfma_f32_16x16x32_bf16 v[48:51], v[190:193], v[206:209], v[48:51]
	v_mfma_f32_16x16x32_bf16 v[44:47], v[152:155], v[214:217], v[44:47]
	v_mfma_f32_16x16x32_bf16 v[40:43], v[190:193], v[214:217], v[40:43]
	v_mfma_f32_16x16x32_bf16 v[36:39], v[152:155], v[222:225], v[36:39]
	v_mfma_f32_16x16x32_bf16 v[32:35], v[190:193], v[222:225], v[32:35]
	v_mfma_f32_16x16x32_bf16 v[60:63], v[156:159], v[202:205], v[60:63]
	v_mfma_f32_16x16x32_bf16 v[56:59], v[194:197], v[202:205], v[56:59]
	v_mfma_f32_16x16x32_bf16 v[52:55], v[156:159], v[210:213], v[52:55]
	v_mfma_f32_16x16x32_bf16 v[48:51], v[194:197], v[210:213], v[48:51]
	v_mfma_f32_16x16x32_bf16 v[44:47], v[156:159], v[218:221], v[44:47]
	v_mfma_f32_16x16x32_bf16 v[40:43], v[194:197], v[218:221], v[40:43]
	v_mfma_f32_16x16x32_bf16 v[36:39], v[156:159], v[242:245], v[36:39]
	v_mfma_f32_16x16x32_bf16 v[32:35], v[194:197], v[242:245], v[32:35]
	s_barrier
	s_add_i32 s4, s6, s10
	v_lshl_add_u64 v[130:131], s[0:1], 0, v[166:167]
	s_mov_b32 m0, s4
	ds_read_b128 v[198:201], v240 offset:16384
	ds_read_b128 v[202:205], v240 offset:17408
	ds_read_b128 v[206:209], v240 offset:18432
	ds_read_b128 v[210:213], v240 offset:19456
	ds_read_b128 v[214:217], v240 offset:20480
	ds_read_b128 v[218:221], v240 offset:21504
	ds_read_b128 v[222:225], v240 offset:22528
	ds_read_b128 v[242:245], v240 offset:23552
	global_load_lds_dwordx4 v[130:131], off
	s_add_i32 m0, s4, 0x2000
	s_add_u32 s4, s0, 0x40000
	v_lshl_add_u64 v[160:161], s[0:1], 0, v[162:163]
	s_addc_u32 s5, s1, 0
	s_add_i32 s6, s7, s10
	global_load_lds_dwordx4 v[160:161], off
	v_lshl_add_u64 v[246:247], s[4:5], 0, v[166:167]
	s_mov_b32 m0, s6
	v_lshl_add_u64 v[248:249], s[64:65], 0, v[164:165]
	global_load_lds_dwordx4 v[246:247], off
	v_lshl_add_u64 v[246:247], s[4:5], 0, v[162:163]
	s_add_i32 m0, s6, 0x2000
	s_nop 0
	global_load_lds_dwordx4 v[246:247], off
	v_lshl_add_u64 v[246:247], s[64:65], 0, v[168:169]
	s_mov_b32 m0, s11
	s_nop 0
	global_load_lds_dwordx4 v[246:247], off
	s_mov_b32 m0, s13
	s_nop 0
	global_load_lds_dwordx4 v[248:249], off
	s_waitcnt vmcnt(8)
	s_waitcnt lgkmcnt(0)
	s_barrier
; #define PG8_STAGE(bufoff, gbase, voff) do { _Pragma("unroll") for (int _i = 0; _i < 2; ++_i) \
;         __builtin_amdgcn_global_load_lds((const unsigned*)((const char*)(gbase) + (voff)[_i]), (PG8_LAS unsigned*)(lds + (bufoff) + ldsw + _i * 8192), 16, 0, 0); } while (0)
; #define PG8_LDA(dst, b, h) do { _Pragma("unroll") for (int m = 0; m < 4; ++m) _Pragma("unroll") for (int k = 0; k < 2; ++k) dst[m][k] = *(const PG8_LAS bf16x8*)(lds + PG8_SA(b, h) + aoff + m * 2048 + k * 1024); } while (0)
; #define PG8_LDB(dst, b, h) do { _Pragma("unroll") for (int n = 0; n < 2; ++n) _Pragma("unroll") for (int k = 0; k < 2; ++k) dst[n][k] = *(const PG8_LAS bf16x8*)(lds + PG8_SB(b, h) + boff + n * 2048 + k * 1024); } while (0)
; #define PG8_MMA(ai, bj, At, Bt) do { __builtin_amdgcn_s_setprio(1); _Pragma("unroll") for (int m = 0; m < 4; ++m) _Pragma("unroll") for (int n = 0; n < 2; ++n) _Pragma("unroll") for (int k = 0; k < 2; ++k) \
;         acc[ai][bj][m][n] = mma16<F16>(Bt[n][k], At[m][k], acc[ai][bj][m][n]); __builtin_amdgcn_s_setprio(0); } while (0)
; #define PG8_WAIT_V(n) asm volatile("s_waitcnt vmcnt(" #n ")" ::: "memory")
; template <class Epi, class Sched, bool ALIGN_EPI = false, bool SP2 = false, bool F16 = false>
; __device__ __forceinline__ void gemm_phase(PG8_LAS unsigned char* lds, const Gemm g, const Sched& S, const Epi& E) {
;     ...
;             PG8_LDB(B0, 0, 0); PG8_LDB(B1, 0, 1); PG8_SCHED; PG8_LDA(At, 0, 0); PG8_STAGE(PG8_SA(1, 1), a1 + hstep, voffA);
;             PG8_WAIT_V(8); PG8_WAIT_L(0); PG8_BAR; PG8_MMA(0, 0, At, B0); PG8_MMA(0, 1, At, B1); PG8_BAR; PG8_SCHED;
;             PG8_LDA(At, 0, 1); PG8_STAGE(PG8_SB(0, 0), b2, voffB); PG8_STAGE(PG8_SB(0, 1), b2 + hstep, voffB); PG8_STAGE(PG8_SA(0, 0), a2, voffA);
;             PG8_WAIT_V(8); PG8_WAIT_L(0); PG8_BAR; PG8_MMA(1, 0, At, B0); PG8_MMA(1, 1, At, B1); PG8_BAR; PG8_SCHED;
;             PG8_LDB(B0, 1, 0); PG8_LDB(B1, 1, 1); PG8_SCHED; PG8_LDA(At, 1, 0); PG8_STAGE(PG8_SA(0, 1), a2 + hstep, voffA);
;             PG8_WAIT_V(8); PG8_WAIT_L(0); PG8_BAR; PG8_MMA(0, 0, At, B0); PG8_MMA(0, 1, At, B1); PG8_BAR; PG8_SCHED;
;             PG8_LDA(At, 1, 1); PG8_STAGE(PG8_SB(1, 0), b3, voffB); PG8_STAGE(PG8_SB(1, 1), b3 + hstep, voffB); PG8_STAGE(PG8_SA(1, 0), a3, voffA);
;             PG8_WAIT_V(8); PG8_WAIT_L(0); PG8_BAR; PG8_MMA(1, 0, At, B0); PG8_MMA(1, 1, At, B1); PG8_BAR; PG8_SCHED;
	s_waitcnt lgkmcnt(0)
	v_mfma_f32_16x16x32_bf16 v[92:95], v[136:139], v[198:201], v[92:95]
	v_mfma_f32_16x16x32_bf16 v[88:91], v[144:147], v[198:201], v[88:91]
	v_mfma_f32_16x16x32_bf16 v[84:87], v[136:139], v[206:209], v[84:87]
	v_mfma_f32_16x16x32_bf16 v[80:83], v[144:147], v[206:209], v[80:83]
	v_mfma_f32_16x16x32_bf16 v[76:79], v[136:139], v[214:217], v[76:79]
	v_mfma_f32_16x16x32_bf16 v[72:75], v[144:147], v[214:217], v[72:75]
	v_mfma_f32_16x16x32_bf16 v[68:71], v[136:139], v[222:225], v[68:71]
	v_mfma_f32_16x16x32_bf16 v[64:67], v[144:147], v[222:225], v[64:67]
	v_mfma_f32_16x16x32_bf16 v[92:95], v[140:143], v[202:205], v[92:95]
	v_mfma_f32_16x16x32_bf16 v[88:91], v[148:151], v[202:205], v[88:91]
	v_mfma_f32_16x16x32_bf16 v[84:87], v[140:143], v[210:213], v[84:87]
	v_mfma_f32_16x16x32_bf16 v[80:83], v[148:151], v[210:213], v[80:83]
	v_mfma_f32_16x16x32_bf16 v[76:79], v[140:143], v[218:221], v[76:79]
	v_mfma_f32_16x16x32_bf16 v[72:75], v[148:151], v[218:221], v[72:75]
	v_mfma_f32_16x16x32_bf16 v[68:71], v[140:143], v[242:245], v[68:71]
	v_mfma_f32_16x16x32_bf16 v[64:67], v[148:151], v[242:245], v[64:67]
	v_mfma_f32_16x16x32_bf16 v[28:31], v[152:155], v[198:201], v[28:31]
	v_mfma_f32_16x16x32_bf16 v[24:27], v[190:193], v[198:201], v[24:27]
	v_mfma_f32_16x16x32_bf16 v[20:23], v[152:155], v[206:209], v[20:23]
	v_mfma_f32_16x16x32_bf16 v[16:19], v[190:193], v[206:209], v[16:19]
	v_mfma_f32_16x16x32_bf16 v[12:15], v[152:155], v[214:217], v[12:15]
	v_mfma_f32_16x16x32_bf16 v[8:11], v[190:193], v[214:217], v[8:11]
	v_mfma_f32_16x16x32_bf16 v[4:7], v[152:155], v[222:225], v[4:7]
	v_mfma_f32_16x16x32_bf16 v[0:3], v[190:193], v[222:225], v[0:3]
	v_mfma_f32_16x16x32_bf16 v[28:31], v[156:159], v[202:205], v[28:31]
	v_mfma_f32_16x16x32_bf16 v[24:27], v[194:197], v[202:205], v[24:27]
	v_mfma_f32_16x16x32_bf16 v[20:23], v[156:159], v[210:213], v[20:23]
	v_mfma_f32_16x16x32_bf16 v[16:19], v[194:197], v[210:213], v[16:19]
	v_mfma_f32_16x16x32_bf16 v[12:15], v[156:159], v[218:221], v[12:15]
	v_mfma_f32_16x16x32_bf16 v[8:11], v[194:197], v[218:221], v[8:11]
	v_mfma_f32_16x16x32_bf16 v[4:7], v[156:159], v[242:245], v[4:7]
	v_mfma_f32_16x16x32_bf16 v[0:3], v[194:197], v[242:245], v[0:3]
	s_barrier
	s_add_i32 s6, 0, 0x18000
	v_add_u32_e32 v128, s6, v239
	s_add_i32 s7, 0, 0x1c000
	ds_read_b128 v[136:139], v128
	ds_read_b128 v[140:143], v128 offset:1024
	ds_read_b128 v[144:147], v128 offset:2048
	ds_read_b128 v[148:151], v128 offset:3072
	v_add_u32_e32 v128, s7, v239
	ds_read_b128 v[152:155], v128
	ds_read_b128 v[156:159], v128 offset:1024
	ds_read_b128 v[190:193], v128 offset:2048
	ds_read_b128 v[194:197], v128 offset:3072
	s_add_u32 s4, s64, 0x40000
	s_addc_u32 s5, s65, 0
	s_mov_b32 m0, s14
	v_lshl_add_u64 v[250:251], s[4:5], 0, v[168:169]
	ds_read_b128 v[198:201], v240 offset:32768
	ds_read_b128 v[202:205], v240 offset:33792
	ds_read_b128 v[206:209], v240 offset:34816
	ds_read_b128 v[210:213], v240 offset:35840
	ds_read_b128 v[214:217], v240 offset:36864
	ds_read_b128 v[218:221], v240 offset:37888
	ds_read_b128 v[222:225], v240 offset:38912
	ds_read_b128 v[242:245], v240 offset:39936
	global_load_lds_dwordx4 v[250:251], off
	v_lshl_add_u64 v[250:251], s[4:5], 0, v[164:165]
	s_mov_b32 m0, s15
	s_nop 0
	global_load_lds_dwordx4 v[250:251], off
	s_waitcnt vmcnt(8)
	s_waitcnt lgkmcnt(0)
	s_barrier
	s_waitcnt lgkmcnt(0)
	v_mfma_f32_16x16x32_bf16 v[124:127], v[136:139], v[198:201], v[124:127]
	v_mfma_f32_16x16x32_bf16 v[120:123], v[144:147], v[198:201], v[120:123]
	v_mfma_f32_16x16x32_bf16 v[116:119], v[136:139], v[206:209], v[116:119]
	v_mfma_f32_16x16x32_bf16 v[112:115], v[144:147], v[206:209], v[112:115]
	v_mfma_f32_16x16x32_bf16 v[108:111], v[136:139], v[214:217], v[108:111]
	v_mfma_f32_16x16x32_bf16 v[104:107], v[144:147], v[214:217], v[104:107]
	v_mfma_f32_16x16x32_bf16 v[100:103], v[136:139], v[222:225], v[100:103]
	v_mfma_f32_16x16x32_bf16 v[96:99], v[144:147], v[222:225], v[96:99]
	v_mfma_f32_16x16x32_bf16 v[124:127], v[140:143], v[202:205], v[124:127]
	v_mfma_f32_16x16x32_bf16 v[120:123], v[148:151], v[202:205], v[120:123]
	v_mfma_f32_16x16x32_bf16 v[116:119], v[140:143], v[210:213], v[116:119]
	v_mfma_f32_16x16x32_bf16 v[112:115], v[148:151], v[210:213], v[112:115]
	v_mfma_f32_16x16x32_bf16 v[108:111], v[140:143], v[218:221], v[108:111]
	v_mfma_f32_16x16x32_bf16 v[104:107], v[148:151], v[218:221], v[104:107]
	v_mfma_f32_16x16x32_bf16 v[100:103], v[140:143], v[242:245], v[100:103]
	v_mfma_f32_16x16x32_bf16 v[96:99], v[148:151], v[242:245], v[96:99]
	v_mfma_f32_16x16x32_bf16 v[60:63], v[152:155], v[198:201], v[60:63]
	v_mfma_f32_16x16x32_bf16 v[56:59], v[190:193], v[198:201], v[56:59]
	v_mfma_f32_16x16x32_bf16 v[52:55], v[152:155], v[206:209], v[52:55]
	v_mfma_f32_16x16x32_bf16 v[48:51], v[190:193], v[206:209], v[48:51]
	v_mfma_f32_16x16x32_bf16 v[44:47], v[152:155], v[214:217], v[44:47]
	v_mfma_f32_16x16x32_bf16 v[40:43], v[190:193], v[214:217], v[40:43]
	v_mfma_f32_16x16x32_bf16 v[36:39], v[152:155], v[222:225], v[36:39]
	v_mfma_f32_16x16x32_bf16 v[32:35], v[190:193], v[222:225], v[32:35]
	v_mfma_f32_16x16x32_bf16 v[60:63], v[156:159], v[202:205], v[60:63]
	v_mfma_f32_16x16x32_bf16 v[56:59], v[194:197], v[202:205], v[56:59]
	v_mfma_f32_16x16x32_bf16 v[52:55], v[156:159], v[210:213], v[52:55]
	v_mfma_f32_16x16x32_bf16 v[48:51], v[194:197], v[210:213], v[48:51]
	v_mfma_f32_16x16x32_bf16 v[44:47], v[156:159], v[218:221], v[44:47]
	v_mfma_f32_16x16x32_bf16 v[40:43], v[194:197], v[218:221], v[40:43]
	v_mfma_f32_16x16x32_bf16 v[36:39], v[156:159], v[242:245], v[36:39]
	v_mfma_f32_16x16x32_bf16 v[32:35], v[194:197], v[242:245], v[32:35]
	s_barrier
; #define PG8_STAGE(bufoff, gbase, voff) do { _Pragma("unroll") for (int _i = 0; _i < 2; ++_i) \
;         __builtin_amdgcn_global_load_lds((const unsigned*)((const char*)(gbase) + (voff)[_i]), (PG8_LAS unsigned*)(lds + (bufoff) + ldsw + _i * 8192), 16, 0, 0); } while (0)
; #define PG8_LDA(dst, b, h) do { _Pragma("unroll") for (int m = 0; m < 4; ++m) _Pragma("unroll") for (int k = 0; k < 2; ++k) dst[m][k] = *(const PG8_LAS bf16x8*)(lds + PG8_SA(b, h) + aoff + m * 2048 + k * 1024); } while (0)
; #define PG8_LDB(dst, b, h) do { _Pragma("unroll") for (int n = 0; n < 2; ++n) _Pragma("unroll") for (int k = 0; k < 2; ++k) dst[n][k] = *(const PG8_LAS bf16x8*)(lds + PG8_SB(b, h) + boff + n * 2048 + k * 1024); } while (0)
; #define PG8_MMA(ai, bj, At, Bt) do { __builtin_amdgcn_s_setprio(1); _Pragma("unroll") for (int m = 0; m < 4; ++m) _Pragma("unroll") for (int n = 0; n < 2; ++n) _Pragma("unroll") for (int k = 0; k < 2; ++k) \
;         acc[ai][bj][m][n] = mma16<F16>(Bt[n][k], At[m][k], acc[ai][bj][m][n]); __builtin_amdgcn_s_setprio(0); } while (0)
; template <class Epi, class Sched, bool ALIGN_EPI = false, bool SP2 = false, bool F16 = false>
; __device__ __forceinline__ void gemm_phase(PG8_LAS unsigned char* lds, const Gemm g, const Sched& S, const Epi& E) {
;     ...
;             if constexpr (Epi::KHOOK) { if (t == 4 || t == 10) E.khook(acc, cur, t, wr, fr); }
;     ...
;             PG8_LDB(B0, 0, 0); PG8_LDB(B1, 0, 1); PG8_SCHED; PG8_LDA(At, 0, 0); PG8_STAGE(PG8_SA(1, 1), a1 + hstep, voffA);
;             PG8_WAIT_V(8); PG8_WAIT_L(0); PG8_BAR; PG8_MMA(0, 0, At, B0); PG8_MMA(0, 1, At, B1); PG8_BAR; PG8_SCHED;
;             PG8_LDA(At, 0, 1); PG8_STAGE(PG8_SB(0, 0), b2, voffB); PG8_STAGE(PG8_SB(0, 1), b2 + hstep, voffB); PG8_STAGE(PG8_SA(0, 0), a2, voffA);
;             PG8_WAIT_V(8); PG8_WAIT_L(0); PG8_BAR; PG8_MMA(1, 0, At, B0); PG8_MMA(1, 1, At, B1); PG8_BAR; PG8_SCHED;
;             PG8_LDB(B0, 1, 0); PG8_LDB(B1, 1, 1); PG8_SCHED; PG8_LDA(At, 1, 0); PG8_STAGE(PG8_SA(0, 1), a2 + hstep, voffA);
;             PG8_WAIT_V(8); PG8_WAIT_L(0); PG8_BAR; PG8_MMA(0, 0, At, B0); PG8_MMA(0, 1, At, B1); PG8_BAR; PG8_SCHED;
;             PG8_LDA(At, 1, 1); PG8_STAGE(PG8_SB(1, 0), b3, voffB); PG8_STAGE(PG8_SB(1, 1), b3 + hstep, voffB); PG8_STAGE(PG8_SA(1, 0), a3, voffA);
;             PG8_WAIT_V(8); PG8_WAIT_L(0); PG8_BAR; PG8_MMA(1, 0, At, B0); PG8_MMA(1, 1, At, B1); PG8_BAR; PG8_SCHED;
	s_add_i32 s4, s6, s10
	v_lshl_add_u64 v[130:131], v[130:131], 0, s[16:17]
	s_mov_b32 m0, s4
	ds_read_b128 v[198:201], v240 offset:49152
	ds_read_b128 v[202:205], v240 offset:50176
	ds_read_b128 v[206:209], v240 offset:51200
	ds_read_b128 v[210:213], v240 offset:52224
	ds_read_b128 v[214:217], v240 offset:53248
	ds_read_b128 v[218:221], v240 offset:54272
	ds_read_b128 v[222:225], v240 offset:55296
	ds_read_b128 v[242:245], v240 offset:56320
	global_load_lds_dwordx4 v[130:131], off
	s_add_i32 m0, s4, 0x2000
	s_add_u32 s0, s0, 0x40080
	v_lshl_add_u64 v[130:131], v[160:161], 0, s[16:17]
	s_addc_u32 s1, s1, 0
	s_add_i32 s4, s7, s10
	global_load_lds_dwordx4 v[130:131], off
	v_lshl_add_u64 v[130:131], s[0:1], 0, v[166:167]
	s_mov_b32 m0, s4
	s_nop 0
	global_load_lds_dwordx4 v[130:131], off
	v_lshl_add_u64 v[130:131], s[0:1], 0, v[162:163]
	s_add_i32 m0, s4, 0x2000
	s_nop 0
	global_load_lds_dwordx4 v[130:131], off
	v_lshl_add_u64 v[130:131], v[246:247], 0, s[16:17]
	s_mov_b32 m0, s30
	s_nop 0
	global_load_lds_dwordx4 v[130:131], off
	v_lshl_add_u64 v[130:131], v[248:249], 0, s[16:17]
	s_mov_b32 m0, s31
	s_nop 0
	global_load_lds_dwordx4 v[130:131], off
	s_waitcnt vmcnt(8)
	s_waitcnt lgkmcnt(0)
	s_barrier
	s_waitcnt lgkmcnt(0)
	v_mfma_f32_16x16x32_bf16 v[92:95], v[136:139], v[198:201], v[92:95]
	v_mfma_f32_16x16x32_bf16 v[88:91], v[144:147], v[198:201], v[88:91]
	v_mfma_f32_16x16x32_bf16 v[84:87], v[136:139], v[206:209], v[84:87]
	v_mfma_f32_16x16x32_bf16 v[80:83], v[144:147], v[206:209], v[80:83]
	v_mfma_f32_16x16x32_bf16 v[76:79], v[136:139], v[214:217], v[76:79]
	v_mfma_f32_16x16x32_bf16 v[72:75], v[144:147], v[214:217], v[72:75]
	v_mfma_f32_16x16x32_bf16 v[68:71], v[136:139], v[222:225], v[68:71]
	v_mfma_f32_16x16x32_bf16 v[64:67], v[144:147], v[222:225], v[64:67]
	v_mfma_f32_16x16x32_bf16 v[92:95], v[140:143], v[202:205], v[92:95]
	v_mfma_f32_16x16x32_bf16 v[88:91], v[148:151], v[202:205], v[88:91]
	v_mfma_f32_16x16x32_bf16 v[84:87], v[140:143], v[210:213], v[84:87]
	v_mfma_f32_16x16x32_bf16 v[80:83], v[148:151], v[210:213], v[80:83]
	v_mfma_f32_16x16x32_bf16 v[76:79], v[140:143], v[218:221], v[76:79]
	v_mfma_f32_16x16x32_bf16 v[72:75], v[148:151], v[218:221], v[72:75]
	v_mfma_f32_16x16x32_bf16 v[68:71], v[140:143], v[242:245], v[68:71]
	v_mfma_f32_16x16x32_bf16 v[64:67], v[148:151], v[242:245], v[64:67]
	v_mfma_f32_16x16x32_bf16 v[28:31], v[152:155], v[198:201], v[28:31]
	v_mfma_f32_16x16x32_bf16 v[24:27], v[190:193], v[198:201], v[24:27]
	v_mfma_f32_16x16x32_bf16 v[20:23], v[152:155], v[206:209], v[20:23]
	v_mfma_f32_16x16x32_bf16 v[16:19], v[190:193], v[206:209], v[16:19]
	v_mfma_f32_16x16x32_bf16 v[12:15], v[152:155], v[214:217], v[12:15]
	v_mfma_f32_16x16x32_bf16 v[8:11], v[190:193], v[214:217], v[8:11]
	v_mfma_f32_16x16x32_bf16 v[4:7], v[152:155], v[222:225], v[4:7]
	v_mfma_f32_16x16x32_bf16 v[0:3], v[190:193], v[222:225], v[0:3]
	v_mfma_f32_16x16x32_bf16 v[28:31], v[156:159], v[202:205], v[28:31]
	v_mfma_f32_16x16x32_bf16 v[24:27], v[194:197], v[202:205], v[24:27]
	v_mfma_f32_16x16x32_bf16 v[20:23], v[156:159], v[210:213], v[20:23]
	v_mfma_f32_16x16x32_bf16 v[16:19], v[194:197], v[210:213], v[16:19]
	v_mfma_f32_16x16x32_bf16 v[12:15], v[156:159], v[218:221], v[12:15]
	v_mfma_f32_16x16x32_bf16 v[8:11], v[194:197], v[218:221], v[8:11]
	v_mfma_f32_16x16x32_bf16 v[4:7], v[156:159], v[242:245], v[4:7]
	v_mfma_f32_16x16x32_bf16 v[0:3], v[194:197], v[242:245], v[0:3]
	s_barrier
	s_add_i32 s0, s78, 2
	s_add_u32 s62, s62, 0x100
	s_addc_u32 s63, s63, 0
	s_cmp_gt_u32 s78, 13
	s_cbranch_scc1 .LBB0_804
	s_mov_b32 s78, s0
	s_cmp_lt_i32 s78, 10
	s_cbranch_scc1 .LBB0_796
	s_branch .LBB0_795

; #define PG8_WAIT_V(n) asm volatile("s_waitcnt vmcnt(" #n ")" ::: "memory")
; #define PG8_BAR __builtin_amdgcn_s_barrier()
; template <class Epi, class Sched, bool ALIGN_EPI = false, bool SP2 = false, bool F16 = false>
; __device__ __forceinline__ void gemm_phase(PG8_LAS unsigned char* lds, const Gemm g, const Sched& S, const Epi& E) {
;     ...
;     PG8_WAIT_V(0);
;     if constexpr (!ALIGN_EPI) { if (wr == 0) PG8_BAR; }
;     PG8_BAR;
.LBB0_825:
	s_setprio 0
	s_waitcnt vmcnt(0)
	s_mov_b32 s13, s95
	s_barrier

; #define PG8_STAGE(bufoff, gbase, voff) do { _Pragma("unroll") for (int _i = 0; _i < 2; ++_i) \
;         __builtin_amdgcn_global_load_lds((const unsigned*)((const char*)(gbase) + (voff)[_i]), (PG8_LAS unsigned*)(lds + (bufoff) + ldsw + _i * 8192), 16, 0, 0); } while (0)
; #define PG8_BAR __builtin_amdgcn_s_barrier()
; template <class Epi, class Sched, bool ALIGN_EPI = false, bool SP2 = false, bool F16 = false>
; __device__ __forceinline__ void gemm_phase(PG8_LAS unsigned char* lds, const Gemm g, const Sched& S, const Epi& E) {
;     int tid_l = threadIdx.x; asm volatile("" : "+v"(tid_l));
;     const int tid = tid_l, wid = __builtin_amdgcn_readfirstlane(tid >> 6), lane = tid & 63, wr = wid >> 2, wc = wid & 3, fr = lane & 15, fq = lane >> 4;
;     const int K = g.K, nt = K / BK;
;     unsigned voffA[2], voffB[2];
; #pragma unroll
;     for (int i = 0; i < 2; ++i) { int R, C; stage_rc(tid * 16 + i * 8192, R, C); const int Rb = Epi::PERM ? ((R & ~31) + perm32(R & 31)) : R;
;         voffA[i] = (unsigned)(R * K + C) * 2u; voffB[i] = (unsigned)(Rb * K + C) * 2u; }
;     const size_t kstep = (size_t)(BK * 2);
;     const size_t hstep = (size_t)HALF * K * 2;
;     const size_t tstep = 2 * hstep;
;     const unsigned ldsw = (unsigned)wid * 1024u;
;     const int aoff = lds_byte(wr * 64 + fr, fq * 8), boff = lds_byte(wc * 32 + fr, fq * 8);
;     ...
;     Unit cur, nxt; int ui = 0;
;     if (!S.next(0, cur)) return;
;     f32x4 acc[2][2][4][2];
; #pragma unroll
;     for (int a = 0; a < 2; ++a)
; #pragma unroll
;         for (int b = 0; b < 2; ++b)
; #pragma unroll
;             for (int m = 0; m < 4; ++m)
; #pragma unroll
;                 for (int n = 0; n < 2; ++n) acc[a][b][m][n] = (f32x4){0.f, 0.f, 0.f, 0.f};
;     bf16x8 At[4][2], B0[2][2], B1[2][2];
;     const char* cA = (const char*)g.A + (size_t)cur.pm * tstep; const char* cB = (const char*)g.Bt + (size_t)cur.pn * tstep + (cur.pm >= g.mhalf ? g.bstride : (size_t)0);
;     S.a_ready(cur);
;     if constexpr (SP2) {
;         PG8_STAGE(PG8_SB(0, 0), cB, voffB); PG8_STAGE(PG8_SB(0, 1), cB + hstep, voffB); PG8_STAGE(PG8_SA(0, 0), cA, voffA); PG8_STAGE(PG8_SA(0, 1), cA + hstep, voffA);
;         if (wr == 1) PG8_BAR;
.LBB0_894:
	s_andn2_b64 vcc, exec, s[0:1]
	s_cbranch_vccnz .LBB0_977
	v_readlane_b32 s0, v254, 21
	v_mov_b32_e32 v4, v226
	v_readlane_b32 s1, v254, 22
	s_andn2_b64 vcc, exec, s[0:1]
	v_readfirstlane_b32 s4, v4
	s_cbranch_vccnz .LBB0_911
	s_lshr_b32 s98, s4, 6
	s_cmp_ge_u32 s98, 4
	s_cbranch_scc0 .Lgu_prio_done
	s_setprio 1
.Lgu_prio_done:
	v_lshlrev_b32_e32 v0, 4, v4
	s_waitcnt lgkmcnt(0)
	v_add_u32_e32 v1, 0x2000, v0
	v_ashrrev_i32_e32 v2, 31, v1
	v_lshrrev_b32_e32 v2, 22, v2
	v_add_u32_e32 v2, v1, v2
	v_ashrrev_i32_e32 v5, 10, v2
	v_mul_i32_i24_e32 v2, 0x400, v5
	v_sub_u32_e32 v1, v1, v2
	v_lshrrev_b32_e32 v2, 4, v1
	v_bitop3_b32 v1, v2, v1, 32 bitop3:0x6c
	v_ashrrev_i32_e32 v2, 31, v1
	v_readlane_b32 s0, v255, 14
	v_lshrrev_b32_e32 v2, 26, v2
	v_readlane_b32 s1, v255, 15
	v_add_u32_e32 v2, v1, v2
	v_lshlrev_b32_e32 v3, 3, v5
	s_mul_i32 s0, s0, 0x1600000
	v_readlane_b32 s1, v254, 17
	v_ashrrev_i32_e32 v6, 6, v2
	v_and_b32_e32 v3, -16, v3
	s_add_u32 s6, s1, s0
	v_readlane_b32 s0, v254, 18
	v_add_u32_e32 v3, v6, v3
	s_addc_u32 s7, s0, 0
	v_and_b32_e32 v7, 3, v6
	s_mov_b32 s0, 0x1fffe0
	v_lshrrev_b32_e32 v8, 2, v3
	v_lshlrev_b32_e32 v9, 1, v3
	v_and_b32_e32 v2, 0xc0, v2
	v_and_or_b32 v7, v3, s0, v7
	v_and_b32_e32 v8, 4, v8
	v_and_b32_e32 v9, 24, v9
	v_sub_u32_e32 v1, v1, v2
	v_or3_b32 v8, v7, v8, v9
	v_lshlrev_b32_e32 v7, 5, v5
	v_ashrrev_i16_sdwa v1, v228, sext(v1) dst_sel:DWORD dst_unused:UNUSED_PAD src0_sel:DWORD src1_sel:BYTE_0
	v_and_b32_e32 v9, 32, v7
	v_bfe_i32 v7, v1, 0, 16
	v_add_lshl_u32 v1, v9, v7, 1
	v_lshl_add_u32 v146, v8, 11, v1
	v_lshl_add_u32 v148, v3, 11, v1
	v_bfe_i32 v1, v4, 27, 1
	v_lshrrev_b32_e32 v1, 22, v1
	v_add_u32_e32 v1, v0, v1
	v_and_b32_e32 v1, 0xfffffc00, v1
	v_sub_u32_e32 v0, v0, v1
	v_lshrrev_b32_e32 v1, 4, v0
	v_ashrrev_i32_e32 v2, 31, v4
	v_bitop3_b32 v0, v1, v0, 32 bitop3:0x6c
	v_lshrrev_b32_e32 v2, 26, v2
	v_ashrrev_i32_e32 v1, 31, v0
	v_add_u32_e32 v2, v4, v2
	v_lshrrev_b32_e32 v1, 26, v1
	v_ashrrev_i32_e32 v9, 6, v2
	v_add_u32_e32 v1, v0, v1
	v_lshlrev_b32_e32 v2, 3, v9
	v_ashrrev_i32_e32 v8, 6, v1
	v_and_b32_e32 v2, -16, v2
	s_ashr_i32 s20, s4, 6
	v_add_u32_e32 v2, v8, v2
	v_and_b32_e32 v3, 3, v8
	s_ashr_i32 s5, s4, 8
	s_lshl_b32 s8, s20, 10
	v_and_or_b32 v3, v2, s0, v3
	v_lshrrev_b32_e32 v10, 2, v2
	v_lshlrev_b32_e32 v11, 1, v2
	v_and_b32_e32 v1, 0xc0, v1
	v_readlane_b32 s0, v254, 26
	v_and_b32_e32 v10, 4, v10
	v_and_b32_e32 v11, 24, v11
	v_sub_u32_e32 v0, v0, v1
	v_readlane_b32 s1, v254, 27
	s_add_u32 s0, s6, s0
	v_or3_b32 v3, v3, v10, v11
	v_lshlrev_b32_e32 v10, 5, v9
	v_ashrrev_i16_sdwa v0, v228, sext(v0) dst_sel:DWORD dst_unused:UNUSED_PAD src0_sel:DWORD src1_sel:BYTE_0
	s_addc_u32 s1, s7, s1
	v_readlane_b32 s9, v254, 31
	v_and_b32_e32 v11, 32, v10
	v_bfe_i32 v10, v0, 0, 16
	s_add_u32 s56, s0, s9
	v_add_lshl_u32 v0, v11, v10, 1
	s_addc_u32 s57, s1, 0
	s_add_i32 s9, s8, 0
	v_lshl_add_u32 v128, v3, 11, v0
	s_add_i32 m0, s9, 0x10000
	v_lshl_add_u32 v150, v2, 11, v0
	global_load_lds_dwordx4 v128, s[56:57]
	s_add_i32 m0, s9, 0x12000
	s_add_u32 s0, s56, 0x40000
	global_load_lds_dwordx4 v146, s[56:57]
	s_addc_u32 s1, s57, 0
	s_add_i32 m0, s9, 0x14000
	s_add_i32 s10, s9, 0x2000
	global_load_lds_dwordx4 v128, s[0:1]
	s_add_i32 m0, s9, 0x16000
	s_add_i32 s11, s9, 0x4000
	global_load_lds_dwordx4 v146, s[0:1]
	v_readlane_b32 s0, v254, 32
	s_mov_b32 m0, s9
	v_readlane_b32 s1, v254, 33
	s_add_i32 s13, s9, 0x6000
	v_mov_b32_e32 v147, v129
	s_cmp_eq_u32 s5, 1
	v_lshl_add_u64 v[0:1], s[56:57], 0, v[128:129]
	v_lshl_add_u64 v[2:3], s[56:57], 0, v[146:147]
	global_load_lds_dwordx4 v150, s[0:1]
	s_mov_b32 m0, s10
	s_nop 0
	global_load_lds_dwordx4 v148, s[0:1]
	v_readlane_b32 s0, v254, 34
	s_mov_b32 m0, s11
	v_readlane_b32 s1, v254, 35
	s_nop 4
	global_load_lds_dwordx4 v150, s[0:1]
	s_mov_b32 m0, s13
	s_nop 0
	global_load_lds_dwordx4 v148, s[0:1]
	s_cselect_b64 s[0:1], -1, 0
	s_cmp_lg_u32 s5, 1
	s_cbranch_scc1 .LBB0_898
	s_barrier

; #define PG8_STAGE(bufoff, gbase, voff) do { _Pragma("unroll") for (int _i = 0; _i < 2; ++_i) \
;         __builtin_amdgcn_global_load_lds((const unsigned*)((const char*)(gbase) + (voff)[_i]), (PG8_LAS unsigned*)(lds + (bufoff) + ldsw + _i * 8192), 16, 0, 0); } while (0)
; #define PG8_WAIT_V(n) asm volatile("s_waitcnt vmcnt(" #n ")" ::: "memory")
; template <class Epi, class Sched, bool ALIGN_EPI = false, bool SP2 = false, bool F16 = false>
; __device__ __forceinline__ void gemm_phase(PG8_LAS unsigned char* lds, const Gemm g, const Sched& S, const Epi& E) {
;     ...
;         const bool has_next = S.next(ui + 1, nxt);
;         const char* nA = has_next ? (const char*)g.A + (size_t)nxt.pm * tstep : cA; const char* nB = has_next ? (const char*)g.Bt + (size_t)nxt.pn * tstep + (nxt.pm >= g.mhalf ? g.bstride : (size_t)0) : cB;
;         for (int t = 0; t < nt; t += 2) {
;             if constexpr (Epi::KHOOK) { if (t == 4 || t == 10) E.khook(acc, cur, t, wr, fr); }
;             const bool last = (t == nt - 2);
;             const char* a1 = cA + (size_t)(t + 1) * kstep;
;             const char* a2 = last ? nA : cA + (size_t)(t + 2) * kstep; const char* b2 = last ? nB : cB + (size_t)(t + 2) * kstep;
;             const char* a3 = a2 + kstep; const char* b3 = b2 + kstep;
;             if (last && has_next) S.a_ready(nxt);
;             if constexpr (SP2) {
;             PG8_LDB(B0, 0, 0); PG8_LDB(B1, 0, 1); PG8_SCHED; PG8_LDA(At, 0, 0); PG8_STAGE(PG8_SA(1, 1), a1 + hstep, voffA);
;             PG8_WAIT_V(8); PG8_WAIT_L(0); PG8_BAR; PG8_MMA(0, 0, At, B0); PG8_MMA(0, 1, At, B1); PG8_BAR; PG8_SCHED;
;             PG8_LDA(At, 0, 1); PG8_STAGE(PG8_SB(0, 0), b2, voffB); PG8_STAGE(PG8_SB(0, 1), b2 + hstep, voffB); PG8_STAGE(PG8_SA(0, 0), a2, voffA);
;             PG8_WAIT_V(8); PG8_WAIT_L(0); PG8_BAR; PG8_MMA(1, 0, At, B0); PG8_MMA(1, 1, At, B1); PG8_BAR; PG8_SCHED;
;             PG8_LDB(B0, 1, 0); PG8_LDB(B1, 1, 1); PG8_SCHED; PG8_LDA(At, 1, 0); PG8_STAGE(PG8_SA(0, 1), a2 + hstep, voffA);
;             PG8_WAIT_V(8); PG8_WAIT_L(0); PG8_BAR; PG8_MMA(0, 0, At, B0); PG8_MMA(0, 1, At, B1); PG8_BAR; PG8_SCHED;
;             PG8_LDA(At, 1, 1); PG8_STAGE(PG8_SB(1, 0), b3, voffB); PG8_STAGE(PG8_SB(1, 1), b3 + hstep, voffB); PG8_STAGE(PG8_SA(1, 0), a3, voffA);
;             PG8_WAIT_V(8); PG8_WAIT_L(0); PG8_BAR; PG8_MMA(1, 0, At, B0); PG8_MMA(1, 1, At, B1); PG8_BAR; PG8_SCHED;
.LBB0_903:
	s_ashr_i32 s49, s48, 31
	s_lshl_b64 s[4:5], s[48:49], 19
	s_add_u32 s50, s96, s4
	s_addc_u32 s51, s97, s5
	s_and_b64 s[4:5], s[40:41], exec
	s_cselect_b32 s4, s51, s55
	s_cselect_b32 s5, s50, s54
	s_ashr_i32 s47, s46, 31
	s_lshl_b64 s[52:53], s[46:47], 19
	s_add_u32 s37, s6, s52
	s_addc_u32 s47, s7, s53
	s_cmp_gt_i32 s48, 63
	s_cselect_b32 s49, 0xb00000, 0
	s_add_u32 s52, s37, s49
	s_addc_u32 s53, s47, 0
	s_and_b64 s[58:59], s[40:41], exec
	s_cselect_b32 s37, s53, s57
	s_cselect_b32 s47, s52, s56
	s_add_u32 s54, s54, 0x40080
	s_addc_u32 s55, s55, 0
	s_add_u32 s49, s56, 0x100
	s_addc_u32 s60, s57, 0
	s_mov_b32 s61, -2
	v_add_u32_e32 v172, 0x10000, v163
	s_add_u32 s56, s54, 0xfffc0080
	s_addc_u32 s57, s55, -1
	s_add_i32 s62, 0, 0x10000
	s_cmp_eq_u32 s61, 12
	s_cselect_b32 s59, s4, s57
	s_cselect_b32 s58, s5, s56
	s_cselect_b32 s57, s37, s60
	s_cselect_b32 s56, s47, s49
	s_add_i32 s64, 0, 0x14000
	ds_read_b128 v[32:35], v172
	ds_read_b128 v[36:39], v172 offset:1024
	ds_read_b128 v[40:43], v172 offset:2048
	ds_read_b128 v[44:47], v172 offset:3072
	ds_read_b128 v[156:159], v172 offset:16384
	ds_read_b128 v[168:171], v172 offset:17408
	ds_read_b128 v[186:189], v172 offset:18432
	ds_read_b128 v[190:193], v172 offset:19456
	s_add_i32 m0, s9, 0xc000
	ds_read_b128 v[194:197], v165
	ds_read_b128 v[198:201], v165 offset:1024
	ds_read_b128 v[202:205], v165 offset:2048
	ds_read_b128 v[206:209], v165 offset:3072
	ds_read_b128 v[210:213], v165 offset:4096
	ds_read_b128 v[214:217], v165 offset:5120
	ds_read_b128 v[218:221], v165 offset:6144
	ds_read_b128 v[222:225], v165 offset:7168
	global_load_lds_dwordx4 v152, s[54:55]
	s_add_i32 m0, s9, 0xe000
	s_nop 0
	global_load_lds_dwordx4 v154, s[54:55]
	s_waitcnt vmcnt(16)
	s_waitcnt lgkmcnt(0)
	s_barrier
	s_waitcnt lgkmcnt(0)
	v_mfma_f32_16x16x32_f16 v[142:145], v[32:35], v[194:197], 0
	v_mfma_f32_16x16x32_f16 v[138:141], v[40:43], v[194:197], 0
	v_mfma_f32_16x16x32_f16 v[124:127], v[32:35], v[202:205], 0
	v_mfma_f32_16x16x32_f16 v[120:123], v[40:43], v[202:205], 0
	v_mfma_f32_16x16x32_f16 v[108:111], v[32:35], v[210:213], 0
	v_mfma_f32_16x16x32_f16 v[104:107], v[40:43], v[210:213], 0
	v_mfma_f32_16x16x32_f16 v[92:95], v[32:35], v[218:221], 0
	v_mfma_f32_16x16x32_f16 v[88:91], v[40:43], v[218:221], 0
	v_mfma_f32_16x16x32_f16 v[142:145], v[36:39], v[198:201], v[142:145]
	v_mfma_f32_16x16x32_f16 v[138:141], v[44:47], v[198:201], v[138:141]
	v_mfma_f32_16x16x32_f16 v[124:127], v[36:39], v[206:209], v[124:127]
	v_mfma_f32_16x16x32_f16 v[120:123], v[44:47], v[206:209], v[120:123]
	v_mfma_f32_16x16x32_f16 v[108:111], v[36:39], v[214:217], v[108:111]
	v_mfma_f32_16x16x32_f16 v[104:107], v[44:47], v[214:217], v[104:107]
	v_mfma_f32_16x16x32_f16 v[92:95], v[36:39], v[222:225], v[92:95]
	v_mfma_f32_16x16x32_f16 v[88:91], v[44:47], v[222:225], v[88:91]
	v_mfma_f32_16x16x32_f16 v[134:137], v[156:159], v[194:197], 0
	v_mfma_f32_16x16x32_f16 v[130:133], v[186:189], v[194:197], 0
	v_mfma_f32_16x16x32_f16 v[116:119], v[156:159], v[202:205], 0
	v_mfma_f32_16x16x32_f16 v[112:115], v[186:189], v[202:205], 0
	v_mfma_f32_16x16x32_f16 v[100:103], v[156:159], v[210:213], 0
	v_mfma_f32_16x16x32_f16 v[96:99], v[186:189], v[210:213], 0
	v_mfma_f32_16x16x32_f16 v[84:87], v[156:159], v[218:221], 0
	v_mfma_f32_16x16x32_f16 v[80:83], v[186:189], v[218:221], 0
	v_mfma_f32_16x16x32_f16 v[134:137], v[168:171], v[198:201], v[134:137]
	v_mfma_f32_16x16x32_f16 v[130:133], v[190:193], v[198:201], v[130:133]
	v_mfma_f32_16x16x32_f16 v[116:119], v[168:171], v[206:209], v[116:119]
	v_mfma_f32_16x16x32_f16 v[112:115], v[190:193], v[206:209], v[112:115]
	v_mfma_f32_16x16x32_f16 v[100:103], v[168:171], v[214:217], v[100:103]
	v_mfma_f32_16x16x32_f16 v[96:99], v[190:193], v[214:217], v[96:99]
	v_mfma_f32_16x16x32_f16 v[84:87], v[168:171], v[222:225], v[84:87]
	v_mfma_f32_16x16x32_f16 v[80:83], v[190:193], v[222:225], v[80:83]
	s_barrier
	s_add_u32 s98, s56, s16
	s_addc_u32 s99, s57, s17
	s_add_u32 s100, s58, s16
	s_addc_u32 s101, s59, s17
	s_add_i32 s62, s62, s8
	s_mov_b32 m0, s62
	ds_read_b128 v[194:197], v165 offset:16384
	ds_read_b128 v[198:201], v165 offset:17408
	ds_read_b128 v[202:205], v165 offset:18432
	ds_read_b128 v[206:209], v165 offset:19456
	ds_read_b128 v[210:213], v165 offset:20480
	ds_read_b128 v[214:217], v165 offset:21504
	ds_read_b128 v[218:221], v165 offset:22528
	ds_read_b128 v[222:225], v165 offset:23552
	global_load_lds_dwordx4 v128, s[56:57]
	s_add_i32 m0, s62, 0x2000
	s_add_u32 s62, s56, 0x40000
	s_addc_u32 s63, s57, 0
	s_add_i32 s64, s64, s8
	global_load_lds_dwordx4 v146, s[56:57]
	s_mov_b32 m0, s64
	s_nop 0
	global_load_lds_dwordx4 v128, s[62:63]
	s_add_i32 m0, s64, 0x2000
	s_nop 0
	global_load_lds_dwordx4 v146, s[62:63]
	s_mov_b32 m0, s9
	s_nop 0
	global_load_lds_dwordx4 v150, s[58:59]
	s_mov_b32 m0, s10
	s_nop 0
	global_load_lds_dwordx4 v148, s[58:59]
	s_waitcnt vmcnt(16)
	s_waitcnt lgkmcnt(0)
	s_barrier
; #define PG8_STAGE(bufoff, gbase, voff) do { _Pragma("unroll") for (int _i = 0; _i < 2; ++_i) \
;         __builtin_amdgcn_global_load_lds((const unsigned*)((const char*)(gbase) + (voff)[_i]), (PG8_LAS unsigned*)(lds + (bufoff) + ldsw + _i * 8192), 16, 0, 0); } while (0)
; #define PG8_LDA(dst, b, h) do { _Pragma("unroll") for (int m = 0; m < 4; ++m) _Pragma("unroll") for (int k = 0; k < 2; ++k) dst[m][k] = *(const PG8_LAS bf16x8*)(lds + PG8_SA(b, h) + aoff + m * 2048 + k * 1024); } while (0)
; #define PG8_LDB(dst, b, h) do { _Pragma("unroll") for (int n = 0; n < 2; ++n) _Pragma("unroll") for (int k = 0; k < 2; ++k) dst[n][k] = *(const PG8_LAS bf16x8*)(lds + PG8_SB(b, h) + boff + n * 2048 + k * 1024); } while (0)
; #define PG8_MMA(ai, bj, At, Bt) do { __builtin_amdgcn_s_setprio(1); _Pragma("unroll") for (int m = 0; m < 4; ++m) _Pragma("unroll") for (int n = 0; n < 2; ++n) _Pragma("unroll") for (int k = 0; k < 2; ++k) \
;         acc[ai][bj][m][n] = mma16<F16>(Bt[n][k], At[m][k], acc[ai][bj][m][n]); __builtin_amdgcn_s_setprio(0); } while (0)
; #define PG8_WAIT_V(n) asm volatile("s_waitcnt vmcnt(" #n ")" ::: "memory")
; template <class Epi, class Sched, bool ALIGN_EPI = false, bool SP2 = false, bool F16 = false>
; __device__ __forceinline__ void gemm_phase(PG8_LAS unsigned char* lds, const Gemm g, const Sched& S, const Epi& E) {
;     ...
;             PG8_LDB(B0, 0, 0); PG8_LDB(B1, 0, 1); PG8_SCHED; PG8_LDA(At, 0, 0); PG8_STAGE(PG8_SA(1, 1), a1 + hstep, voffA);
;             PG8_WAIT_V(8); PG8_WAIT_L(0); PG8_BAR; PG8_MMA(0, 0, At, B0); PG8_MMA(0, 1, At, B1); PG8_BAR; PG8_SCHED;
;             PG8_LDA(At, 0, 1); PG8_STAGE(PG8_SB(0, 0), b2, voffB); PG8_STAGE(PG8_SB(0, 1), b2 + hstep, voffB); PG8_STAGE(PG8_SA(0, 0), a2, voffA);
;             PG8_WAIT_V(8); PG8_WAIT_L(0); PG8_BAR; PG8_MMA(1, 0, At, B0); PG8_MMA(1, 1, At, B1); PG8_BAR; PG8_SCHED;
;             PG8_LDB(B0, 1, 0); PG8_LDB(B1, 1, 1); PG8_SCHED; PG8_LDA(At, 1, 0); PG8_STAGE(PG8_SA(0, 1), a2 + hstep, voffA);
;             PG8_WAIT_V(8); PG8_WAIT_L(0); PG8_BAR; PG8_MMA(0, 0, At, B0); PG8_MMA(0, 1, At, B1); PG8_BAR; PG8_SCHED;
;             PG8_LDA(At, 1, 1); PG8_STAGE(PG8_SB(1, 0), b3, voffB); PG8_STAGE(PG8_SB(1, 1), b3 + hstep, voffB); PG8_STAGE(PG8_SA(1, 0), a3, voffA);
;             PG8_WAIT_V(8); PG8_WAIT_L(0); PG8_BAR; PG8_MMA(1, 0, At, B0); PG8_MMA(1, 1, At, B1); PG8_BAR; PG8_SCHED;
	s_waitcnt lgkmcnt(0)
	v_mfma_f32_16x16x32_f16 v[76:79], v[32:35], v[194:197], 0
	v_mfma_f32_16x16x32_f16 v[72:75], v[40:43], v[194:197], 0
	v_mfma_f32_16x16x32_f16 v[60:63], v[32:35], v[202:205], 0
	v_mfma_f32_16x16x32_f16 v[56:59], v[40:43], v[202:205], 0
	v_mfma_f32_16x16x32_f16 v[28:31], v[32:35], v[210:213], 0
	v_mfma_f32_16x16x32_f16 v[24:27], v[40:43], v[210:213], 0
	v_mfma_f32_16x16x32_f16 v[12:15], v[32:35], v[218:221], 0
	v_mfma_f32_16x16x32_f16 v[8:11], v[40:43], v[218:221], 0
	v_mfma_f32_16x16x32_f16 v[76:79], v[36:39], v[198:201], v[76:79]
	v_mfma_f32_16x16x32_f16 v[72:75], v[44:47], v[198:201], v[72:75]
	v_mfma_f32_16x16x32_f16 v[60:63], v[36:39], v[206:209], v[60:63]
	v_mfma_f32_16x16x32_f16 v[56:59], v[44:47], v[206:209], v[56:59]
	v_mfma_f32_16x16x32_f16 v[28:31], v[36:39], v[214:217], v[28:31]
	v_mfma_f32_16x16x32_f16 v[24:27], v[44:47], v[214:217], v[24:27]
	v_mfma_f32_16x16x32_f16 v[12:15], v[36:39], v[222:225], v[12:15]
	v_mfma_f32_16x16x32_f16 v[8:11], v[44:47], v[222:225], v[8:11]
	v_mfma_f32_16x16x32_f16 v[20:23], v[156:159], v[210:213], 0
	v_mfma_f32_16x16x32_f16 v[16:19], v[186:189], v[210:213], 0
	v_mfma_f32_16x16x32_f16 v[4:7], v[156:159], v[218:221], 0
	v_mfma_f32_16x16x32_f16 v[0:3], v[186:189], v[218:221], 0
	v_mfma_f32_16x16x32_f16 v[32:35], v[156:159], v[194:197], 0
	v_mfma_f32_16x16x32_f16 v[36:39], v[186:189], v[194:197], 0
	v_mfma_f32_16x16x32_f16 v[40:43], v[156:159], v[202:205], 0
	v_mfma_f32_16x16x32_f16 v[44:47], v[186:189], v[202:205], 0
	v_mfma_f32_16x16x32_f16 v[20:23], v[168:171], v[214:217], v[20:23]
	v_mfma_f32_16x16x32_f16 v[16:19], v[190:193], v[214:217], v[16:19]
	v_mfma_f32_16x16x32_f16 v[4:7], v[168:171], v[222:225], v[4:7]
	v_mfma_f32_16x16x32_f16 v[0:3], v[190:193], v[222:225], v[0:3]
	v_mfma_f32_16x16x32_f16 v[32:35], v[168:171], v[198:201], v[32:35]
	v_mfma_f32_16x16x32_f16 v[36:39], v[190:193], v[198:201], v[36:39]
	v_mfma_f32_16x16x32_f16 v[40:43], v[168:171], v[206:209], v[40:43]
	v_mfma_f32_16x16x32_f16 v[44:47], v[190:193], v[206:209], v[44:47]
	s_barrier
	s_add_i32 s62, 0, 0x18000
	s_add_i32 s63, 0, 0x1c000
	ds_read_b128 v[48:51], v172 offset:32768
	ds_read_b128 v[52:55], v172 offset:33792
	ds_read_b128 v[64:67], v172 offset:34816
	ds_read_b128 v[68:71], v172 offset:35840
	ds_read_b128 v[156:159], v172 offset:49152
	ds_read_b128 v[168:171], v172 offset:50176
	ds_read_b128 v[186:189], v172 offset:51200
	ds_read_b128 v[190:193], v172 offset:52224
	s_add_u32 s58, s58, 0x40000
	s_addc_u32 s59, s59, 0
	s_mov_b32 m0, s11
	ds_read_b128 v[194:197], v165 offset:32768
	ds_read_b128 v[198:201], v165 offset:33792
	ds_read_b128 v[202:205], v165 offset:34816
	ds_read_b128 v[206:209], v165 offset:35840
	ds_read_b128 v[210:213], v165 offset:36864
	ds_read_b128 v[214:217], v165 offset:37888
	ds_read_b128 v[218:221], v165 offset:38912
	ds_read_b128 v[222:225], v165 offset:39936
	global_load_lds_dwordx4 v150, s[58:59]
	s_mov_b32 m0, s13
	s_nop 0
	global_load_lds_dwordx4 v148, s[58:59]
	s_waitcnt vmcnt(8)
	s_waitcnt lgkmcnt(0)
	s_barrier
	s_waitcnt lgkmcnt(0)
	v_mfma_f32_16x16x32_f16 v[142:145], v[48:51], v[194:197], v[142:145]
	v_mfma_f32_16x16x32_f16 v[138:141], v[64:67], v[194:197], v[138:141]
	v_mfma_f32_16x16x32_f16 v[124:127], v[48:51], v[202:205], v[124:127]
	v_mfma_f32_16x16x32_f16 v[120:123], v[64:67], v[202:205], v[120:123]
	v_mfma_f32_16x16x32_f16 v[108:111], v[48:51], v[210:213], v[108:111]
	v_mfma_f32_16x16x32_f16 v[104:107], v[64:67], v[210:213], v[104:107]
	v_mfma_f32_16x16x32_f16 v[92:95], v[48:51], v[218:221], v[92:95]
	v_mfma_f32_16x16x32_f16 v[88:91], v[64:67], v[218:221], v[88:91]
	v_mfma_f32_16x16x32_f16 v[142:145], v[52:55], v[198:201], v[142:145]
	v_mfma_f32_16x16x32_f16 v[138:141], v[68:71], v[198:201], v[138:141]
	v_mfma_f32_16x16x32_f16 v[124:127], v[52:55], v[206:209], v[124:127]
	v_mfma_f32_16x16x32_f16 v[120:123], v[68:71], v[206:209], v[120:123]
	v_mfma_f32_16x16x32_f16 v[108:111], v[52:55], v[214:217], v[108:111]
	v_mfma_f32_16x16x32_f16 v[104:107], v[68:71], v[214:217], v[104:107]
	v_mfma_f32_16x16x32_f16 v[92:95], v[52:55], v[222:225], v[92:95]
	v_mfma_f32_16x16x32_f16 v[88:91], v[68:71], v[222:225], v[88:91]
	v_mfma_f32_16x16x32_f16 v[134:137], v[156:159], v[194:197], v[134:137]
	v_mfma_f32_16x16x32_f16 v[130:133], v[186:189], v[194:197], v[130:133]
	v_mfma_f32_16x16x32_f16 v[116:119], v[156:159], v[202:205], v[116:119]
	v_mfma_f32_16x16x32_f16 v[112:115], v[186:189], v[202:205], v[112:115]
	v_mfma_f32_16x16x32_f16 v[100:103], v[156:159], v[210:213], v[100:103]
	v_mfma_f32_16x16x32_f16 v[96:99], v[186:189], v[210:213], v[96:99]
	v_mfma_f32_16x16x32_f16 v[84:87], v[156:159], v[218:221], v[84:87]
	v_mfma_f32_16x16x32_f16 v[80:83], v[186:189], v[218:221], v[80:83]
	v_mfma_f32_16x16x32_f16 v[134:137], v[168:171], v[198:201], v[134:137]
	v_mfma_f32_16x16x32_f16 v[130:133], v[190:193], v[198:201], v[130:133]
	v_mfma_f32_16x16x32_f16 v[116:119], v[168:171], v[206:209], v[116:119]
	v_mfma_f32_16x16x32_f16 v[112:115], v[190:193], v[206:209], v[112:115]
	v_mfma_f32_16x16x32_f16 v[100:103], v[168:171], v[214:217], v[100:103]
	v_mfma_f32_16x16x32_f16 v[96:99], v[190:193], v[214:217], v[96:99]
	v_mfma_f32_16x16x32_f16 v[84:87], v[168:171], v[222:225], v[84:87]
	v_mfma_f32_16x16x32_f16 v[80:83], v[190:193], v[222:225], v[80:83]
	s_barrier
; #define PG8_STAGE(bufoff, gbase, voff) do { _Pragma("unroll") for (int _i = 0; _i < 2; ++_i) \
;         __builtin_amdgcn_global_load_lds((const unsigned*)((const char*)(gbase) + (voff)[_i]), (PG8_LAS unsigned*)(lds + (bufoff) + ldsw + _i * 8192), 16, 0, 0); } while (0)
; #define PG8_LDA(dst, b, h) do { _Pragma("unroll") for (int m = 0; m < 4; ++m) _Pragma("unroll") for (int k = 0; k < 2; ++k) dst[m][k] = *(const PG8_LAS bf16x8*)(lds + PG8_SA(b, h) + aoff + m * 2048 + k * 1024); } while (0)
; #define PG8_LDB(dst, b, h) do { _Pragma("unroll") for (int n = 0; n < 2; ++n) _Pragma("unroll") for (int k = 0; k < 2; ++k) dst[n][k] = *(const PG8_LAS bf16x8*)(lds + PG8_SB(b, h) + boff + n * 2048 + k * 1024); } while (0)
; #define PG8_MMA(ai, bj, At, Bt) do { __builtin_amdgcn_s_setprio(1); _Pragma("unroll") for (int m = 0; m < 4; ++m) _Pragma("unroll") for (int n = 0; n < 2; ++n) _Pragma("unroll") for (int k = 0; k < 2; ++k) \
;         acc[ai][bj][m][n] = mma16<F16>(Bt[n][k], At[m][k], acc[ai][bj][m][n]); __builtin_amdgcn_s_setprio(0); } while (0)
; #define PG8_WAIT_V(n) asm volatile("s_waitcnt vmcnt(" #n ")" ::: "memory")
; template <class Epi, class Sched, bool ALIGN_EPI = false, bool SP2 = false, bool F16 = false>
; __device__ __forceinline__ void gemm_phase(PG8_LAS unsigned char* lds, const Gemm g, const Sched& S, const Epi& E) {
;     ...
;             PG8_LDB(B0, 0, 0); PG8_LDB(B1, 0, 1); PG8_SCHED; PG8_LDA(At, 0, 0); PG8_STAGE(PG8_SA(1, 1), a1 + hstep, voffA);
;             PG8_WAIT_V(8); PG8_WAIT_L(0); PG8_BAR; PG8_MMA(0, 0, At, B0); PG8_MMA(0, 1, At, B1); PG8_BAR; PG8_SCHED;
;             PG8_LDA(At, 0, 1); PG8_STAGE(PG8_SB(0, 0), b2, voffB); PG8_STAGE(PG8_SB(0, 1), b2 + hstep, voffB); PG8_STAGE(PG8_SA(0, 0), a2, voffA);
;             PG8_WAIT_V(8); PG8_WAIT_L(0); PG8_BAR; PG8_MMA(1, 0, At, B0); PG8_MMA(1, 1, At, B1); PG8_BAR; PG8_SCHED;
;             PG8_LDB(B0, 1, 0); PG8_LDB(B1, 1, 1); PG8_SCHED; PG8_LDA(At, 1, 0); PG8_STAGE(PG8_SA(0, 1), a2 + hstep, voffA);
;             PG8_WAIT_V(8); PG8_WAIT_L(0); PG8_BAR; PG8_MMA(0, 0, At, B0); PG8_MMA(0, 1, At, B1); PG8_BAR; PG8_SCHED;
;             PG8_LDA(At, 1, 1); PG8_STAGE(PG8_SB(1, 0), b3, voffB); PG8_STAGE(PG8_SB(1, 1), b3 + hstep, voffB); PG8_STAGE(PG8_SA(1, 0), a3, voffA);
;             PG8_WAIT_V(8); PG8_WAIT_L(0); PG8_BAR; PG8_MMA(1, 0, At, B0); PG8_MMA(1, 1, At, B1); PG8_BAR; PG8_SCHED;
	s_add_i32 s58, s62, s8
	s_mov_b32 m0, s58
	ds_read_b128 v[194:197], v165 offset:49152
	ds_read_b128 v[198:201], v165 offset:50176
	ds_read_b128 v[202:205], v165 offset:51200
	ds_read_b128 v[206:209], v165 offset:52224
	ds_read_b128 v[210:213], v165 offset:53248
	ds_read_b128 v[214:217], v165 offset:54272
	ds_read_b128 v[218:221], v165 offset:55296
	ds_read_b128 v[222:225], v165 offset:56320
	global_load_lds_dwordx4 v128, s[98:99]
	s_add_i32 m0, s58, 0x2000
	s_add_u32 s56, s56, 0x40080
	s_addc_u32 s57, s57, 0
	s_add_i32 s58, s63, s8
	global_load_lds_dwordx4 v146, s[98:99]
	s_mov_b32 m0, s58
	s_nop 0
	global_load_lds_dwordx4 v128, s[56:57]
	s_add_i32 m0, s58, 0x2000
	s_nop 0
	global_load_lds_dwordx4 v146, s[56:57]
	s_mov_b32 m0, s20
	s_nop 0
	global_load_lds_dwordx4 v150, s[100:101]
	s_mov_b32 m0, s21
	s_nop 0
	global_load_lds_dwordx4 v148, s[100:101]
	s_waitcnt vmcnt(8)
	s_waitcnt lgkmcnt(0)
	s_barrier
	s_waitcnt lgkmcnt(0)
	v_mfma_f32_16x16x32_f16 v[76:79], v[48:51], v[194:197], v[76:79]
	v_mfma_f32_16x16x32_f16 v[72:75], v[64:67], v[194:197], v[72:75]
	v_mfma_f32_16x16x32_f16 v[60:63], v[48:51], v[202:205], v[60:63]
	v_mfma_f32_16x16x32_f16 v[56:59], v[64:67], v[202:205], v[56:59]
	v_mfma_f32_16x16x32_f16 v[28:31], v[48:51], v[210:213], v[28:31]
	v_mfma_f32_16x16x32_f16 v[24:27], v[64:67], v[210:213], v[24:27]
	v_mfma_f32_16x16x32_f16 v[12:15], v[48:51], v[218:221], v[12:15]
	v_mfma_f32_16x16x32_f16 v[8:11], v[64:67], v[218:221], v[8:11]
	v_mfma_f32_16x16x32_f16 v[76:79], v[52:55], v[198:201], v[76:79]
	v_mfma_f32_16x16x32_f16 v[72:75], v[68:71], v[198:201], v[72:75]
	v_mfma_f32_16x16x32_f16 v[60:63], v[52:55], v[206:209], v[60:63]
	v_mfma_f32_16x16x32_f16 v[56:59], v[68:71], v[206:209], v[56:59]
	v_mfma_f32_16x16x32_f16 v[28:31], v[52:55], v[214:217], v[28:31]
	v_mfma_f32_16x16x32_f16 v[24:27], v[68:71], v[214:217], v[24:27]
	v_mfma_f32_16x16x32_f16 v[12:15], v[52:55], v[222:225], v[12:15]
	v_mfma_f32_16x16x32_f16 v[8:11], v[68:71], v[222:225], v[8:11]
	v_mfma_f32_16x16x32_f16 v[32:35], v[156:159], v[194:197], v[32:35]
	v_mfma_f32_16x16x32_f16 v[68:71], v[168:171], v[198:201], v[32:35]
	v_mfma_f32_16x16x32_f16 v[32:35], v[186:189], v[194:197], v[36:39]
	v_mfma_f32_16x16x32_f16 v[64:67], v[190:193], v[198:201], v[32:35]
	v_mfma_f32_16x16x32_f16 v[32:35], v[156:159], v[202:205], v[40:43]
	v_mfma_f32_16x16x32_f16 v[52:55], v[168:171], v[206:209], v[32:35]
	v_mfma_f32_16x16x32_f16 v[32:35], v[186:189], v[202:205], v[44:47]
	v_mfma_f32_16x16x32_f16 v[20:23], v[156:159], v[210:213], v[20:23]
	v_mfma_f32_16x16x32_f16 v[16:19], v[186:189], v[210:213], v[16:19]
	v_mfma_f32_16x16x32_f16 v[4:7], v[156:159], v[218:221], v[4:7]
	v_mfma_f32_16x16x32_f16 v[0:3], v[186:189], v[218:221], v[0:3]
	v_mfma_f32_16x16x32_f16 v[48:51], v[190:193], v[206:209], v[32:35]
	v_mfma_f32_16x16x32_f16 v[20:23], v[168:171], v[214:217], v[20:23]
	v_mfma_f32_16x16x32_f16 v[16:19], v[190:193], v[214:217], v[16:19]
	v_mfma_f32_16x16x32_f16 v[4:7], v[168:171], v[222:225], v[4:7]
	v_mfma_f32_16x16x32_f16 v[0:3], v[190:193], v[222:225], v[0:3]
	s_barrier
	s_add_i32 s61, s61, 2
	s_add_u32 s54, s54, 0x100
	s_addc_u32 s55, s55, 0
	s_add_u32 s49, s49, 0x100
	s_addc_u32 s60, s60, 0
	s_cmp_gt_u32 s61, 13

; #define PG8_STAGE(bufoff, gbase, voff) do { _Pragma("unroll") for (int _i = 0; _i < 2; ++_i) \
;         __builtin_amdgcn_global_load_lds((const unsigned*)((const char*)(gbase) + (voff)[_i]), (PG8_LAS unsigned*)(lds + (bufoff) + ldsw + _i * 8192), 16, 0, 0); } while (0)
; #define PG8_LDA(dst, b, h) do { _Pragma("unroll") for (int m = 0; m < 4; ++m) _Pragma("unroll") for (int k = 0; k < 2; ++k) dst[m][k] = *(const PG8_LAS bf16x8*)(lds + PG8_SA(b, h) + aoff + m * 2048 + k * 1024); } while (0)
; #define PG8_LDB(dst, b, h) do { _Pragma("unroll") for (int n = 0; n < 2; ++n) _Pragma("unroll") for (int k = 0; k < 2; ++k) dst[n][k] = *(const PG8_LAS bf16x8*)(lds + PG8_SB(b, h) + boff + n * 2048 + k * 1024); } while (0)
; #define PG8_MMA(ai, bj, At, Bt) do { __builtin_amdgcn_s_setprio(1); _Pragma("unroll") for (int m = 0; m < 4; ++m) _Pragma("unroll") for (int n = 0; n < 2; ++n) _Pragma("unroll") for (int k = 0; k < 2; ++k) \
;         acc[ai][bj][m][n] = mma16<F16>(Bt[n][k], At[m][k], acc[ai][bj][m][n]); __builtin_amdgcn_s_setprio(0); } while (0)
; #define PG8_WAIT_V(n) asm volatile("s_waitcnt vmcnt(" #n ")" ::: "memory")
; template <class Epi, class Sched, bool ALIGN_EPI = false, bool SP2 = false, bool F16 = false>
; __device__ __forceinline__ void gemm_phase(PG8_LAS unsigned char* lds, const Gemm g, const Sched& S, const Epi& E) {
;     ...
;             PG8_LDB(B0, 0, 0); PG8_LDB(B1, 0, 1); PG8_SCHED; PG8_LDA(At, 0, 0); PG8_STAGE(PG8_SA(1, 1), a1 + hstep, voffA);
;             PG8_WAIT_V(8); PG8_WAIT_L(0); PG8_BAR; PG8_MMA(0, 0, At, B0); PG8_MMA(0, 1, At, B1); PG8_BAR; PG8_SCHED;
;             PG8_LDA(At, 0, 1); PG8_STAGE(PG8_SB(0, 0), b2, voffB); PG8_STAGE(PG8_SB(0, 1), b2 + hstep, voffB); PG8_STAGE(PG8_SA(0, 0), a2, voffA);
;             PG8_WAIT_V(8); PG8_WAIT_L(0); PG8_BAR; PG8_MMA(1, 0, At, B0); PG8_MMA(1, 1, At, B1); PG8_BAR; PG8_SCHED;
;             PG8_LDB(B0, 1, 0); PG8_LDB(B1, 1, 1); PG8_SCHED; PG8_LDA(At, 1, 0); PG8_STAGE(PG8_SA(0, 1), a2 + hstep, voffA);
;             PG8_WAIT_V(8); PG8_WAIT_L(0); PG8_BAR; PG8_MMA(0, 0, At, B0); PG8_MMA(0, 1, At, B1); PG8_BAR; PG8_SCHED;
;             PG8_LDA(At, 1, 1); PG8_STAGE(PG8_SB(1, 0), b3, voffB); PG8_STAGE(PG8_SB(1, 1), b3 + hstep, voffB); PG8_STAGE(PG8_SA(1, 0), a3, voffA);
;             PG8_WAIT_V(8); PG8_WAIT_L(0); PG8_BAR; PG8_MMA(1, 0, At, B0); PG8_MMA(1, 1, At, B1); PG8_BAR; PG8_SCHED;
.Lgu_nopf:
	ds_read_b128 v[32:35], v172
	ds_read_b128 v[36:39], v172 offset:1024
	ds_read_b128 v[40:43], v172 offset:2048
	ds_read_b128 v[44:47], v172 offset:3072
	ds_read_b128 v[156:159], v172 offset:16384
	ds_read_b128 v[168:171], v172 offset:17408
	ds_read_b128 v[186:189], v172 offset:18432
	ds_read_b128 v[190:193], v172 offset:19456
	s_add_i32 m0, s9, 0xc000
	ds_read_b128 v[194:197], v165
	ds_read_b128 v[198:201], v165 offset:1024
	ds_read_b128 v[202:205], v165 offset:2048
	ds_read_b128 v[206:209], v165 offset:3072
	ds_read_b128 v[210:213], v165 offset:4096
	ds_read_b128 v[214:217], v165 offset:5120
	ds_read_b128 v[218:221], v165 offset:6144
	ds_read_b128 v[222:225], v165 offset:7168
	global_load_lds_dwordx4 v152, s[54:55]
	s_add_i32 m0, s9, 0xe000
	s_nop 0
	global_load_lds_dwordx4 v154, s[54:55]
	s_waitcnt vmcnt(8)
	s_waitcnt lgkmcnt(0)
	s_barrier
	s_waitcnt lgkmcnt(0)
	v_mfma_f32_16x16x32_f16 v[142:145], v[32:35], v[194:197], v[142:145]
	v_mfma_f32_16x16x32_f16 v[138:141], v[40:43], v[194:197], v[138:141]
	v_mfma_f32_16x16x32_f16 v[124:127], v[32:35], v[202:205], v[124:127]
	v_mfma_f32_16x16x32_f16 v[120:123], v[40:43], v[202:205], v[120:123]
	v_mfma_f32_16x16x32_f16 v[108:111], v[32:35], v[210:213], v[108:111]
	v_mfma_f32_16x16x32_f16 v[104:107], v[40:43], v[210:213], v[104:107]
	v_mfma_f32_16x16x32_f16 v[92:95], v[32:35], v[218:221], v[92:95]
	v_mfma_f32_16x16x32_f16 v[88:91], v[40:43], v[218:221], v[88:91]
	v_mfma_f32_16x16x32_f16 v[142:145], v[36:39], v[198:201], v[142:145]
	v_mfma_f32_16x16x32_f16 v[138:141], v[44:47], v[198:201], v[138:141]
	v_mfma_f32_16x16x32_f16 v[124:127], v[36:39], v[206:209], v[124:127]
	v_mfma_f32_16x16x32_f16 v[120:123], v[44:47], v[206:209], v[120:123]
	v_mfma_f32_16x16x32_f16 v[108:111], v[36:39], v[214:217], v[108:111]
	v_mfma_f32_16x16x32_f16 v[104:107], v[44:47], v[214:217], v[104:107]
	v_mfma_f32_16x16x32_f16 v[92:95], v[36:39], v[222:225], v[92:95]
	v_mfma_f32_16x16x32_f16 v[88:91], v[44:47], v[222:225], v[88:91]
	v_mfma_f32_16x16x32_f16 v[134:137], v[156:159], v[194:197], v[134:137]
	v_mfma_f32_16x16x32_f16 v[130:133], v[186:189], v[194:197], v[130:133]
	v_mfma_f32_16x16x32_f16 v[116:119], v[156:159], v[202:205], v[116:119]
	v_mfma_f32_16x16x32_f16 v[112:115], v[186:189], v[202:205], v[112:115]
	v_mfma_f32_16x16x32_f16 v[100:103], v[156:159], v[210:213], v[100:103]
	v_mfma_f32_16x16x32_f16 v[96:99], v[186:189], v[210:213], v[96:99]
	v_mfma_f32_16x16x32_f16 v[84:87], v[156:159], v[218:221], v[84:87]
	v_mfma_f32_16x16x32_f16 v[80:83], v[186:189], v[218:221], v[80:83]
	v_mfma_f32_16x16x32_f16 v[134:137], v[168:171], v[198:201], v[134:137]
	v_mfma_f32_16x16x32_f16 v[130:133], v[190:193], v[198:201], v[130:133]
	v_mfma_f32_16x16x32_f16 v[116:119], v[168:171], v[206:209], v[116:119]
	v_mfma_f32_16x16x32_f16 v[112:115], v[190:193], v[206:209], v[112:115]
	v_mfma_f32_16x16x32_f16 v[100:103], v[168:171], v[214:217], v[100:103]
	v_mfma_f32_16x16x32_f16 v[96:99], v[190:193], v[214:217], v[96:99]
	v_mfma_f32_16x16x32_f16 v[84:87], v[168:171], v[222:225], v[84:87]
	v_mfma_f32_16x16x32_f16 v[80:83], v[190:193], v[222:225], v[80:83]
	s_barrier
	s_add_u32 s98, s56, s16
	s_addc_u32 s99, s57, s17
	s_add_u32 s100, s58, s16
	s_addc_u32 s101, s59, s17
	s_add_i32 s62, s62, s8
	s_mov_b32 m0, s62
	ds_read_b128 v[194:197], v165 offset:16384
	ds_read_b128 v[198:201], v165 offset:17408
	ds_read_b128 v[202:205], v165 offset:18432
	ds_read_b128 v[206:209], v165 offset:19456
	ds_read_b128 v[210:213], v165 offset:20480
	ds_read_b128 v[214:217], v165 offset:21504
	ds_read_b128 v[218:221], v165 offset:22528
	ds_read_b128 v[222:225], v165 offset:23552
	global_load_lds_dwordx4 v128, s[56:57]
	s_add_i32 m0, s62, 0x2000
	s_add_u32 s62, s56, 0x40000
	s_addc_u32 s63, s57, 0
	s_add_i32 s64, s64, s8
	global_load_lds_dwordx4 v146, s[56:57]
	s_mov_b32 m0, s64
	s_nop 0
	global_load_lds_dwordx4 v128, s[62:63]
	s_add_i32 m0, s64, 0x2000
	s_nop 0
	global_load_lds_dwordx4 v146, s[62:63]
	s_mov_b32 m0, s9
	s_nop 0
	global_load_lds_dwordx4 v150, s[58:59]
	s_mov_b32 m0, s10
	s_nop 0
	global_load_lds_dwordx4 v148, s[58:59]
	s_waitcnt vmcnt(8)
	s_waitcnt lgkmcnt(0)
	s_barrier
	s_waitcnt lgkmcnt(0)
	v_mfma_f32_16x16x32_f16 v[76:79], v[32:35], v[194:197], v[76:79]
	v_mfma_f32_16x16x32_f16 v[72:75], v[40:43], v[194:197], v[72:75]
	v_mfma_f32_16x16x32_f16 v[60:63], v[32:35], v[202:205], v[60:63]
	v_mfma_f32_16x16x32_f16 v[56:59], v[40:43], v[202:205], v[56:59]
	v_mfma_f32_16x16x32_f16 v[28:31], v[32:35], v[210:213], v[28:31]
	v_mfma_f32_16x16x32_f16 v[24:27], v[40:43], v[210:213], v[24:27]
	v_mfma_f32_16x16x32_f16 v[12:15], v[32:35], v[218:221], v[12:15]
	v_mfma_f32_16x16x32_f16 v[8:11], v[40:43], v[218:221], v[8:11]
	v_mfma_f32_16x16x32_f16 v[76:79], v[36:39], v[198:201], v[76:79]
	v_mfma_f32_16x16x32_f16 v[72:75], v[44:47], v[198:201], v[72:75]
	v_mfma_f32_16x16x32_f16 v[60:63], v[36:39], v[206:209], v[60:63]
	v_mfma_f32_16x16x32_f16 v[56:59], v[44:47], v[206:209], v[56:59]
	v_mfma_f32_16x16x32_f16 v[28:31], v[36:39], v[214:217], v[28:31]
	v_mfma_f32_16x16x32_f16 v[24:27], v[44:47], v[214:217], v[24:27]
	v_mfma_f32_16x16x32_f16 v[12:15], v[36:39], v[222:225], v[12:15]
	v_mfma_f32_16x16x32_f16 v[8:11], v[44:47], v[222:225], v[8:11]
	v_mfma_f32_16x16x32_f16 v[20:23], v[156:159], v[210:213], v[20:23]
	v_mfma_f32_16x16x32_f16 v[16:19], v[186:189], v[210:213], v[16:19]
	v_mfma_f32_16x16x32_f16 v[4:7], v[156:159], v[218:221], v[4:7]
	v_mfma_f32_16x16x32_f16 v[0:3], v[186:189], v[218:221], v[0:3]
	v_mfma_f32_16x16x32_f16 v[32:35], v[156:159], v[194:197], v[68:71]
	v_mfma_f32_16x16x32_f16 v[36:39], v[186:189], v[194:197], v[64:67]
	v_mfma_f32_16x16x32_f16 v[40:43], v[156:159], v[202:205], v[52:55]
	v_mfma_f32_16x16x32_f16 v[44:47], v[186:189], v[202:205], v[48:51]
	v_mfma_f32_16x16x32_f16 v[20:23], v[168:171], v[214:217], v[20:23]
	v_mfma_f32_16x16x32_f16 v[16:19], v[190:193], v[214:217], v[16:19]
	v_mfma_f32_16x16x32_f16 v[4:7], v[168:171], v[222:225], v[4:7]
	v_mfma_f32_16x16x32_f16 v[0:3], v[190:193], v[222:225], v[0:3]
	v_mfma_f32_16x16x32_f16 v[32:35], v[168:171], v[198:201], v[32:35]
	v_mfma_f32_16x16x32_f16 v[36:39], v[190:193], v[198:201], v[36:39]
	v_mfma_f32_16x16x32_f16 v[40:43], v[168:171], v[206:209], v[40:43]
	v_mfma_f32_16x16x32_f16 v[44:47], v[190:193], v[206:209], v[44:47]
	s_barrier
; #define PG8_STAGE(bufoff, gbase, voff) do { _Pragma("unroll") for (int _i = 0; _i < 2; ++_i) \
;         __builtin_amdgcn_global_load_lds((const unsigned*)((const char*)(gbase) + (voff)[_i]), (PG8_LAS unsigned*)(lds + (bufoff) + ldsw + _i * 8192), 16, 0, 0); } while (0)
; #define PG8_LDA(dst, b, h) do { _Pragma("unroll") for (int m = 0; m < 4; ++m) _Pragma("unroll") for (int k = 0; k < 2; ++k) dst[m][k] = *(const PG8_LAS bf16x8*)(lds + PG8_SA(b, h) + aoff + m * 2048 + k * 1024); } while (0)
; #define PG8_LDB(dst, b, h) do { _Pragma("unroll") for (int n = 0; n < 2; ++n) _Pragma("unroll") for (int k = 0; k < 2; ++k) dst[n][k] = *(const PG8_LAS bf16x8*)(lds + PG8_SB(b, h) + boff + n * 2048 + k * 1024); } while (0)
; #define PG8_MMA(ai, bj, At, Bt) do { __builtin_amdgcn_s_setprio(1); _Pragma("unroll") for (int m = 0; m < 4; ++m) _Pragma("unroll") for (int n = 0; n < 2; ++n) _Pragma("unroll") for (int k = 0; k < 2; ++k) \
;         acc[ai][bj][m][n] = mma16<F16>(Bt[n][k], At[m][k], acc[ai][bj][m][n]); __builtin_amdgcn_s_setprio(0); } while (0)
; template <class Epi, class Sched, bool ALIGN_EPI = false, bool SP2 = false, bool F16 = false>
; __device__ __forceinline__ void gemm_phase(PG8_LAS unsigned char* lds, const Gemm g, const Sched& S, const Epi& E) {
;     ...
;             PG8_LDB(B0, 0, 0); PG8_LDB(B1, 0, 1); PG8_SCHED; PG8_LDA(At, 0, 0); PG8_STAGE(PG8_SA(1, 1), a1 + hstep, voffA);
;             PG8_WAIT_V(8); PG8_WAIT_L(0); PG8_BAR; PG8_MMA(0, 0, At, B0); PG8_MMA(0, 1, At, B1); PG8_BAR; PG8_SCHED;
;             PG8_LDA(At, 0, 1); PG8_STAGE(PG8_SB(0, 0), b2, voffB); PG8_STAGE(PG8_SB(0, 1), b2 + hstep, voffB); PG8_STAGE(PG8_SA(0, 0), a2, voffA);
;             PG8_WAIT_V(8); PG8_WAIT_L(0); PG8_BAR; PG8_MMA(1, 0, At, B0); PG8_MMA(1, 1, At, B1); PG8_BAR; PG8_SCHED;
;             PG8_LDB(B0, 1, 0); PG8_LDB(B1, 1, 1); PG8_SCHED; PG8_LDA(At, 1, 0); PG8_STAGE(PG8_SA(0, 1), a2 + hstep, voffA);
;             PG8_WAIT_V(8); PG8_WAIT_L(0); PG8_BAR; PG8_MMA(0, 0, At, B0); PG8_MMA(0, 1, At, B1); PG8_BAR; PG8_SCHED;
;             PG8_LDA(At, 1, 1); PG8_STAGE(PG8_SB(1, 0), b3, voffB); PG8_STAGE(PG8_SB(1, 1), b3 + hstep, voffB); PG8_STAGE(PG8_SA(1, 0), a3, voffA);
;             PG8_WAIT_V(8); PG8_WAIT_L(0); PG8_BAR; PG8_MMA(1, 0, At, B0); PG8_MMA(1, 1, At, B1); PG8_BAR; PG8_SCHED;
;     ...
;         if constexpr (ALIGN_EPI) { if (wr == 0) PG8_BAR; }
	s_add_i32 s62, 0, 0x18000
	s_add_i32 s63, 0, 0x1c000
	ds_read_b128 v[48:51], v172 offset:32768
	ds_read_b128 v[52:55], v172 offset:33792
	ds_read_b128 v[64:67], v172 offset:34816
	ds_read_b128 v[68:71], v172 offset:35840
	ds_read_b128 v[156:159], v172 offset:49152
	ds_read_b128 v[168:171], v172 offset:50176
	ds_read_b128 v[186:189], v172 offset:51200
	ds_read_b128 v[190:193], v172 offset:52224
	s_add_u32 s58, s58, 0x40000
	s_addc_u32 s59, s59, 0
	s_mov_b32 m0, s11
	ds_read_b128 v[194:197], v165 offset:32768
	ds_read_b128 v[198:201], v165 offset:33792
	ds_read_b128 v[202:205], v165 offset:34816
	ds_read_b128 v[206:209], v165 offset:35840
	ds_read_b128 v[210:213], v165 offset:36864
	ds_read_b128 v[214:217], v165 offset:37888
	ds_read_b128 v[218:221], v165 offset:38912
	ds_read_b128 v[222:225], v165 offset:39936
	global_load_lds_dwordx4 v150, s[58:59]
	s_mov_b32 m0, s13
	s_nop 0
	global_load_lds_dwordx4 v148, s[58:59]
	s_waitcnt vmcnt(8)
	s_waitcnt lgkmcnt(0)
	s_barrier
	s_waitcnt lgkmcnt(0)
	v_mfma_f32_16x16x32_f16 v[142:145], v[48:51], v[194:197], v[142:145]
	v_mfma_f32_16x16x32_f16 v[138:141], v[64:67], v[194:197], v[138:141]
	v_mfma_f32_16x16x32_f16 v[124:127], v[48:51], v[202:205], v[124:127]
	v_mfma_f32_16x16x32_f16 v[120:123], v[64:67], v[202:205], v[120:123]
	v_mfma_f32_16x16x32_f16 v[108:111], v[48:51], v[210:213], v[108:111]
	v_mfma_f32_16x16x32_f16 v[104:107], v[64:67], v[210:213], v[104:107]
	v_mfma_f32_16x16x32_f16 v[92:95], v[48:51], v[218:221], v[92:95]
	v_mfma_f32_16x16x32_f16 v[88:91], v[64:67], v[218:221], v[88:91]
	v_mfma_f32_16x16x32_f16 v[142:145], v[52:55], v[198:201], v[142:145]
	v_mfma_f32_16x16x32_f16 v[138:141], v[68:71], v[198:201], v[138:141]
	v_mfma_f32_16x16x32_f16 v[124:127], v[52:55], v[206:209], v[124:127]
	v_mfma_f32_16x16x32_f16 v[120:123], v[68:71], v[206:209], v[120:123]
	v_mfma_f32_16x16x32_f16 v[108:111], v[52:55], v[214:217], v[108:111]
	v_mfma_f32_16x16x32_f16 v[104:107], v[68:71], v[214:217], v[104:107]
	v_mfma_f32_16x16x32_f16 v[92:95], v[52:55], v[222:225], v[92:95]
	v_mfma_f32_16x16x32_f16 v[88:91], v[68:71], v[222:225], v[88:91]
	v_mfma_f32_16x16x32_f16 v[134:137], v[156:159], v[194:197], v[134:137]
	v_mfma_f32_16x16x32_f16 v[130:133], v[186:189], v[194:197], v[130:133]
	v_mfma_f32_16x16x32_f16 v[116:119], v[156:159], v[202:205], v[116:119]
	v_mfma_f32_16x16x32_f16 v[112:115], v[186:189], v[202:205], v[112:115]
	v_mfma_f32_16x16x32_f16 v[100:103], v[156:159], v[210:213], v[100:103]
	v_mfma_f32_16x16x32_f16 v[96:99], v[186:189], v[210:213], v[96:99]
	v_mfma_f32_16x16x32_f16 v[84:87], v[156:159], v[218:221], v[84:87]
	v_mfma_f32_16x16x32_f16 v[80:83], v[186:189], v[218:221], v[80:83]
	v_mfma_f32_16x16x32_f16 v[134:137], v[168:171], v[198:201], v[134:137]
	v_mfma_f32_16x16x32_f16 v[130:133], v[190:193], v[198:201], v[130:133]
	v_mfma_f32_16x16x32_f16 v[116:119], v[168:171], v[206:209], v[116:119]
	v_mfma_f32_16x16x32_f16 v[112:115], v[190:193], v[206:209], v[112:115]
	v_mfma_f32_16x16x32_f16 v[100:103], v[168:171], v[214:217], v[100:103]
	v_mfma_f32_16x16x32_f16 v[96:99], v[190:193], v[214:217], v[96:99]
	v_mfma_f32_16x16x32_f16 v[84:87], v[168:171], v[222:225], v[84:87]
	v_mfma_f32_16x16x32_f16 v[80:83], v[190:193], v[222:225], v[80:83]
	s_barrier
	s_add_i32 s58, s62, s8
	s_mov_b32 m0, s58
	ds_read_b128 v[194:197], v165 offset:49152
	ds_read_b128 v[198:201], v165 offset:50176
	ds_read_b128 v[202:205], v165 offset:51200
	ds_read_b128 v[206:209], v165 offset:52224
	ds_read_b128 v[210:213], v165 offset:53248
	ds_read_b128 v[214:217], v165 offset:54272
	ds_read_b128 v[218:221], v165 offset:55296
	ds_read_b128 v[222:225], v165 offset:56320
	global_load_lds_dwordx4 v128, s[98:99]
	s_add_i32 m0, s58, 0x2000
	s_add_u32 s56, s56, 0x40080
	s_addc_u32 s57, s57, 0
	s_add_i32 s58, s63, s8
	global_load_lds_dwordx4 v146, s[98:99]
	s_mov_b32 m0, s58
	s_nop 0
	global_load_lds_dwordx4 v128, s[56:57]
	s_add_i32 m0, s58, 0x2000
	s_nop 0
	global_load_lds_dwordx4 v146, s[56:57]
	s_mov_b32 m0, s20
	s_nop 0
	global_load_lds_dwordx4 v150, s[100:101]
	s_mov_b32 m0, s21
	s_nop 0
	global_load_lds_dwordx4 v148, s[100:101]
	s_waitcnt vmcnt(8)
	s_waitcnt lgkmcnt(0)
	s_barrier
	s_waitcnt lgkmcnt(0)
	v_mfma_f32_16x16x32_f16 v[76:79], v[48:51], v[194:197], v[76:79]
	v_mfma_f32_16x16x32_f16 v[72:75], v[64:67], v[194:197], v[72:75]
	v_mfma_f32_16x16x32_f16 v[60:63], v[48:51], v[202:205], v[60:63]
	v_mfma_f32_16x16x32_f16 v[56:59], v[64:67], v[202:205], v[56:59]
	v_mfma_f32_16x16x32_f16 v[28:31], v[48:51], v[210:213], v[28:31]
	v_mfma_f32_16x16x32_f16 v[24:27], v[64:67], v[210:213], v[24:27]
	v_mfma_f32_16x16x32_f16 v[12:15], v[48:51], v[218:221], v[12:15]
	v_mfma_f32_16x16x32_f16 v[8:11], v[64:67], v[218:221], v[8:11]
	v_mfma_f32_16x16x32_f16 v[76:79], v[52:55], v[198:201], v[76:79]
	v_mfma_f32_16x16x32_f16 v[72:75], v[68:71], v[198:201], v[72:75]
	v_mfma_f32_16x16x32_f16 v[60:63], v[52:55], v[206:209], v[60:63]
	v_mfma_f32_16x16x32_f16 v[56:59], v[68:71], v[206:209], v[56:59]
	v_mfma_f32_16x16x32_f16 v[28:31], v[52:55], v[214:217], v[28:31]
	v_mfma_f32_16x16x32_f16 v[24:27], v[68:71], v[214:217], v[24:27]
	v_mfma_f32_16x16x32_f16 v[12:15], v[52:55], v[222:225], v[12:15]
	v_mfma_f32_16x16x32_f16 v[8:11], v[68:71], v[222:225], v[8:11]
	v_mfma_f32_16x16x32_f16 v[32:35], v[156:159], v[194:197], v[32:35]
	v_mfma_f32_16x16x32_f16 v[68:71], v[168:171], v[198:201], v[32:35]
	v_mfma_f32_16x16x32_f16 v[32:35], v[186:189], v[194:197], v[36:39]
	v_mfma_f32_16x16x32_f16 v[64:67], v[190:193], v[198:201], v[32:35]
	v_mfma_f32_16x16x32_f16 v[32:35], v[156:159], v[202:205], v[40:43]
	v_mfma_f32_16x16x32_f16 v[52:55], v[168:171], v[206:209], v[32:35]
	v_mfma_f32_16x16x32_f16 v[32:35], v[186:189], v[202:205], v[44:47]
	v_mfma_f32_16x16x32_f16 v[20:23], v[156:159], v[210:213], v[20:23]
	v_mfma_f32_16x16x32_f16 v[16:19], v[186:189], v[210:213], v[16:19]
	v_mfma_f32_16x16x32_f16 v[4:7], v[156:159], v[218:221], v[4:7]
	v_mfma_f32_16x16x32_f16 v[0:3], v[186:189], v[218:221], v[0:3]
	v_mfma_f32_16x16x32_f16 v[48:51], v[190:193], v[206:209], v[32:35]
	v_mfma_f32_16x16x32_f16 v[20:23], v[168:171], v[214:217], v[20:23]
	v_mfma_f32_16x16x32_f16 v[16:19], v[190:193], v[214:217], v[16:19]
	v_mfma_f32_16x16x32_f16 v[4:7], v[168:171], v[222:225], v[4:7]
	v_mfma_f32_16x16x32_f16 v[0:3], v[190:193], v[222:225], v[0:3]
	s_barrier
	s_add_i32 s61, s61, 2
	s_add_u32 s54, s54, 0x100
	s_addc_u32 s55, s55, 0
	s_add_u32 s49, s49, 0x100
	s_addc_u32 s60, s60, 0
	s_cmp_gt_u32 s61, 13
	s_cbranch_scc0 .LBB0_904
	s_and_b64 vcc, exec, s[44:45]
	s_cbranch_vccz .LBB0_907
	s_barrier

; #define PG8_STAGE(bufoff, gbase, voff) do { _Pragma("unroll") for (int _i = 0; _i < 2; ++_i) \
;         __builtin_amdgcn_global_load_lds((const unsigned*)((const char*)(gbase) + (voff)[_i]), (PG8_LAS unsigned*)(lds + (bufoff) + ldsw + _i * 8192), 16, 0, 0); } while (0)
; #define PG8_BAR __builtin_amdgcn_s_barrier()
; template <class Epi, class Sched, bool ALIGN_EPI = false, bool SP2 = false, bool F16 = false>
; __device__ __forceinline__ void gemm_phase(PG8_LAS unsigned char* lds, const Gemm g, const Sched& S, const Epi& E) {
;     int tid_l = threadIdx.x; asm volatile("" : "+v"(tid_l));
;     const int tid = tid_l, wid = __builtin_amdgcn_readfirstlane(tid >> 6), lane = tid & 63, wr = wid >> 2, wc = wid & 3, fr = lane & 15, fq = lane >> 4;
;     const int K = g.K, nt = K / BK;
;     unsigned voffA[2], voffB[2];
; #pragma unroll
;     for (int i = 0; i < 2; ++i) { int R, C; stage_rc(tid * 16 + i * 8192, R, C); const int Rb = Epi::PERM ? ((R & ~31) + perm32(R & 31)) : R;
;         voffA[i] = (unsigned)(R * K + C) * 2u; voffB[i] = (unsigned)(Rb * K + C) * 2u; }
;     const size_t kstep = (size_t)(BK * 2);
;     const size_t hstep = (size_t)HALF * K * 2;
;     const size_t tstep = 2 * hstep;
;     const unsigned ldsw = (unsigned)wid * 1024u;
;     const int aoff = lds_byte(wr * 64 + fr, fq * 8), boff = lds_byte(wc * 32 + fr, fq * 8);
;     ...
;     Unit cur, nxt; int ui = 0;
;     if (!S.next(0, cur)) return;
;     f32x4 acc[2][2][4][2];
; #pragma unroll
;     for (int a = 0; a < 2; ++a)
; #pragma unroll
;         for (int b = 0; b < 2; ++b)
; #pragma unroll
;             for (int m = 0; m < 4; ++m)
; #pragma unroll
;                 for (int n = 0; n < 2; ++n) acc[a][b][m][n] = (f32x4){0.f, 0.f, 0.f, 0.f};
;     bf16x8 At[4][2], B0[2][2], B1[2][2];
;     const char* cA = (const char*)g.A + (size_t)cur.pm * tstep; const char* cB = (const char*)g.Bt + (size_t)cur.pn * tstep + (cur.pm >= g.mhalf ? g.bstride : (size_t)0);
;     S.a_ready(cur);
;     if constexpr (SP2) {
;         PG8_STAGE(PG8_SB(0, 0), cB, voffB); PG8_STAGE(PG8_SB(0, 1), cB + hstep, voffB); PG8_STAGE(PG8_SA(0, 0), cA, voffA); PG8_STAGE(PG8_SA(0, 1), cA + hstep, voffA);
;         if (wr == 1) PG8_BAR;
.LBB0_979:
	s_andn2_b64 vcc, exec, s[0:1]
	s_cbranch_vccnz .LBB0_239
	v_mov_b32_e32 v12, v226
	s_and_b64 vcc, exec, s[38:39]
	v_readfirstlane_b32 s4, v12
	s_cbranch_vccnz .LBB0_1020
	s_lshr_b32 s98, s4, 6
	s_cmp_ge_u32 s98, 4
	s_cbranch_scc0 .Ldown_prio_done
	s_setprio 1
.Ldown_prio_done:
	v_lshlrev_b32_e32 v0, 4, v12
	s_waitcnt lgkmcnt(0)
	v_add_u32_e32 v1, 0x2000, v0
	v_ashrrev_i32_e32 v2, 31, v1
	v_lshrrev_b32_e32 v2, 22, v2
	v_add_u32_e32 v2, v1, v2
	v_ashrrev_i32_e32 v4, 10, v2
	v_mul_i32_i24_e32 v2, 0x400, v4
	v_sub_u32_e32 v1, v1, v2
	v_lshrrev_b32_e32 v2, 4, v1
	v_bitop3_b32 v1, v2, v1, 32 bitop3:0x6c
	v_ashrrev_i32_e32 v2, 31, v1
	v_lshrrev_b32_e32 v2, 26, v2
	v_readlane_b32 s0, v255, 14
	v_add_u32_e32 v2, v1, v2
	v_lshlrev_b32_e32 v3, 3, v4
	v_readlane_b32 s1, v255, 15
	v_ashrrev_i32_e32 v5, 6, v2
	v_and_b32_e32 v3, -16, v3
	s_mul_i32 s0, s0, 0x580000
	v_readlane_b32 s1, v254, 23
	v_add_u32_e32 v3, v5, v3
	s_add_u32 s6, s1, s0
	v_and_b32_e32 v6, 3, v5
	s_mov_b32 s1, 0xffffe0
	v_lshrrev_b32_e32 v7, 2, v3
	v_lshlrev_b32_e32 v8, 1, v3
	v_and_or_b32 v6, v3, s1, v6
	v_and_b32_e32 v7, 4, v7
	v_and_b32_e32 v8, 24, v8
	v_and_b32_e32 v2, 0xc0, v2
	v_or3_b32 v6, v6, v7, v8
	v_sub_u32_e32 v1, v1, v2
	v_readlane_b32 s0, v254, 24
	v_mul_u32_u24_e32 v8, 0xb00, v6
	v_lshlrev_b32_e32 v6, 5, v4
	v_ashrrev_i16_sdwa v1, v228, sext(v1) dst_sel:DWORD dst_unused:UNUSED_PAD src0_sel:DWORD src1_sel:BYTE_0
	s_addc_u32 s7, s0, 0
	v_and_b32_e32 v6, 32, v6
	v_bfe_i32 v7, v1, 0, 16
	s_movk_i32 s0, 0xb00
	v_add_u32_e32 v1, v6, v7
	v_mul_lo_u32 v2, v3, s0
	v_add_lshl_u32 v162, v8, v1, 1
	v_add_lshl_u32 v164, v1, v2, 1
	v_bfe_i32 v1, v12, 27, 1
	v_lshrrev_b32_e32 v1, 22, v1
	v_add_u32_e32 v1, v0, v1
	v_and_b32_e32 v1, 0xfffffc00, v1
	v_sub_u32_e32 v0, v0, v1
	v_lshrrev_b32_e32 v1, 4, v0
	v_ashrrev_i32_e32 v2, 31, v12
	v_bitop3_b32 v0, v1, v0, 32 bitop3:0x6c
	v_lshrrev_b32_e32 v2, 26, v2
	v_ashrrev_i32_e32 v1, 31, v0
	v_add_u32_e32 v2, v12, v2
	v_lshrrev_b32_e32 v1, 26, v1
	v_ashrrev_i32_e32 v9, 6, v2
	v_add_u32_e32 v1, v0, v1
	v_lshlrev_b32_e32 v2, 3, v9
	v_ashrrev_i32_e32 v8, 6, v1
	v_and_b32_e32 v2, -16, v2
	v_add_u32_e32 v2, v8, v2
	v_and_b32_e32 v3, 3, v8
	v_lshrrev_b32_e32 v10, 2, v2
	v_lshlrev_b32_e32 v11, 1, v2
	v_and_b32_e32 v1, 0xc0, v1
	s_ashr_i32 s5, s4, 6
	v_and_or_b32 v3, v2, s1, v3
	v_and_b32_e32 v10, 4, v10
	v_and_b32_e32 v11, 24, v11
	v_sub_u32_e32 v0, v0, v1
	v_readlane_b32 s1, v254, 28
	s_ashr_i32 s21, s4, 8
	s_lshl_b32 s8, s5, 10
	v_or3_b32 v3, v3, v10, v11
	v_lshlrev_b32_e32 v10, 5, v9
	v_ashrrev_i16_sdwa v0, v228, sext(v0) dst_sel:DWORD dst_unused:UNUSED_PAD src0_sel:DWORD src1_sel:BYTE_0
	v_mul_lo_u32 v1, v2, s0
	s_mul_i32 s0, s1, 0x160000
	v_and_b32_e32 v10, 32, v10
	v_bfe_i32 v11, v0, 0, 16
	s_add_u32 s50, s6, s0
	s_mul_hi_i32 s0, s1, 0x160000
	v_mul_u32_u24_e32 v3, 0xb00, v3
	v_add_u32_e32 v0, v10, v11
	s_addc_u32 s51, s7, s0
	s_add_i32 s9, s8, 0
	v_add_lshl_u32 v128, v3, v0, 1
	s_add_i32 m0, s9, 0x10000
	v_add_lshl_u32 v166, v0, v1, 1
	global_load_lds_dwordx4 v128, s[50:51]
	s_add_i32 m0, s9, 0x12000
	s_add_u32 s0, s50, 0xb0000
	global_load_lds_dwordx4 v162, s[50:51]
	s_addc_u32 s1, s51, 0
	s_add_i32 m0, s9, 0x14000
	s_add_i32 s10, s9, 0x2000
	global_load_lds_dwordx4 v128, s[0:1]
	s_add_i32 m0, s9, 0x16000
	s_add_i32 s11, s9, 0x4000
	global_load_lds_dwordx4 v162, s[0:1]
	v_readlane_b32 s0, v254, 56
	s_mov_b32 m0, s9
	v_readlane_b32 s1, v254, 57
	s_add_i32 s14, s9, 0x6000
	v_mov_b32_e32 v163, v129
	s_cmp_eq_u32 s21, 1
	v_lshl_add_u64 v[0:1], s[50:51], 0, v[128:129]
	v_lshl_add_u64 v[2:3], s[50:51], 0, v[162:163]
	global_load_lds_dwordx4 v166, s[0:1]
	s_mov_b32 m0, s10
	s_nop 0
	global_load_lds_dwordx4 v164, s[0:1]
	v_readlane_b32 s0, v254, 58
	s_mov_b32 m0, s11
	v_readlane_b32 s1, v254, 59
	s_nop 4
	global_load_lds_dwordx4 v166, s[0:1]
	s_mov_b32 m0, s14
	s_nop 0
	global_load_lds_dwordx4 v164, s[0:1]
	s_cselect_b64 s[0:1], -1, 0
	s_cmp_lg_u32 s21, 1
	s_cbranch_scc1 .LBB0_983
	s_barrier

; #define PG8_STAGE(bufoff, gbase, voff) do { _Pragma("unroll") for (int _i = 0; _i < 2; ++_i) \
;         __builtin_amdgcn_global_load_lds((const unsigned*)((const char*)(gbase) + (voff)[_i]), (PG8_LAS unsigned*)(lds + (bufoff) + ldsw + _i * 8192), 16, 0, 0); } while (0)
; #define PG8_WAIT_V(n) asm volatile("s_waitcnt vmcnt(" #n ")" ::: "memory")
; template <class Epi, class Sched, bool ALIGN_EPI = false, bool SP2 = false, bool F16 = false>
; __device__ __forceinline__ void gemm_phase(PG8_LAS unsigned char* lds, const Gemm g, const Sched& S, const Epi& E) {
;     ...
;         const bool has_next = S.next(ui + 1, nxt);
;         const char* nA = has_next ? (const char*)g.A + (size_t)nxt.pm * tstep : cA; const char* nB = has_next ? (const char*)g.Bt + (size_t)nxt.pn * tstep + (nxt.pm >= g.mhalf ? g.bstride : (size_t)0) : cB;
;         for (int t = 0; t < nt; t += 2) {
;             if constexpr (Epi::KHOOK) { if (t == 4 || t == 10) E.khook(acc, cur, t, wr, fr); }
;             const bool last = (t == nt - 2);
;             const char* a1 = cA + (size_t)(t + 1) * kstep;
;             const char* a2 = last ? nA : cA + (size_t)(t + 2) * kstep; const char* b2 = last ? nB : cB + (size_t)(t + 2) * kstep;
;             const char* a3 = a2 + kstep; const char* b3 = b2 + kstep;
;             if (last && has_next) S.a_ready(nxt);
;             if constexpr (SP2) {
;             PG8_LDB(B0, 0, 0); PG8_LDB(B1, 0, 1); PG8_SCHED; PG8_LDA(At, 0, 0); PG8_STAGE(PG8_SA(1, 1), a1 + hstep, voffA);
;             PG8_WAIT_V(8); PG8_WAIT_L(0); PG8_BAR; PG8_MMA(0, 0, At, B0); PG8_MMA(0, 1, At, B1); PG8_BAR; PG8_SCHED;
;             PG8_LDA(At, 0, 1); PG8_STAGE(PG8_SB(0, 0), b2, voffB); PG8_STAGE(PG8_SB(0, 1), b2 + hstep, voffB); PG8_STAGE(PG8_SA(0, 0), a2, voffA);
;             PG8_WAIT_V(8); PG8_WAIT_L(0); PG8_BAR; PG8_MMA(1, 0, At, B0); PG8_MMA(1, 1, At, B1); PG8_BAR; PG8_SCHED;
;             PG8_LDB(B0, 1, 0); PG8_LDB(B1, 1, 1); PG8_SCHED; PG8_LDA(At, 1, 0); PG8_STAGE(PG8_SA(0, 1), a2 + hstep, voffA);
;             PG8_WAIT_V(8); PG8_WAIT_L(0); PG8_BAR; PG8_MMA(0, 0, At, B0); PG8_MMA(0, 1, At, B1); PG8_BAR; PG8_SCHED;
;             PG8_LDA(At, 1, 1); PG8_STAGE(PG8_SB(1, 0), b3, voffB); PG8_STAGE(PG8_SB(1, 1), b3 + hstep, voffB); PG8_STAGE(PG8_SA(1, 0), a3, voffA);
;             PG8_WAIT_V(8); PG8_WAIT_L(0); PG8_BAR; PG8_MMA(1, 0, At, B0); PG8_MMA(1, 1, At, B1); PG8_BAR; PG8_SCHED;
.LBB0_996:
	s_add_u32 s4, s50, 0x100
	s_addc_u32 s5, s51, 0
	s_mov_b32 s58, -2
	s_waitcnt lgkmcnt(0)
	v_add_u32_e32 v172, 0x10000, v224
	s_add_u32 s50, s48, 0x100
	s_addc_u32 s51, s49, 0
	s_add_i32 s59, 0, 0x10000
	s_cmp_eq_u32 s58, 40
	s_cselect_b32 s55, s43, s51
	s_cselect_b32 s54, s42, s50
	s_cselect_b32 s53, s47, s5
	s_cselect_b32 s52, s46, s4
	s_add_i32 s60, 0, 0x14000
	ds_read_b128 v[130:133], v172
	ds_read_b128 v[134:137], v172 offset:1024
	ds_read_b128 v[138:141], v172 offset:2048
	ds_read_b128 v[142:145], v172 offset:3072
	ds_read_b128 v[146:149], v172 offset:16384
	ds_read_b128 v[150:153], v172 offset:17408
	ds_read_b128 v[154:157], v172 offset:18432
	ds_read_b128 v[158:161], v172 offset:19456
	s_add_i32 m0, s9, 0xc000
	ds_read_b128 v[186:189], v225
	ds_read_b128 v[190:193], v225 offset:1024
	ds_read_b128 v[194:197], v225 offset:2048
	ds_read_b128 v[198:201], v225 offset:3072
	ds_read_b128 v[202:205], v225 offset:4096
	ds_read_b128 v[206:209], v225 offset:5120
	ds_read_b128 v[210:213], v225 offset:6144
	ds_read_b128 v[214:217], v225 offset:7168
	global_load_lds_dwordx4 v168, s[48:49]
	s_add_i32 m0, s9, 0xe000
	s_nop 0
	global_load_lds_dwordx4 v170, s[48:49]
	s_waitcnt vmcnt(24)
	s_waitcnt lgkmcnt(0)
	s_barrier
	s_waitcnt lgkmcnt(0)
	v_mfma_f32_16x16x32_bf16 v[124:127], v[130:133], v[186:189], 0
	v_mfma_f32_16x16x32_bf16 v[120:123], v[138:141], v[186:189], 0
	v_mfma_f32_16x16x32_bf16 v[116:119], v[130:133], v[194:197], 0
	v_mfma_f32_16x16x32_bf16 v[112:115], v[138:141], v[194:197], 0
	v_mfma_f32_16x16x32_bf16 v[108:111], v[130:133], v[202:205], 0
	v_mfma_f32_16x16x32_bf16 v[104:107], v[138:141], v[202:205], 0
	v_mfma_f32_16x16x32_bf16 v[100:103], v[130:133], v[210:213], 0
	v_mfma_f32_16x16x32_bf16 v[96:99], v[138:141], v[210:213], 0
	v_mfma_f32_16x16x32_bf16 v[124:127], v[134:137], v[190:193], v[124:127]
	v_mfma_f32_16x16x32_bf16 v[120:123], v[142:145], v[190:193], v[120:123]
	v_mfma_f32_16x16x32_bf16 v[116:119], v[134:137], v[198:201], v[116:119]
	v_mfma_f32_16x16x32_bf16 v[112:115], v[142:145], v[198:201], v[112:115]
	v_mfma_f32_16x16x32_bf16 v[108:111], v[134:137], v[206:209], v[108:111]
	v_mfma_f32_16x16x32_bf16 v[104:107], v[142:145], v[206:209], v[104:107]
	v_mfma_f32_16x16x32_bf16 v[100:103], v[134:137], v[214:217], v[100:103]
	v_mfma_f32_16x16x32_bf16 v[96:99], v[142:145], v[214:217], v[96:99]
	v_mfma_f32_16x16x32_bf16 v[60:63], v[146:149], v[186:189], 0
	v_mfma_f32_16x16x32_bf16 v[56:59], v[154:157], v[186:189], 0
	v_mfma_f32_16x16x32_bf16 v[52:55], v[146:149], v[194:197], 0
	v_mfma_f32_16x16x32_bf16 v[48:51], v[154:157], v[194:197], 0
	v_mfma_f32_16x16x32_bf16 v[44:47], v[146:149], v[202:205], 0
	v_mfma_f32_16x16x32_bf16 v[40:43], v[154:157], v[202:205], 0
	v_mfma_f32_16x16x32_bf16 v[36:39], v[146:149], v[210:213], 0
	v_mfma_f32_16x16x32_bf16 v[32:35], v[154:157], v[210:213], 0
	v_mfma_f32_16x16x32_bf16 v[60:63], v[150:153], v[190:193], v[60:63]
	v_mfma_f32_16x16x32_bf16 v[56:59], v[158:161], v[190:193], v[56:59]
	v_mfma_f32_16x16x32_bf16 v[52:55], v[150:153], v[198:201], v[52:55]
	v_mfma_f32_16x16x32_bf16 v[48:51], v[158:161], v[198:201], v[48:51]
	v_mfma_f32_16x16x32_bf16 v[44:47], v[150:153], v[206:209], v[44:47]
	v_mfma_f32_16x16x32_bf16 v[40:43], v[158:161], v[206:209], v[40:43]
	v_mfma_f32_16x16x32_bf16 v[36:39], v[150:153], v[214:217], v[36:39]
	v_mfma_f32_16x16x32_bf16 v[32:35], v[158:161], v[214:217], v[32:35]
	s_barrier
	s_add_u32 s98, s52, s16
	s_addc_u32 s99, s53, s17
	s_add_u32 s100, s54, s16
	s_addc_u32 s101, s55, s17
	s_add_i32 s48, s59, s8
	s_mov_b32 m0, s48
	ds_read_b128 v[186:189], v225 offset:16384
	ds_read_b128 v[190:193], v225 offset:17408
	ds_read_b128 v[194:197], v225 offset:18432
	ds_read_b128 v[198:201], v225 offset:19456
	ds_read_b128 v[202:205], v225 offset:20480
	ds_read_b128 v[206:209], v225 offset:21504
	ds_read_b128 v[210:213], v225 offset:22528
	ds_read_b128 v[214:217], v225 offset:23552
	global_load_lds_dwordx4 v128, s[52:53]
	s_add_i32 m0, s48, 0x2000
	s_add_u32 s48, s52, 0xb0000
	s_addc_u32 s49, s53, 0
	s_add_i32 s59, s60, s8
	global_load_lds_dwordx4 v162, s[52:53]
	s_mov_b32 m0, s59
	s_nop 0
	global_load_lds_dwordx4 v128, s[48:49]
	s_add_i32 m0, s59, 0x2000
	s_nop 0
	global_load_lds_dwordx4 v162, s[48:49]
	s_mov_b32 m0, s9
	s_nop 0
	global_load_lds_dwordx4 v166, s[54:55]
	s_mov_b32 m0, s10
	s_nop 0
	global_load_lds_dwordx4 v164, s[54:55]
	s_waitcnt vmcnt(24)
	s_waitcnt lgkmcnt(0)
	s_barrier
	s_waitcnt lgkmcnt(0)
	v_mfma_f32_16x16x32_bf16 v[92:95], v[130:133], v[186:189], 0
	v_mfma_f32_16x16x32_bf16 v[88:91], v[138:141], v[186:189], 0
	v_mfma_f32_16x16x32_bf16 v[84:87], v[130:133], v[194:197], 0
	v_mfma_f32_16x16x32_bf16 v[80:83], v[138:141], v[194:197], 0
	v_mfma_f32_16x16x32_bf16 v[76:79], v[130:133], v[202:205], 0
	v_mfma_f32_16x16x32_bf16 v[72:75], v[138:141], v[202:205], 0
	v_mfma_f32_16x16x32_bf16 v[68:71], v[130:133], v[210:213], 0
	v_mfma_f32_16x16x32_bf16 v[64:67], v[138:141], v[210:213], 0
	v_mfma_f32_16x16x32_bf16 v[92:95], v[134:137], v[190:193], v[92:95]
	v_mfma_f32_16x16x32_bf16 v[88:91], v[142:145], v[190:193], v[88:91]
	v_mfma_f32_16x16x32_bf16 v[84:87], v[134:137], v[198:201], v[84:87]
	v_mfma_f32_16x16x32_bf16 v[80:83], v[142:145], v[198:201], v[80:83]
	v_mfma_f32_16x16x32_bf16 v[76:79], v[134:137], v[206:209], v[76:79]
	v_mfma_f32_16x16x32_bf16 v[72:75], v[142:145], v[206:209], v[72:75]
	v_mfma_f32_16x16x32_bf16 v[68:71], v[134:137], v[214:217], v[68:71]
	v_mfma_f32_16x16x32_bf16 v[64:67], v[142:145], v[214:217], v[64:67]
	v_mfma_f32_16x16x32_bf16 v[28:31], v[146:149], v[186:189], 0
	v_mfma_f32_16x16x32_bf16 v[24:27], v[154:157], v[186:189], 0
	v_mfma_f32_16x16x32_bf16 v[20:23], v[146:149], v[194:197], 0
	v_mfma_f32_16x16x32_bf16 v[16:19], v[154:157], v[194:197], 0
	v_mfma_f32_16x16x32_bf16 v[12:15], v[146:149], v[202:205], 0
	v_mfma_f32_16x16x32_bf16 v[8:11], v[154:157], v[202:205], 0
	v_mfma_f32_16x16x32_bf16 v[4:7], v[146:149], v[210:213], 0
	v_mfma_f32_16x16x32_bf16 v[0:3], v[154:157], v[210:213], 0
	v_mfma_f32_16x16x32_bf16 v[28:31], v[150:153], v[190:193], v[28:31]
	v_mfma_f32_16x16x32_bf16 v[24:27], v[158:161], v[190:193], v[24:27]
	v_mfma_f32_16x16x32_bf16 v[20:23], v[150:153], v[198:201], v[20:23]
	v_mfma_f32_16x16x32_bf16 v[16:19], v[158:161], v[198:201], v[16:19]
	v_mfma_f32_16x16x32_bf16 v[12:15], v[150:153], v[206:209], v[12:15]
	v_mfma_f32_16x16x32_bf16 v[8:11], v[158:161], v[206:209], v[8:11]
	v_mfma_f32_16x16x32_bf16 v[4:7], v[150:153], v[214:217], v[4:7]
	v_mfma_f32_16x16x32_bf16 v[0:3], v[158:161], v[214:217], v[0:3]
	s_barrier
; #define PG8_STAGE(bufoff, gbase, voff) do { _Pragma("unroll") for (int _i = 0; _i < 2; ++_i) \
;         __builtin_amdgcn_global_load_lds((const unsigned*)((const char*)(gbase) + (voff)[_i]), (PG8_LAS unsigned*)(lds + (bufoff) + ldsw + _i * 8192), 16, 0, 0); } while (0)
; #define PG8_LDA(dst, b, h) do { _Pragma("unroll") for (int m = 0; m < 4; ++m) _Pragma("unroll") for (int k = 0; k < 2; ++k) dst[m][k] = *(const PG8_LAS bf16x8*)(lds + PG8_SA(b, h) + aoff + m * 2048 + k * 1024); } while (0)
; #define PG8_LDB(dst, b, h) do { _Pragma("unroll") for (int n = 0; n < 2; ++n) _Pragma("unroll") for (int k = 0; k < 2; ++k) dst[n][k] = *(const PG8_LAS bf16x8*)(lds + PG8_SB(b, h) + boff + n * 2048 + k * 1024); } while (0)
; #define PG8_MMA(ai, bj, At, Bt) do { __builtin_amdgcn_s_setprio(1); _Pragma("unroll") for (int m = 0; m < 4; ++m) _Pragma("unroll") for (int n = 0; n < 2; ++n) _Pragma("unroll") for (int k = 0; k < 2; ++k) \
;         acc[ai][bj][m][n] = mma16<F16>(Bt[n][k], At[m][k], acc[ai][bj][m][n]); __builtin_amdgcn_s_setprio(0); } while (0)
; #define PG8_WAIT_V(n) asm volatile("s_waitcnt vmcnt(" #n ")" ::: "memory")
; template <class Epi, class Sched, bool ALIGN_EPI = false, bool SP2 = false, bool F16 = false>
; __device__ __forceinline__ void gemm_phase(PG8_LAS unsigned char* lds, const Gemm g, const Sched& S, const Epi& E) {
;     ...
;             PG8_LDB(B0, 0, 0); PG8_LDB(B1, 0, 1); PG8_SCHED; PG8_LDA(At, 0, 0); PG8_STAGE(PG8_SA(1, 1), a1 + hstep, voffA);
;             PG8_WAIT_V(8); PG8_WAIT_L(0); PG8_BAR; PG8_MMA(0, 0, At, B0); PG8_MMA(0, 1, At, B1); PG8_BAR; PG8_SCHED;
;             PG8_LDA(At, 0, 1); PG8_STAGE(PG8_SB(0, 0), b2, voffB); PG8_STAGE(PG8_SB(0, 1), b2 + hstep, voffB); PG8_STAGE(PG8_SA(0, 0), a2, voffA);
;             PG8_WAIT_V(8); PG8_WAIT_L(0); PG8_BAR; PG8_MMA(1, 0, At, B0); PG8_MMA(1, 1, At, B1); PG8_BAR; PG8_SCHED;
;             PG8_LDB(B0, 1, 0); PG8_LDB(B1, 1, 1); PG8_SCHED; PG8_LDA(At, 1, 0); PG8_STAGE(PG8_SA(0, 1), a2 + hstep, voffA);
;             PG8_WAIT_V(8); PG8_WAIT_L(0); PG8_BAR; PG8_MMA(0, 0, At, B0); PG8_MMA(0, 1, At, B1); PG8_BAR; PG8_SCHED;
;             PG8_LDA(At, 1, 1); PG8_STAGE(PG8_SB(1, 0), b3, voffB); PG8_STAGE(PG8_SB(1, 1), b3 + hstep, voffB); PG8_STAGE(PG8_SA(1, 0), a3, voffA);
;             PG8_WAIT_V(8); PG8_WAIT_L(0); PG8_BAR; PG8_MMA(1, 0, At, B0); PG8_MMA(1, 1, At, B1); PG8_BAR; PG8_SCHED;
	s_add_i32 s59, 0, 0x18000
	s_add_i32 s60, 0, 0x1c000
	ds_read_b128 v[130:133], v172 offset:32768
	ds_read_b128 v[134:137], v172 offset:33792
	ds_read_b128 v[138:141], v172 offset:34816
	ds_read_b128 v[142:145], v172 offset:35840
	ds_read_b128 v[146:149], v172 offset:49152
	ds_read_b128 v[150:153], v172 offset:50176
	ds_read_b128 v[154:157], v172 offset:51200
	ds_read_b128 v[158:161], v172 offset:52224
	s_add_u32 s48, s54, 0xb0000
	s_addc_u32 s49, s55, 0
	s_mov_b32 m0, s11
	ds_read_b128 v[186:189], v225 offset:32768
	ds_read_b128 v[190:193], v225 offset:33792
	ds_read_b128 v[194:197], v225 offset:34816
	ds_read_b128 v[198:201], v225 offset:35840
	ds_read_b128 v[202:205], v225 offset:36864
	ds_read_b128 v[206:209], v225 offset:37888
	ds_read_b128 v[210:213], v225 offset:38912
	ds_read_b128 v[214:217], v225 offset:39936
	global_load_lds_dwordx4 v166, s[48:49]
	s_mov_b32 m0, s14
	s_nop 0
	global_load_lds_dwordx4 v164, s[48:49]
	s_waitcnt vmcnt(8)
	s_waitcnt lgkmcnt(0)
	s_barrier
	s_waitcnt lgkmcnt(0)
	v_mfma_f32_16x16x32_bf16 v[124:127], v[130:133], v[186:189], v[124:127]
	v_mfma_f32_16x16x32_bf16 v[120:123], v[138:141], v[186:189], v[120:123]
	v_mfma_f32_16x16x32_bf16 v[116:119], v[130:133], v[194:197], v[116:119]
	v_mfma_f32_16x16x32_bf16 v[112:115], v[138:141], v[194:197], v[112:115]
	v_mfma_f32_16x16x32_bf16 v[108:111], v[130:133], v[202:205], v[108:111]
	v_mfma_f32_16x16x32_bf16 v[104:107], v[138:141], v[202:205], v[104:107]
	v_mfma_f32_16x16x32_bf16 v[100:103], v[130:133], v[210:213], v[100:103]
	v_mfma_f32_16x16x32_bf16 v[96:99], v[138:141], v[210:213], v[96:99]
	v_mfma_f32_16x16x32_bf16 v[124:127], v[134:137], v[190:193], v[124:127]
	v_mfma_f32_16x16x32_bf16 v[120:123], v[142:145], v[190:193], v[120:123]
	v_mfma_f32_16x16x32_bf16 v[116:119], v[134:137], v[198:201], v[116:119]
	v_mfma_f32_16x16x32_bf16 v[112:115], v[142:145], v[198:201], v[112:115]
	v_mfma_f32_16x16x32_bf16 v[108:111], v[134:137], v[206:209], v[108:111]
	v_mfma_f32_16x16x32_bf16 v[104:107], v[142:145], v[206:209], v[104:107]
	v_mfma_f32_16x16x32_bf16 v[100:103], v[134:137], v[214:217], v[100:103]
	v_mfma_f32_16x16x32_bf16 v[96:99], v[142:145], v[214:217], v[96:99]
	v_mfma_f32_16x16x32_bf16 v[60:63], v[146:149], v[186:189], v[60:63]
	v_mfma_f32_16x16x32_bf16 v[56:59], v[154:157], v[186:189], v[56:59]
	v_mfma_f32_16x16x32_bf16 v[52:55], v[146:149], v[194:197], v[52:55]
	v_mfma_f32_16x16x32_bf16 v[48:51], v[154:157], v[194:197], v[48:51]
	v_mfma_f32_16x16x32_bf16 v[44:47], v[146:149], v[202:205], v[44:47]
	v_mfma_f32_16x16x32_bf16 v[40:43], v[154:157], v[202:205], v[40:43]
	v_mfma_f32_16x16x32_bf16 v[36:39], v[146:149], v[210:213], v[36:39]
	v_mfma_f32_16x16x32_bf16 v[32:35], v[154:157], v[210:213], v[32:35]
	v_mfma_f32_16x16x32_bf16 v[60:63], v[150:153], v[190:193], v[60:63]
	v_mfma_f32_16x16x32_bf16 v[56:59], v[158:161], v[190:193], v[56:59]
	v_mfma_f32_16x16x32_bf16 v[52:55], v[150:153], v[198:201], v[52:55]
	v_mfma_f32_16x16x32_bf16 v[48:51], v[158:161], v[198:201], v[48:51]
	v_mfma_f32_16x16x32_bf16 v[44:47], v[150:153], v[206:209], v[44:47]
	v_mfma_f32_16x16x32_bf16 v[40:43], v[158:161], v[206:209], v[40:43]
	v_mfma_f32_16x16x32_bf16 v[36:39], v[150:153], v[214:217], v[36:39]
	v_mfma_f32_16x16x32_bf16 v[32:35], v[158:161], v[214:217], v[32:35]
	s_barrier
	s_add_i32 s48, s59, s8
	s_mov_b32 m0, s48
	ds_read_b128 v[186:189], v225 offset:49152
	ds_read_b128 v[190:193], v225 offset:50176
	ds_read_b128 v[194:197], v225 offset:51200
	ds_read_b128 v[198:201], v225 offset:52224
	ds_read_b128 v[202:205], v225 offset:53248
	ds_read_b128 v[206:209], v225 offset:54272
	ds_read_b128 v[210:213], v225 offset:55296
	ds_read_b128 v[214:217], v225 offset:56320
	global_load_lds_dwordx4 v128, s[98:99]
	s_add_i32 m0, s48, 0x2000
	s_add_u32 s48, s52, 0xb0080
	s_addc_u32 s49, s53, 0
	s_add_i32 s52, s60, s8
	global_load_lds_dwordx4 v162, s[98:99]
	s_mov_b32 m0, s52
	s_nop 0
	global_load_lds_dwordx4 v128, s[48:49]
	s_add_i32 m0, s52, 0x2000
	s_nop 0
	global_load_lds_dwordx4 v162, s[48:49]
	s_mov_b32 m0, s29
	s_nop 0
	global_load_lds_dwordx4 v166, s[100:101]
	s_mov_b32 m0, s30
	s_nop 0
	global_load_lds_dwordx4 v164, s[100:101]
	s_waitcnt vmcnt(8)
	s_waitcnt lgkmcnt(0)
	s_barrier
	s_waitcnt lgkmcnt(0)
	v_mfma_f32_16x16x32_bf16 v[92:95], v[130:133], v[186:189], v[92:95]
	v_mfma_f32_16x16x32_bf16 v[88:91], v[138:141], v[186:189], v[88:91]
	v_mfma_f32_16x16x32_bf16 v[84:87], v[130:133], v[194:197], v[84:87]
	v_mfma_f32_16x16x32_bf16 v[80:83], v[138:141], v[194:197], v[80:83]
	v_mfma_f32_16x16x32_bf16 v[76:79], v[130:133], v[202:205], v[76:79]
	v_mfma_f32_16x16x32_bf16 v[72:75], v[138:141], v[202:205], v[72:75]
	v_mfma_f32_16x16x32_bf16 v[68:71], v[130:133], v[210:213], v[68:71]
	v_mfma_f32_16x16x32_bf16 v[64:67], v[138:141], v[210:213], v[64:67]
	v_mfma_f32_16x16x32_bf16 v[92:95], v[134:137], v[190:193], v[92:95]
	v_mfma_f32_16x16x32_bf16 v[88:91], v[142:145], v[190:193], v[88:91]
	v_mfma_f32_16x16x32_bf16 v[84:87], v[134:137], v[198:201], v[84:87]
	v_mfma_f32_16x16x32_bf16 v[80:83], v[142:145], v[198:201], v[80:83]
	v_mfma_f32_16x16x32_bf16 v[76:79], v[134:137], v[206:209], v[76:79]
	v_mfma_f32_16x16x32_bf16 v[72:75], v[142:145], v[206:209], v[72:75]
	v_mfma_f32_16x16x32_bf16 v[68:71], v[134:137], v[214:217], v[68:71]
	v_mfma_f32_16x16x32_bf16 v[64:67], v[142:145], v[214:217], v[64:67]
	v_mfma_f32_16x16x32_bf16 v[28:31], v[146:149], v[186:189], v[28:31]
	v_mfma_f32_16x16x32_bf16 v[24:27], v[154:157], v[186:189], v[24:27]
	v_mfma_f32_16x16x32_bf16 v[20:23], v[146:149], v[194:197], v[20:23]
	v_mfma_f32_16x16x32_bf16 v[16:19], v[154:157], v[194:197], v[16:19]
	v_mfma_f32_16x16x32_bf16 v[12:15], v[146:149], v[202:205], v[12:15]
	v_mfma_f32_16x16x32_bf16 v[8:11], v[154:157], v[202:205], v[8:11]
	v_mfma_f32_16x16x32_bf16 v[4:7], v[146:149], v[210:213], v[4:7]
	v_mfma_f32_16x16x32_bf16 v[0:3], v[154:157], v[210:213], v[0:3]
	v_mfma_f32_16x16x32_bf16 v[28:31], v[150:153], v[190:193], v[28:31]
	v_mfma_f32_16x16x32_bf16 v[24:27], v[158:161], v[190:193], v[24:27]
	v_mfma_f32_16x16x32_bf16 v[20:23], v[150:153], v[198:201], v[20:23]
	v_mfma_f32_16x16x32_bf16 v[16:19], v[158:161], v[198:201], v[16:19]
	v_mfma_f32_16x16x32_bf16 v[12:15], v[150:153], v[206:209], v[12:15]
	v_mfma_f32_16x16x32_bf16 v[8:11], v[158:161], v[206:209], v[8:11]
	v_mfma_f32_16x16x32_bf16 v[4:7], v[150:153], v[214:217], v[4:7]
	v_mfma_f32_16x16x32_bf16 v[0:3], v[158:161], v[214:217], v[0:3]
	s_barrier
	s_add_i32 s58, s58, 2
	s_add_u32 s4, s4, 0x100
	s_addc_u32 s5, s5, 0
	s_cmp_gt_u32 s58, 41
	s_mov_b64 s[48:49], s[50:51]
; #define PG8_STAGE(bufoff, gbase, voff) do { _Pragma("unroll") for (int _i = 0; _i < 2; ++_i) \
;         __builtin_amdgcn_global_load_lds((const unsigned*)((const char*)(gbase) + (voff)[_i]), (PG8_LAS unsigned*)(lds + (bufoff) + ldsw + _i * 8192), 16, 0, 0); } while (0)
; #define PG8_LDA(dst, b, h) do { _Pragma("unroll") for (int m = 0; m < 4; ++m) _Pragma("unroll") for (int k = 0; k < 2; ++k) dst[m][k] = *(const PG8_LAS bf16x8*)(lds + PG8_SA(b, h) + aoff + m * 2048 + k * 1024); } while (0)
; #define PG8_LDB(dst, b, h) do { _Pragma("unroll") for (int n = 0; n < 2; ++n) _Pragma("unroll") for (int k = 0; k < 2; ++k) dst[n][k] = *(const PG8_LAS bf16x8*)(lds + PG8_SB(b, h) + boff + n * 2048 + k * 1024); } while (0)
; #define PG8_MMA(ai, bj, At, Bt) do { __builtin_amdgcn_s_setprio(1); _Pragma("unroll") for (int m = 0; m < 4; ++m) _Pragma("unroll") for (int n = 0; n < 2; ++n) _Pragma("unroll") for (int k = 0; k < 2; ++k) \
;         acc[ai][bj][m][n] = mma16<F16>(Bt[n][k], At[m][k], acc[ai][bj][m][n]); __builtin_amdgcn_s_setprio(0); } while (0)
; #define PG8_WAIT_V(n) asm volatile("s_waitcnt vmcnt(" #n ")" ::: "memory")
; template <class Epi, class Sched, bool ALIGN_EPI = false, bool SP2 = false, bool F16 = false>
; __device__ __forceinline__ void gemm_phase(PG8_LAS unsigned char* lds, const Gemm g, const Sched& S, const Epi& E) {
;     ...
;             PG8_LDB(B0, 0, 0); PG8_LDB(B1, 0, 1); PG8_SCHED; PG8_LDA(At, 0, 0); PG8_STAGE(PG8_SA(1, 1), a1 + hstep, voffA);
;             PG8_WAIT_V(8); PG8_WAIT_L(0); PG8_BAR; PG8_MMA(0, 0, At, B0); PG8_MMA(0, 1, At, B1); PG8_BAR; PG8_SCHED;
;             PG8_LDA(At, 0, 1); PG8_STAGE(PG8_SB(0, 0), b2, voffB); PG8_STAGE(PG8_SB(0, 1), b2 + hstep, voffB); PG8_STAGE(PG8_SA(0, 0), a2, voffA);
;             PG8_WAIT_V(8); PG8_WAIT_L(0); PG8_BAR; PG8_MMA(1, 0, At, B0); PG8_MMA(1, 1, At, B1); PG8_BAR; PG8_SCHED;
;             PG8_LDB(B0, 1, 0); PG8_LDB(B1, 1, 1); PG8_SCHED; PG8_LDA(At, 1, 0); PG8_STAGE(PG8_SA(0, 1), a2 + hstep, voffA);
;             PG8_WAIT_V(8); PG8_WAIT_L(0); PG8_BAR; PG8_MMA(0, 0, At, B0); PG8_MMA(0, 1, At, B1); PG8_BAR; PG8_SCHED;
;             PG8_LDA(At, 1, 1); PG8_STAGE(PG8_SB(1, 0), b3, voffB); PG8_STAGE(PG8_SB(1, 1), b3 + hstep, voffB); PG8_STAGE(PG8_SA(1, 0), a3, voffA);
;             PG8_WAIT_V(8); PG8_WAIT_L(0); PG8_BAR; PG8_MMA(1, 0, At, B0); PG8_MMA(1, 1, At, B1); PG8_BAR; PG8_SCHED;
.LBB0_997:
	s_add_u32 s50, s48, 0x100
	s_addc_u32 s51, s49, 0
	s_add_i32 s59, 0, 0x10000
	s_cmp_eq_u32 s58, 40
	s_cselect_b32 s55, s43, s51
	s_cselect_b32 s54, s42, s50
	s_cselect_b32 s53, s47, s5
	s_cselect_b32 s52, s46, s4
	s_add_i32 s60, 0, 0x14000
	ds_read_b128 v[130:133], v172
	ds_read_b128 v[134:137], v172 offset:1024
	ds_read_b128 v[138:141], v172 offset:2048
	ds_read_b128 v[142:145], v172 offset:3072
	ds_read_b128 v[146:149], v172 offset:16384
	ds_read_b128 v[150:153], v172 offset:17408
	ds_read_b128 v[154:157], v172 offset:18432
	ds_read_b128 v[158:161], v172 offset:19456
	s_add_i32 m0, s9, 0xc000
	ds_read_b128 v[186:189], v225
	ds_read_b128 v[190:193], v225 offset:1024
	ds_read_b128 v[194:197], v225 offset:2048
	ds_read_b128 v[198:201], v225 offset:3072
	ds_read_b128 v[202:205], v225 offset:4096
	ds_read_b128 v[206:209], v225 offset:5120
	ds_read_b128 v[210:213], v225 offset:6144
	ds_read_b128 v[214:217], v225 offset:7168
	global_load_lds_dwordx4 v168, s[48:49]
	s_add_i32 m0, s9, 0xe000
	s_nop 0
	global_load_lds_dwordx4 v170, s[48:49]
	s_waitcnt vmcnt(8)
	s_waitcnt lgkmcnt(0)
	s_barrier
	s_waitcnt lgkmcnt(0)
	v_mfma_f32_16x16x32_bf16 v[124:127], v[130:133], v[186:189], v[124:127]
	v_mfma_f32_16x16x32_bf16 v[120:123], v[138:141], v[186:189], v[120:123]
	v_mfma_f32_16x16x32_bf16 v[116:119], v[130:133], v[194:197], v[116:119]
	v_mfma_f32_16x16x32_bf16 v[112:115], v[138:141], v[194:197], v[112:115]
	v_mfma_f32_16x16x32_bf16 v[108:111], v[130:133], v[202:205], v[108:111]
	v_mfma_f32_16x16x32_bf16 v[104:107], v[138:141], v[202:205], v[104:107]
	v_mfma_f32_16x16x32_bf16 v[100:103], v[130:133], v[210:213], v[100:103]
	v_mfma_f32_16x16x32_bf16 v[96:99], v[138:141], v[210:213], v[96:99]
	v_mfma_f32_16x16x32_bf16 v[124:127], v[134:137], v[190:193], v[124:127]
	v_mfma_f32_16x16x32_bf16 v[120:123], v[142:145], v[190:193], v[120:123]
	v_mfma_f32_16x16x32_bf16 v[116:119], v[134:137], v[198:201], v[116:119]
	v_mfma_f32_16x16x32_bf16 v[112:115], v[142:145], v[198:201], v[112:115]
	v_mfma_f32_16x16x32_bf16 v[108:111], v[134:137], v[206:209], v[108:111]
	v_mfma_f32_16x16x32_bf16 v[104:107], v[142:145], v[206:209], v[104:107]
	v_mfma_f32_16x16x32_bf16 v[100:103], v[134:137], v[214:217], v[100:103]
	v_mfma_f32_16x16x32_bf16 v[96:99], v[142:145], v[214:217], v[96:99]
	v_mfma_f32_16x16x32_bf16 v[60:63], v[146:149], v[186:189], v[60:63]
	v_mfma_f32_16x16x32_bf16 v[56:59], v[154:157], v[186:189], v[56:59]
	v_mfma_f32_16x16x32_bf16 v[52:55], v[146:149], v[194:197], v[52:55]
	v_mfma_f32_16x16x32_bf16 v[48:51], v[154:157], v[194:197], v[48:51]
	v_mfma_f32_16x16x32_bf16 v[44:47], v[146:149], v[202:205], v[44:47]
	v_mfma_f32_16x16x32_bf16 v[40:43], v[154:157], v[202:205], v[40:43]
	v_mfma_f32_16x16x32_bf16 v[36:39], v[146:149], v[210:213], v[36:39]
	v_mfma_f32_16x16x32_bf16 v[32:35], v[154:157], v[210:213], v[32:35]
	v_mfma_f32_16x16x32_bf16 v[60:63], v[150:153], v[190:193], v[60:63]
	v_mfma_f32_16x16x32_bf16 v[56:59], v[158:161], v[190:193], v[56:59]
	v_mfma_f32_16x16x32_bf16 v[52:55], v[150:153], v[198:201], v[52:55]
	v_mfma_f32_16x16x32_bf16 v[48:51], v[158:161], v[198:201], v[48:51]
	v_mfma_f32_16x16x32_bf16 v[44:47], v[150:153], v[206:209], v[44:47]
	v_mfma_f32_16x16x32_bf16 v[40:43], v[158:161], v[206:209], v[40:43]
	v_mfma_f32_16x16x32_bf16 v[36:39], v[150:153], v[214:217], v[36:39]
	v_mfma_f32_16x16x32_bf16 v[32:35], v[158:161], v[214:217], v[32:35]
	s_barrier
	s_add_u32 s98, s52, s16
	s_addc_u32 s99, s53, s17
	s_add_u32 s100, s54, s16
	s_addc_u32 s101, s55, s17
	s_add_i32 s48, s59, s8
	s_mov_b32 m0, s48
	ds_read_b128 v[186:189], v225 offset:16384
	ds_read_b128 v[190:193], v225 offset:17408
	ds_read_b128 v[194:197], v225 offset:18432
	ds_read_b128 v[198:201], v225 offset:19456
	ds_read_b128 v[202:205], v225 offset:20480
	ds_read_b128 v[206:209], v225 offset:21504
	ds_read_b128 v[210:213], v225 offset:22528
	ds_read_b128 v[214:217], v225 offset:23552
	global_load_lds_dwordx4 v128, s[52:53]
	s_add_i32 m0, s48, 0x2000
	s_add_u32 s48, s52, 0xb0000
	s_addc_u32 s49, s53, 0
	s_add_i32 s59, s60, s8
	global_load_lds_dwordx4 v162, s[52:53]
	s_mov_b32 m0, s59
	s_nop 0
	global_load_lds_dwordx4 v128, s[48:49]
	s_add_i32 m0, s59, 0x2000
	s_nop 0
	global_load_lds_dwordx4 v162, s[48:49]
	s_mov_b32 m0, s9
	s_nop 0
	global_load_lds_dwordx4 v166, s[54:55]
	s_mov_b32 m0, s10
	s_nop 0
	global_load_lds_dwordx4 v164, s[54:55]
	s_waitcnt vmcnt(8)
	s_waitcnt lgkmcnt(0)
	s_barrier
	s_waitcnt lgkmcnt(0)
	v_mfma_f32_16x16x32_bf16 v[92:95], v[130:133], v[186:189], v[92:95]
	v_mfma_f32_16x16x32_bf16 v[88:91], v[138:141], v[186:189], v[88:91]
	v_mfma_f32_16x16x32_bf16 v[84:87], v[130:133], v[194:197], v[84:87]
	v_mfma_f32_16x16x32_bf16 v[80:83], v[138:141], v[194:197], v[80:83]
	v_mfma_f32_16x16x32_bf16 v[76:79], v[130:133], v[202:205], v[76:79]
	v_mfma_f32_16x16x32_bf16 v[72:75], v[138:141], v[202:205], v[72:75]
	v_mfma_f32_16x16x32_bf16 v[68:71], v[130:133], v[210:213], v[68:71]
	v_mfma_f32_16x16x32_bf16 v[64:67], v[138:141], v[210:213], v[64:67]
	v_mfma_f32_16x16x32_bf16 v[92:95], v[134:137], v[190:193], v[92:95]
	v_mfma_f32_16x16x32_bf16 v[88:91], v[142:145], v[190:193], v[88:91]
	v_mfma_f32_16x16x32_bf16 v[84:87], v[134:137], v[198:201], v[84:87]
	v_mfma_f32_16x16x32_bf16 v[80:83], v[142:145], v[198:201], v[80:83]
	v_mfma_f32_16x16x32_bf16 v[76:79], v[134:137], v[206:209], v[76:79]
	v_mfma_f32_16x16x32_bf16 v[72:75], v[142:145], v[206:209], v[72:75]
	v_mfma_f32_16x16x32_bf16 v[68:71], v[134:137], v[214:217], v[68:71]
	v_mfma_f32_16x16x32_bf16 v[64:67], v[142:145], v[214:217], v[64:67]
	v_mfma_f32_16x16x32_bf16 v[28:31], v[146:149], v[186:189], v[28:31]
	v_mfma_f32_16x16x32_bf16 v[24:27], v[154:157], v[186:189], v[24:27]
	v_mfma_f32_16x16x32_bf16 v[20:23], v[146:149], v[194:197], v[20:23]
	v_mfma_f32_16x16x32_bf16 v[16:19], v[154:157], v[194:197], v[16:19]
	v_mfma_f32_16x16x32_bf16 v[12:15], v[146:149], v[202:205], v[12:15]
	v_mfma_f32_16x16x32_bf16 v[8:11], v[154:157], v[202:205], v[8:11]
	v_mfma_f32_16x16x32_bf16 v[4:7], v[146:149], v[210:213], v[4:7]
	v_mfma_f32_16x16x32_bf16 v[0:3], v[154:157], v[210:213], v[0:3]
	v_mfma_f32_16x16x32_bf16 v[28:31], v[150:153], v[190:193], v[28:31]
	v_mfma_f32_16x16x32_bf16 v[24:27], v[158:161], v[190:193], v[24:27]
	v_mfma_f32_16x16x32_bf16 v[20:23], v[150:153], v[198:201], v[20:23]
	v_mfma_f32_16x16x32_bf16 v[16:19], v[158:161], v[198:201], v[16:19]
	v_mfma_f32_16x16x32_bf16 v[12:15], v[150:153], v[206:209], v[12:15]
	v_mfma_f32_16x16x32_bf16 v[8:11], v[158:161], v[206:209], v[8:11]
	v_mfma_f32_16x16x32_bf16 v[4:7], v[150:153], v[214:217], v[4:7]
	v_mfma_f32_16x16x32_bf16 v[0:3], v[158:161], v[214:217], v[0:3]
	s_barrier
; #define PG8_STAGE(bufoff, gbase, voff) do { _Pragma("unroll") for (int _i = 0; _i < 2; ++_i) \
;         __builtin_amdgcn_global_load_lds((const unsigned*)((const char*)(gbase) + (voff)[_i]), (PG8_LAS unsigned*)(lds + (bufoff) + ldsw + _i * 8192), 16, 0, 0); } while (0)
; #define PG8_LDA(dst, b, h) do { _Pragma("unroll") for (int m = 0; m < 4; ++m) _Pragma("unroll") for (int k = 0; k < 2; ++k) dst[m][k] = *(const PG8_LAS bf16x8*)(lds + PG8_SA(b, h) + aoff + m * 2048 + k * 1024); } while (0)
; #define PG8_LDB(dst, b, h) do { _Pragma("unroll") for (int n = 0; n < 2; ++n) _Pragma("unroll") for (int k = 0; k < 2; ++k) dst[n][k] = *(const PG8_LAS bf16x8*)(lds + PG8_SB(b, h) + boff + n * 2048 + k * 1024); } while (0)
; #define PG8_MMA(ai, bj, At, Bt) do { __builtin_amdgcn_s_setprio(1); _Pragma("unroll") for (int m = 0; m < 4; ++m) _Pragma("unroll") for (int n = 0; n < 2; ++n) _Pragma("unroll") for (int k = 0; k < 2; ++k) \
;         acc[ai][bj][m][n] = mma16<F16>(Bt[n][k], At[m][k], acc[ai][bj][m][n]); __builtin_amdgcn_s_setprio(0); } while (0)
; template <class Epi, class Sched, bool ALIGN_EPI = false, bool SP2 = false, bool F16 = false>
; __device__ __forceinline__ void gemm_phase(PG8_LAS unsigned char* lds, const Gemm g, const Sched& S, const Epi& E) {
;     ...
;             PG8_LDB(B0, 0, 0); PG8_LDB(B1, 0, 1); PG8_SCHED; PG8_LDA(At, 0, 0); PG8_STAGE(PG8_SA(1, 1), a1 + hstep, voffA);
;             PG8_WAIT_V(8); PG8_WAIT_L(0); PG8_BAR; PG8_MMA(0, 0, At, B0); PG8_MMA(0, 1, At, B1); PG8_BAR; PG8_SCHED;
;             PG8_LDA(At, 0, 1); PG8_STAGE(PG8_SB(0, 0), b2, voffB); PG8_STAGE(PG8_SB(0, 1), b2 + hstep, voffB); PG8_STAGE(PG8_SA(0, 0), a2, voffA);
;             PG8_WAIT_V(8); PG8_WAIT_L(0); PG8_BAR; PG8_MMA(1, 0, At, B0); PG8_MMA(1, 1, At, B1); PG8_BAR; PG8_SCHED;
;             PG8_LDB(B0, 1, 0); PG8_LDB(B1, 1, 1); PG8_SCHED; PG8_LDA(At, 1, 0); PG8_STAGE(PG8_SA(0, 1), a2 + hstep, voffA);
;             PG8_WAIT_V(8); PG8_WAIT_L(0); PG8_BAR; PG8_MMA(0, 0, At, B0); PG8_MMA(0, 1, At, B1); PG8_BAR; PG8_SCHED;
;             PG8_LDA(At, 1, 1); PG8_STAGE(PG8_SB(1, 0), b3, voffB); PG8_STAGE(PG8_SB(1, 1), b3 + hstep, voffB); PG8_STAGE(PG8_SA(1, 0), a3, voffA);
;             PG8_WAIT_V(8); PG8_WAIT_L(0); PG8_BAR; PG8_MMA(1, 0, At, B0); PG8_MMA(1, 1, At, B1); PG8_BAR; PG8_SCHED;
;     ...
;         if constexpr (ALIGN_EPI) { if (wr == 0) PG8_BAR; }
	s_add_i32 s59, 0, 0x18000
	s_add_i32 s60, 0, 0x1c000
	ds_read_b128 v[130:133], v172 offset:32768
	ds_read_b128 v[134:137], v172 offset:33792
	ds_read_b128 v[138:141], v172 offset:34816
	ds_read_b128 v[142:145], v172 offset:35840
	ds_read_b128 v[146:149], v172 offset:49152
	ds_read_b128 v[150:153], v172 offset:50176
	ds_read_b128 v[154:157], v172 offset:51200
	ds_read_b128 v[158:161], v172 offset:52224
	s_add_u32 s48, s54, 0xb0000
	s_addc_u32 s49, s55, 0
	s_mov_b32 m0, s11
	ds_read_b128 v[186:189], v225 offset:32768
	ds_read_b128 v[190:193], v225 offset:33792
	ds_read_b128 v[194:197], v225 offset:34816
	ds_read_b128 v[198:201], v225 offset:35840
	ds_read_b128 v[202:205], v225 offset:36864
	ds_read_b128 v[206:209], v225 offset:37888
	ds_read_b128 v[210:213], v225 offset:38912
	ds_read_b128 v[214:217], v225 offset:39936
	global_load_lds_dwordx4 v166, s[48:49]
	s_mov_b32 m0, s14
	s_nop 0
	global_load_lds_dwordx4 v164, s[48:49]
	s_waitcnt vmcnt(8)
	s_waitcnt lgkmcnt(0)
	s_barrier
	s_waitcnt lgkmcnt(0)
	v_mfma_f32_16x16x32_bf16 v[124:127], v[130:133], v[186:189], v[124:127]
	v_mfma_f32_16x16x32_bf16 v[120:123], v[138:141], v[186:189], v[120:123]
	v_mfma_f32_16x16x32_bf16 v[116:119], v[130:133], v[194:197], v[116:119]
	v_mfma_f32_16x16x32_bf16 v[112:115], v[138:141], v[194:197], v[112:115]
	v_mfma_f32_16x16x32_bf16 v[108:111], v[130:133], v[202:205], v[108:111]
	v_mfma_f32_16x16x32_bf16 v[104:107], v[138:141], v[202:205], v[104:107]
	v_mfma_f32_16x16x32_bf16 v[100:103], v[130:133], v[210:213], v[100:103]
	v_mfma_f32_16x16x32_bf16 v[96:99], v[138:141], v[210:213], v[96:99]
	v_mfma_f32_16x16x32_bf16 v[124:127], v[134:137], v[190:193], v[124:127]
	v_mfma_f32_16x16x32_bf16 v[120:123], v[142:145], v[190:193], v[120:123]
	v_mfma_f32_16x16x32_bf16 v[116:119], v[134:137], v[198:201], v[116:119]
	v_mfma_f32_16x16x32_bf16 v[112:115], v[142:145], v[198:201], v[112:115]
	v_mfma_f32_16x16x32_bf16 v[108:111], v[134:137], v[206:209], v[108:111]
	v_mfma_f32_16x16x32_bf16 v[104:107], v[142:145], v[206:209], v[104:107]
	v_mfma_f32_16x16x32_bf16 v[100:103], v[134:137], v[214:217], v[100:103]
	v_mfma_f32_16x16x32_bf16 v[96:99], v[142:145], v[214:217], v[96:99]
	v_mfma_f32_16x16x32_bf16 v[60:63], v[146:149], v[186:189], v[60:63]
	v_mfma_f32_16x16x32_bf16 v[56:59], v[154:157], v[186:189], v[56:59]
	v_mfma_f32_16x16x32_bf16 v[52:55], v[146:149], v[194:197], v[52:55]
	v_mfma_f32_16x16x32_bf16 v[48:51], v[154:157], v[194:197], v[48:51]
	v_mfma_f32_16x16x32_bf16 v[44:47], v[146:149], v[202:205], v[44:47]
	v_mfma_f32_16x16x32_bf16 v[40:43], v[154:157], v[202:205], v[40:43]
	v_mfma_f32_16x16x32_bf16 v[36:39], v[146:149], v[210:213], v[36:39]
	v_mfma_f32_16x16x32_bf16 v[32:35], v[154:157], v[210:213], v[32:35]
	v_mfma_f32_16x16x32_bf16 v[60:63], v[150:153], v[190:193], v[60:63]
	v_mfma_f32_16x16x32_bf16 v[56:59], v[158:161], v[190:193], v[56:59]
	v_mfma_f32_16x16x32_bf16 v[52:55], v[150:153], v[198:201], v[52:55]
	v_mfma_f32_16x16x32_bf16 v[48:51], v[158:161], v[198:201], v[48:51]
	v_mfma_f32_16x16x32_bf16 v[44:47], v[150:153], v[206:209], v[44:47]
	v_mfma_f32_16x16x32_bf16 v[40:43], v[158:161], v[206:209], v[40:43]
	v_mfma_f32_16x16x32_bf16 v[36:39], v[150:153], v[214:217], v[36:39]
	v_mfma_f32_16x16x32_bf16 v[32:35], v[158:161], v[214:217], v[32:35]
	s_barrier
	s_add_i32 s48, s59, s8
	s_mov_b32 m0, s48
	ds_read_b128 v[186:189], v225 offset:49152
	ds_read_b128 v[190:193], v225 offset:50176
	ds_read_b128 v[194:197], v225 offset:51200
	ds_read_b128 v[198:201], v225 offset:52224
	ds_read_b128 v[202:205], v225 offset:53248
	ds_read_b128 v[206:209], v225 offset:54272
	ds_read_b128 v[210:213], v225 offset:55296
	ds_read_b128 v[214:217], v225 offset:56320
	global_load_lds_dwordx4 v128, s[98:99]
	s_add_i32 m0, s48, 0x2000
	s_add_u32 s48, s52, 0xb0080
	s_addc_u32 s49, s53, 0
	s_add_i32 s52, s60, s8
	global_load_lds_dwordx4 v162, s[98:99]
	s_mov_b32 m0, s52
	s_nop 0
	global_load_lds_dwordx4 v128, s[48:49]
	s_add_i32 m0, s52, 0x2000
	s_nop 0
	global_load_lds_dwordx4 v162, s[48:49]
	s_mov_b32 m0, s29
	s_nop 0
	global_load_lds_dwordx4 v166, s[100:101]
	s_mov_b32 m0, s30
	s_nop 0
	global_load_lds_dwordx4 v164, s[100:101]
	s_waitcnt vmcnt(8)
	s_waitcnt lgkmcnt(0)
	s_barrier
	s_waitcnt lgkmcnt(0)
	v_mfma_f32_16x16x32_bf16 v[92:95], v[130:133], v[186:189], v[92:95]
	v_mfma_f32_16x16x32_bf16 v[88:91], v[138:141], v[186:189], v[88:91]
	v_mfma_f32_16x16x32_bf16 v[84:87], v[130:133], v[194:197], v[84:87]
	v_mfma_f32_16x16x32_bf16 v[80:83], v[138:141], v[194:197], v[80:83]
	v_mfma_f32_16x16x32_bf16 v[76:79], v[130:133], v[202:205], v[76:79]
	v_mfma_f32_16x16x32_bf16 v[72:75], v[138:141], v[202:205], v[72:75]
	v_mfma_f32_16x16x32_bf16 v[68:71], v[130:133], v[210:213], v[68:71]
	v_mfma_f32_16x16x32_bf16 v[64:67], v[138:141], v[210:213], v[64:67]
	v_mfma_f32_16x16x32_bf16 v[92:95], v[134:137], v[190:193], v[92:95]
	v_mfma_f32_16x16x32_bf16 v[88:91], v[142:145], v[190:193], v[88:91]
	v_mfma_f32_16x16x32_bf16 v[84:87], v[134:137], v[198:201], v[84:87]
	v_mfma_f32_16x16x32_bf16 v[80:83], v[142:145], v[198:201], v[80:83]
	v_mfma_f32_16x16x32_bf16 v[76:79], v[134:137], v[206:209], v[76:79]
	v_mfma_f32_16x16x32_bf16 v[72:75], v[142:145], v[206:209], v[72:75]
	v_mfma_f32_16x16x32_bf16 v[68:71], v[134:137], v[214:217], v[68:71]
	v_mfma_f32_16x16x32_bf16 v[64:67], v[142:145], v[214:217], v[64:67]
	v_mfma_f32_16x16x32_bf16 v[28:31], v[146:149], v[186:189], v[28:31]
	v_mfma_f32_16x16x32_bf16 v[24:27], v[154:157], v[186:189], v[24:27]
	v_mfma_f32_16x16x32_bf16 v[20:23], v[146:149], v[194:197], v[20:23]
	v_mfma_f32_16x16x32_bf16 v[16:19], v[154:157], v[194:197], v[16:19]
	v_mfma_f32_16x16x32_bf16 v[12:15], v[146:149], v[202:205], v[12:15]
	v_mfma_f32_16x16x32_bf16 v[8:11], v[154:157], v[202:205], v[8:11]
	v_mfma_f32_16x16x32_bf16 v[4:7], v[146:149], v[210:213], v[4:7]
	v_mfma_f32_16x16x32_bf16 v[0:3], v[154:157], v[210:213], v[0:3]
	v_mfma_f32_16x16x32_bf16 v[28:31], v[150:153], v[190:193], v[28:31]
	v_mfma_f32_16x16x32_bf16 v[24:27], v[158:161], v[190:193], v[24:27]
	v_mfma_f32_16x16x32_bf16 v[20:23], v[150:153], v[198:201], v[20:23]
	v_mfma_f32_16x16x32_bf16 v[16:19], v[158:161], v[198:201], v[16:19]
	v_mfma_f32_16x16x32_bf16 v[12:15], v[150:153], v[206:209], v[12:15]
	v_mfma_f32_16x16x32_bf16 v[8:11], v[158:161], v[206:209], v[8:11]
	v_mfma_f32_16x16x32_bf16 v[4:7], v[150:153], v[214:217], v[4:7]
	v_mfma_f32_16x16x32_bf16 v[0:3], v[158:161], v[214:217], v[0:3]
	s_barrier
	s_add_i32 s58, s58, 2
	s_add_u32 s4, s4, 0x100
	s_addc_u32 s5, s5, 0
	s_cmp_gt_u32 s58, 41
	s_mov_b64 s[48:49], s[50:51]
	s_cbranch_scc0 .LBB0_997
	s_and_b64 vcc, exec, s[44:45]
	s_cbranch_vccz .LBB0_1000
	s_barrier
